# LoRA/gate GEMM epilogues: adjacent 16-column groups paired with v_permlane16_swap, 16-byte stores (16 -> 8 per tile)
# speedup vs baseline: 1.0296x; 1.0019x over previous
;     ...
;     GLDS(ap, 0, 0, 0)
;     asm volatile("s_waitcnt vmcnt(0)" ::: "memory");
;     __syncthreads();
;     for (int kt = 0; kt < KT; kt++) {
;       const int cur = (kt & 1) * 16384;
;       if (kt + 1 < KT) {
;         const bf16_t* apx = ap;
;         int kc = (kt + 1) * 64;
;         if (SHIFT && kc >= 1024) { apx = ap - lda; kc -= 1024; }
;         const int nxt = ((kt + 1) & 1) * 16384;
;         GLDS(apx, kc, (kt + 1) * 64, nxt)
;       }
; #pragma unroll
;       for (int kk = 0; kk < 2; kk++) {
;         bf16x8 af[4], bfr[4];
;         const int csw = (((kk * 4 + fq) ^ fsw) << 3);
; #pragma unroll
;         for (int mi = 0; mi < 4; mi++) af[mi] = *(const bf16x8*)(smem + cur + (wm * 64 + mi * 16 + fr) * 64 + csw);
; #pragma unroll
;         for (int ni = 0; ni < 4; ni++) bfr[ni] = *(const bf16x8*)(smem + cur + 8192 + (wn * 64 + ni * 16 + fr) * 64 + csw);
; #pragma unroll
;         for (int mi = 0; mi < 4; mi++)
; #pragma unroll
;           for (int ni = 0; ni < 4; ni++)
;             acc[mi][ni] = TR ? __builtin_amdgcn_mfma_f32_16x16x32_bf16(bfr[ni], af[mi], acc[mi][ni], 0, 0, 0)
;                              : __builtin_amdgcn_mfma_f32_16x16x32_bf16(af[mi], bfr[ni], acc[mi][ni], 0, 0, 0);
;       }
.LBB0_445:
	v_bfe_u32 v204, v2, 4, 1
	v_mov_b32_e32 v205, 0
	v_mul_u32_u24_e32 v204, 24, v204
	s_lshl_b32 s0, s9, 7
	s_lshl_b32 s1, s8, 7
	v_add_u32_e32 v8, s0, v115
	v_mad_i64_i32 v[76:77], s[8:9], v8, s45, v[78:79]
	v_add_u32_e32 v8, s1, v115
	s_movk_i32 s5, 0x180
	v_mad_i64_i32 v[10:11], s[8:9], v8, s5, v[80:81]
	v_readfirstlane_b32 s5, v123
	s_mov_b64 s[8:9], 0x5000
	v_add_u32_e32 v8, 0x1000, v123
	s_mov_b32 m0, s5
	v_lshl_add_u64 v[12:13], v[76:77], 0, s[8:9]
	v_readfirstlane_b32 s8, v8
	v_add_u32_e32 v8, 0x2000, v123
	global_load_lds_dwordx4 v[76:77], off
	s_mov_b32 m0, s8
	s_mov_b64 s[10:11], 0xa000
	v_readfirstlane_b32 s9, v8
	global_load_lds_dwordx4 v[12:13], off
	v_lshl_add_u64 v[12:13], v[76:77], 0, s[10:11]
	s_mov_b32 m0, s9
	s_mov_b64 s[10:11], 0xf000
	v_add_u32_e32 v8, 0x3000, v123
	global_load_lds_dwordx4 v[12:13], off
	v_lshl_add_u64 v[12:13], v[76:77], 0, s[10:11]
	v_readfirstlane_b32 s10, v8
	v_add_u32_e32 v8, 0x4000, v123
	s_mov_b32 m0, s10
	v_readfirstlane_b32 s11, v8
	s_mov_b64 s[12:13], 0x3000
	v_add_u32_e32 v8, 0x5000, v123
	global_load_lds_dwordx4 v[12:13], off
	s_mov_b32 m0, s11
	v_lshl_add_u64 v[12:13], v[10:11], 0, s[12:13]
	v_readfirstlane_b32 s12, v8
	v_add_u32_e32 v8, 0x6000, v123
	global_load_lds_dwordx4 v[10:11], off
	s_mov_b32 m0, s12
	s_mov_b64 s[14:15], 0x6000
	v_readfirstlane_b32 s13, v8
	global_load_lds_dwordx4 v[12:13], off
	v_lshl_add_u64 v[12:13], v[10:11], 0, s[14:15]
	s_mov_b32 m0, s13
	s_mov_b64 s[14:15], 0x9000
	v_add_u32_e32 v8, 0x7000, v123
	global_load_lds_dwordx4 v[12:13], off
	v_lshl_add_u64 v[12:13], v[10:11], 0, s[14:15]
	v_readfirstlane_b32 s14, v8
	v_add_u32_e32 v8, 0x8000, v123
	s_mov_b32 m0, s14
	s_mov_b64 s[18:19], 0x80
	v_readfirstlane_b32 s15, v8
	v_add_u32_e32 v8, 0x9000, v123
	global_load_lds_dwordx4 v[12:13], off
	v_lshl_add_u64 v[12:13], v[76:77], 0, s[18:19]
	s_mov_b32 m0, s15
	s_mov_b64 s[16:17], 0x5080
	v_readfirstlane_b32 s15, v8
	v_add_u32_e32 v8, 0xa000, v123
	s_waitcnt vmcnt(0)
	s_waitcnt vmcnt(0) lgkmcnt(0)
	s_barrier
	global_load_lds_dwordx4 v[12:13], off
	v_lshl_add_u64 v[12:13], v[76:77], 0, s[16:17]
	s_mov_b32 m0, s15
	s_mov_b64 s[16:17], 0xa080
	v_readfirstlane_b32 s15, v8
	v_add_u32_e32 v8, 0xb000, v123
	global_load_lds_dwordx4 v[12:13], off
	v_lshl_add_u64 v[12:13], v[76:77], 0, s[16:17]
	s_mov_b32 m0, s15
	s_mov_b64 s[16:17], 0xf080
	v_readfirstlane_b32 s15, v8
	v_add_u32_e32 v8, 0xc000, v123
	global_load_lds_dwordx4 v[12:13], off
	v_lshl_add_u64 v[12:13], v[76:77], 0, s[16:17]
	s_mov_b32 m0, s15
	v_readfirstlane_b32 s15, v8
	v_add_u32_e32 v8, 0xd000, v123
	global_load_lds_dwordx4 v[12:13], off
	v_lshl_add_u64 v[12:13], v[10:11], 0, s[18:19]
	s_mov_b32 m0, s15
	s_mov_b64 s[16:17], 0x3080
	v_readfirstlane_b32 s15, v8
	v_add_u32_e32 v8, 0xe000, v123
	global_load_lds_dwordx4 v[12:13], off
	v_lshl_add_u64 v[12:13], v[10:11], 0, s[16:17]
	s_mov_b32 m0, s15
	s_mov_b64 s[16:17], 0x6080
	v_readfirstlane_b32 s15, v8
	v_add_u32_e32 v8, 0xf000, v123
	global_load_lds_dwordx4 v[12:13], off
	v_lshl_add_u64 v[12:13], v[10:11], 0, s[16:17]
	s_mov_b32 m0, s15
	s_mov_b64 s[16:17], 0x9080
	v_readfirstlane_b32 s15, v8
	global_load_lds_dwordx4 v[12:13], off
	v_lshl_add_u64 v[12:13], v[10:11], 0, s[16:17]
	s_mov_b32 m0, s15
	s_mov_b64 s[18:19], 0x100
	global_load_lds_dwordx4 v[12:13], off
	ds_read_b128 v[12:15], v127
	ds_read_b128 v[16:19], v127 offset:2048
	ds_read_b128 v[20:23], v127 offset:4096
	ds_read_b128 v[24:27], v127 offset:6144
	ds_read_b128 v[28:31], v128 offset:16384
	ds_read_b128 v[32:35], v128 offset:18432
	ds_read_b128 v[36:39], v128 offset:20480
	ds_read_b128 v[40:43], v128 offset:22528
	s_waitcnt lgkmcnt(0)
	v_mfma_f32_16x16x32_bf16 v[44:47], v[28:31], v[12:15], 0
	s_mov_b32 m0, s5
	s_mov_b64 s[16:17], 0x5100
	v_add_u32_e32 v8, s0, v124
	v_mfma_f32_16x16x32_bf16 v[48:51], v[32:35], v[12:15], 0
	s_mov_b32 s24, 0xfc0fc0fd
	s_movk_i32 s0, 0x4100
	v_cmp_gt_u32_e32 vcc, s0, v8
	v_mfma_f32_16x16x32_bf16 v[52:55], v[36:39], v[12:15], 0
	s_mov_b32 s5, 0x800000
	v_mfma_f32_16x16x32_bf16 v[12:15], v[40:43], v[12:15], 0
	v_mfma_f32_16x16x32_bf16 v[56:59], v[28:31], v[16:19], 0
	v_mfma_f32_16x16x32_bf16 v[60:63], v[32:35], v[16:19], 0
	v_mfma_f32_16x16x32_bf16 v[64:67], v[36:39], v[16:19], 0
	v_mfma_f32_16x16x32_bf16 v[16:19], v[40:43], v[16:19], 0
	v_mfma_f32_16x16x32_bf16 v[68:71], v[28:31], v[20:23], 0
	v_mfma_f32_16x16x32_bf16 v[72:75], v[32:35], v[20:23], 0
	v_mfma_f32_16x16x32_bf16 v[82:85], v[36:39], v[20:23], 0
	v_mfma_f32_16x16x32_bf16 v[20:23], v[40:43], v[20:23], 0
	v_mfma_f32_16x16x32_bf16 v[28:31], v[28:31], v[24:27], 0
	v_mfma_f32_16x16x32_bf16 v[32:35], v[32:35], v[24:27], 0
	v_mfma_f32_16x16x32_bf16 v[36:39], v[36:39], v[24:27], 0
	v_mfma_f32_16x16x32_bf16 v[24:27], v[40:43], v[24:27], 0
	ds_read_b128 v[40:43], v129
	ds_read_b128 v[86:89], v129 offset:2048
	ds_read_b128 v[90:93], v129 offset:4096
	ds_read_b128 v[94:97], v129 offset:6144
	ds_read_b128 v[98:101], v130 offset:16384
	ds_read_b128 v[102:105], v130 offset:18432
	ds_read_b128 v[106:109], v130 offset:20480
	ds_read_b128 v[110:113], v130 offset:22528
	s_waitcnt vmcnt(0)
	s_waitcnt vmcnt(0) lgkmcnt(0)
	v_mfma_f32_16x16x32_bf16 v[44:47], v[98:101], v[40:43], v[44:47]
	s_barrier
;     ...
;     for (int kt = 0; kt < KT; kt++) {
;       const int cur = (kt & 1) * 16384;
;       if (kt + 1 < KT) {
;         const bf16_t* apx = ap;
;         int kc = (kt + 1) * 64;
;         if (SHIFT && kc >= 1024) { apx = ap - lda; kc -= 1024; }
;         const int nxt = ((kt + 1) & 1) * 16384;
;         GLDS(apx, kc, (kt + 1) * 64, nxt)
;       }
; #pragma unroll
;       for (int kk = 0; kk < 2; kk++) {
;         bf16x8 af[4], bfr[4];
;         const int csw = (((kk * 4 + fq) ^ fsw) << 3);
; #pragma unroll
;         for (int mi = 0; mi < 4; mi++) af[mi] = *(const bf16x8*)(smem + cur + (wm * 64 + mi * 16 + fr) * 64 + csw);
; #pragma unroll
;         for (int ni = 0; ni < 4; ni++) bfr[ni] = *(const bf16x8*)(smem + cur + 8192 + (wn * 64 + ni * 16 + fr) * 64 + csw);
; #pragma unroll
;         for (int mi = 0; mi < 4; mi++)
; #pragma unroll
;           for (int ni = 0; ni < 4; ni++)
;             acc[mi][ni] = TR ? __builtin_amdgcn_mfma_f32_16x16x32_bf16(bfr[ni], af[mi], acc[mi][ni], 0, 0, 0)
;                              : __builtin_amdgcn_mfma_f32_16x16x32_bf16(af[mi], bfr[ni], acc[mi][ni], 0, 0, 0);
;       }
;       asm volatile("s_waitcnt vmcnt(0)" ::: "memory");
;       __syncthreads();
	v_mfma_f32_16x16x32_bf16 v[48:51], v[102:105], v[40:43], v[48:51]
	v_mfma_f32_16x16x32_bf16 v[52:55], v[106:109], v[40:43], v[52:55]
	v_mfma_f32_16x16x32_bf16 v[12:15], v[110:113], v[40:43], v[12:15]
	v_mfma_f32_16x16x32_bf16 v[40:43], v[98:101], v[86:89], v[56:59]
	v_mfma_f32_16x16x32_bf16 v[56:59], v[102:105], v[86:89], v[60:63]
	v_mfma_f32_16x16x32_bf16 v[60:63], v[106:109], v[86:89], v[64:67]
	v_mfma_f32_16x16x32_bf16 v[64:67], v[98:101], v[90:93], v[68:71]
	v_mfma_f32_16x16x32_bf16 v[68:71], v[102:105], v[90:93], v[72:75]
	v_mfma_f32_16x16x32_bf16 v[72:75], v[106:109], v[90:93], v[82:85]
	s_nop 2
	v_lshl_add_u64 v[82:83], v[76:77], 0, s[18:19]
	global_load_lds_dwordx4 v[82:83], off
	v_lshl_add_u64 v[82:83], v[76:77], 0, s[16:17]
	s_mov_b32 m0, s8
	s_mov_b64 s[16:17], 0xa100
	global_load_lds_dwordx4 v[82:83], off
	v_lshl_add_u64 v[82:83], v[76:77], 0, s[16:17]
	s_mov_b32 m0, s9
	s_mov_b64 s[8:9], 0xf100
	global_load_lds_dwordx4 v[82:83], off
	v_lshl_add_u64 v[76:77], v[76:77], 0, s[8:9]
	s_mov_b32 m0, s10
	s_mov_b64 s[8:9], 0x3100
	global_load_lds_dwordx4 v[76:77], off
	v_lshl_add_u64 v[76:77], v[10:11], 0, s[18:19]
	s_mov_b32 m0, s11
	v_mfma_f32_16x16x32_bf16 v[16:19], v[110:113], v[86:89], v[16:19]
	global_load_lds_dwordx4 v[76:77], off
	v_lshl_add_u64 v[76:77], v[10:11], 0, s[8:9]
	s_mov_b32 m0, s12
	s_mov_b64 s[8:9], 0x6100
	global_load_lds_dwordx4 v[76:77], off
	v_lshl_add_u64 v[76:77], v[10:11], 0, s[8:9]
	s_mov_b32 m0, s13
	s_mov_b64 s[8:9], 0x9100
	global_load_lds_dwordx4 v[76:77], off
	v_lshl_add_u64 v[10:11], v[10:11], 0, s[8:9]
	s_mov_b32 m0, s14
	v_mfma_f32_16x16x32_bf16 v[20:23], v[110:113], v[90:93], v[20:23]
	global_load_lds_dwordx4 v[10:11], off
	v_readlane_b32 s8, v247, 7
	v_mfma_f32_16x16x32_bf16 v[28:31], v[98:101], v[94:97], v[28:31]
	v_readlane_b32 s15, v247, 14
	s_movk_i32 s15, 0xc00
	v_readlane_b32 s10, v247, 9
	v_mfma_f32_16x16x32_bf16 v[32:35], v[102:105], v[94:97], v[32:35]
	v_readlane_b32 s11, v247, 10
	v_readlane_b32 s10, v246, 9
	v_readlane_b32 s11, v246, 10
	v_mfma_f32_16x16x32_bf16 v[36:39], v[106:109], v[94:97], v[36:39]
	v_readlane_b32 s12, v247, 11
	v_readlane_b32 s13, v247, 12
	v_readlane_b32 s12, v246, 11
	v_mfma_f32_16x16x32_bf16 v[24:27], v[110:113], v[94:97], v[24:27]
	ds_read_b128 v[82:85], v127 offset:32768
	ds_read_b128 v[86:89], v127 offset:34816
	ds_read_b128 v[90:93], v127 offset:36864
	ds_read_b128 v[94:97], v127 offset:38912
	ds_read_b128 v[98:101], v128 offset:49152
	ds_read_b128 v[102:105], v128 offset:51200
	ds_read_b128 v[106:109], v128 offset:53248
	ds_read_b128 v[110:113], v128 offset:55296
	v_readlane_b32 s14, v247, 13
	v_readlane_b32 s16, v247, 15
	s_waitcnt lgkmcnt(0)
	v_mfma_f32_16x16x32_bf16 v[44:47], v[98:101], v[82:85], v[44:47]
	v_readlane_b32 s17, v247, 16
	v_readlane_b32 s13, v246, 12
	v_readlane_b32 s18, v247, 17
	v_mfma_f32_16x16x32_bf16 v[48:51], v[102:105], v[82:85], v[48:51]
	v_readlane_b32 s19, v247, 18
	s_movk_i32 s14, 0x70
	v_readlane_b32 s9, v247, 8
	v_mfma_f32_16x16x32_bf16 v[52:55], v[106:109], v[82:85], v[52:55]
	v_readlane_b32 s8, v247, 25
	v_readlane_b32 s9, v247, 26
	v_readlane_b32 s20, v247, 19
	v_mfma_f32_16x16x32_bf16 v[10:13], v[110:113], v[82:85], v[12:15]
	v_readlane_b32 s21, v247, 20
	v_readlane_b32 s22, v247, 21
	v_readlane_b32 s23, v247, 22
	v_mfma_f32_16x16x32_bf16 v[40:43], v[98:101], v[86:89], v[40:43]
	v_mfma_f32_16x16x32_bf16 v[56:59], v[102:105], v[86:89], v[56:59]
	v_mfma_f32_16x16x32_bf16 v[60:63], v[106:109], v[86:89], v[60:63]
	v_mfma_f32_16x16x32_bf16 v[14:17], v[110:113], v[86:89], v[16:19]
	v_mfma_f32_16x16x32_bf16 v[64:67], v[98:101], v[90:93], v[64:67]
	v_mfma_f32_16x16x32_bf16 v[68:71], v[102:105], v[90:93], v[68:71]
	v_mfma_f32_16x16x32_bf16 v[72:75], v[106:109], v[90:93], v[72:75]
	v_mfma_f32_16x16x32_bf16 v[18:21], v[110:113], v[90:93], v[20:23]
	v_mfma_f32_16x16x32_bf16 v[28:31], v[98:101], v[94:97], v[28:31]
	v_mfma_f32_16x16x32_bf16 v[32:35], v[102:105], v[94:97], v[32:35]
	v_mfma_f32_16x16x32_bf16 v[36:39], v[106:109], v[94:97], v[36:39]
	v_mfma_f32_16x16x32_bf16 v[22:25], v[110:113], v[94:97], v[24:27]
	ds_read_b128 v[82:85], v129 offset:32768
	ds_read_b128 v[86:89], v129 offset:34816
	ds_read_b128 v[90:93], v129 offset:36864
	ds_read_b128 v[94:97], v129 offset:38912
	ds_read_b128 v[98:101], v130 offset:49152
	ds_read_b128 v[102:105], v130 offset:51200
	ds_read_b128 v[106:109], v130 offset:53248
	ds_read_b128 v[110:113], v130 offset:55296
	s_waitcnt vmcnt(0)
	s_waitcnt vmcnt(0) lgkmcnt(0)
	v_mfma_f32_16x16x32_bf16 v[72:75], v[106:109], v[90:93], v[72:75]
	s_barrier
	v_mfma_f32_16x16x32_bf16 v[44:47], v[98:101], v[82:85], v[44:47]
	v_mfma_f32_16x16x32_bf16 v[48:51], v[102:105], v[82:85], v[48:51]
	v_mfma_f32_16x16x32_bf16 v[52:55], v[106:109], v[82:85], v[52:55]
	v_mfma_f32_16x16x32_bf16 v[10:13], v[110:113], v[82:85], v[10:13]
	v_mfma_f32_16x16x32_bf16 v[40:43], v[98:101], v[86:89], v[40:43]
	v_mfma_f32_16x16x32_bf16 v[56:59], v[102:105], v[86:89], v[56:59]
	v_mfma_f32_16x16x32_bf16 v[60:63], v[106:109], v[86:89], v[60:63]
	v_mfma_f32_16x16x32_bf16 v[14:17], v[110:113], v[86:89], v[14:17]
	v_mfma_f32_16x16x32_bf16 v[64:67], v[98:101], v[90:93], v[64:67]
	v_mfma_f32_16x16x32_bf16 v[68:71], v[102:105], v[90:93], v[68:71]
	v_mfma_f32_16x16x32_bf16 v[18:21], v[110:113], v[90:93], v[18:21]
	v_mfma_f32_16x16x32_bf16 v[26:29], v[98:101], v[94:97], v[28:31]
	v_mfma_f32_16x16x32_bf16 v[30:33], v[102:105], v[94:97], v[32:35]
	v_mfma_f32_16x16x32_bf16 v[34:37], v[106:109], v[94:97], v[36:39]
	v_mfma_f32_16x16x32_bf16 v[22:25], v[110:113], v[94:97], v[22:25]
	ds_read_b128 v[82:85], v130 offset:22528
	ds_read_b128 v[86:89], v130 offset:20480
	ds_read_b128 v[90:93], v130 offset:18432
	ds_read_b128 v[94:97], v130 offset:16384
	ds_read_b128 v[98:101], v129 offset:6144
	ds_read_b128 v[102:105], v129 offset:4096
	ds_read_b128 v[106:109], v129 offset:2048
	ds_read_b128 v[110:113], v129
	ds_read_b128 v[116:119], v128 offset:22528
	ds_read_b128 v[132:135], v128 offset:20480
	ds_read_b128 v[136:139], v128 offset:18432
	ds_read_b128 v[140:143], v128 offset:16384
	ds_read_b128 v[144:147], v127 offset:6144
	ds_read_b128 v[148:151], v127 offset:4096
	ds_read_b128 v[152:155], v127 offset:2048
	ds_read_b128 v[156:159], v127
	s_waitcnt vmcnt(0)
	s_waitcnt lgkmcnt(0)
	v_mfma_f32_16x16x32_bf16 v[74:77], v[132:135], v[148:151], v[72:75]
	s_barrier
; __device__ __forceinline__ float bf2f(bf16_t h) { return __uint_as_float(((unsigned)h) << 16); }
;     ...
;         if constexpr (EPI == EPI_LG) {
;           const unsigned hh = (unsigned)(n0 + wn * 64) >> 6;
;           const unsigned bb = row / (unsigned)LP;
;           const bf16_t* yb = (bb < 2u) ? (e.y01 + (size_t)bb * LP * D) : (e.y23 + (size_t)(bb - 2u) * LP * D);
;           float yv[4][4], vv[4][4];
;           float s1 = 0.f;
; #pragma unroll
;           for (int ni = 0; ni < 4; ni++) {
;             const unsigned col = cb2 + ni * 16;
;             const uint2 yu = *(const uint2*)(yb + (size_t)pr * D + col);
;             const uint2 vu = *(const uint2*)(e.c0 + (row * (unsigned)RKLD + 2048 + col));
;             const float m_ = e.mu[row * 64u + hh * 4u + ni];
;             yv[ni][0] = bf2f((bf16_t)(yu.x & 0xffff)) + m_; yv[ni][1] = bf2f((bf16_t)(yu.x >> 16)) + m_;
;             yv[ni][2] = bf2f((bf16_t)(yu.y & 0xffff)) + m_; yv[ni][3] = bf2f((bf16_t)(yu.y >> 16)) + m_;
;             vv[ni][0] = bf2f((bf16_t)(vu.x & 0xffff)); vv[ni][1] = bf2f((bf16_t)(vu.x >> 16));
;             vv[ni][2] = bf2f((bf16_t)(vu.y & 0xffff)); vv[ni][3] = bf2f((bf16_t)(vu.y >> 16));
;             s1 += (yv[ni][0] + yv[ni][1]) + (yv[ni][2] + yv[ni][3]);
;           }
	v_mfma_f32_16x16x32_bf16 v[44:47], v[140:143], v[156:159], v[44:47]
	v_mfma_f32_16x16x32_bf16 v[52:55], v[132:135], v[156:159], v[52:55]
	v_mfma_f32_16x16x32_bf16 v[10:13], v[116:119], v[156:159], v[10:13]
	v_mfma_f32_16x16x32_bf16 v[166:169], v[132:135], v[152:155], v[60:63]
	v_mfma_f32_16x16x32_bf16 v[14:17], v[116:119], v[152:155], v[14:17]
	v_mfma_f32_16x16x32_bf16 v[18:21], v[116:119], v[148:151], v[18:21]
	v_mfma_f32_16x16x32_bf16 v[132:135], v[132:135], v[144:147], v[34:37]
	v_mfma_f32_16x16x32_bf16 v[116:119], v[116:119], v[144:147], v[22:25]
	v_mfma_f32_16x16x32_bf16 v[48:51], v[136:139], v[156:159], v[48:51]
	v_mfma_f32_16x16x32_bf16 v[156:159], v[136:139], v[152:155], v[56:59]
	v_mfma_f32_16x16x32_bf16 v[170:173], v[136:139], v[148:151], v[68:71]
	v_mfma_f32_16x16x32_bf16 v[136:139], v[136:139], v[144:147], v[30:33]
	v_mfma_f32_16x16x32_bf16 v[30:33], v[86:89], v[102:105], v[74:77]
	s_nop 2
	v_or_b32_e32 v74, s1, v125
	v_mul_hi_u32 v75, v8, s24
	v_readlane_b32 s0, v246, 7
	v_lshrrev_b32_e32 v76, 13, v75
	v_readlane_b32 s1, v246, 8
	v_mfma_f32_16x16x32_bf16 v[38:41], v[140:143], v[152:155], v[40:43]
	v_mfma_f32_16x16x32_bf16 v[152:155], v[140:143], v[148:151], v[64:67]
	v_mfma_f32_16x16x32_bf16 v[140:143], v[140:143], v[144:147], v[26:29]
	v_mfma_f32_16x16x32_bf16 v[70:73], v[94:97], v[110:113], v[44:47]
	v_mfma_f32_16x16x32_bf16 v[58:61], v[82:85], v[110:113], v[10:13]
	v_mfma_f32_16x16x32_bf16 v[42:45], v[82:85], v[106:109], v[14:17]
	v_mfma_f32_16x16x32_bf16 v[26:29], v[82:85], v[102:105], v[18:21]
	v_mfma_f32_16x16x32_bf16 v[14:17], v[86:89], v[98:101], v[132:135]
	v_mfma_f32_16x16x32_bf16 v[10:13], v[82:85], v[98:101], v[116:119]
	v_or_b32_e32 v84, v74, v126
	s_nop 0
	v_or_b32_e32 v135, v8, v122
	v_lshrrev_b32_e32 v133, 6, v74
	v_lshrrev_b32_e32 v134, 4, v74
	v_add_u32_e32 v8, -2, v76
	v_mov_b64_e32 v[74:75], s[0:1]
	s_mov_b32 s0, 0x1040000
	v_mad_u64_u32 v[74:75], s[0:1], v8, s0, v[74:75]
	v_readlane_b32 s0, v246, 5
	v_mul_u32_u24_e32 v8, 0x820000, v76
	v_readlane_b32 s1, v246, 6
	v_mfma_f32_16x16x32_bf16 v[18:21], v[90:93], v[98:101], v[136:139]
	v_mov_b32_e32 v85, v9
	v_lshl_add_u64 v[76:77], v[8:9], 1, s[0:1]
	v_mul_hi_u32 v8, v135, s24
	v_lshrrev_b32_e32 v8, 13, v8
	v_mul_u32_u24_e32 v8, 0x2080, v8
	v_sub_u32_e32 v138, v135, v8
	v_mfma_f32_16x16x32_bf16 v[66:69], v[90:93], v[110:113], v[48:51]
	v_lshlrev_b32_e32 v8, 11, v138
	v_or_b32_e32 v131, 32, v84
	v_or_b32_e32 v132, 48, v84
	v_mfma_f32_16x16x32_bf16 v[62:65], v[86:89], v[110:113], v[52:55]
	v_mfma_f32_16x16x32_bf16 v[46:49], v[86:89], v[106:109], v[166:169]
	v_cndmask_b32_e32 v89, v75, v77, vcc
	v_cndmask_b32_e32 v88, v74, v76, vcc
	v_lshl_add_u64 v[74:75], v[88:89], 0, v[8:9]
	v_mul_lo_u32 v8, v135, s15
	v_add_u32_e32 v114, 0x800, v8
	v_mfma_f32_16x16x32_bf16 v[50:53], v[90:93], v[106:109], v[156:159]
	v_add_u32_e32 v8, v114, v84
	v_lshlrev_b64 v[86:87], 2, v[84:85]
	v_lshl_add_u32 v76, v135, 6, v134
	v_mfma_f32_16x16x32_bf16 v[34:37], v[90:93], v[102:105], v[170:173]
	v_lshlrev_b64 v[90:91], 1, v[84:85]
	v_or_b32_e32 v85, 16, v84
	v_mov_b32_e32 v77, v9
	v_mfma_f32_16x16x32_bf16 v[54:57], v[94:97], v[106:109], v[38:41]
	v_lshl_add_u64 v[106:107], v[74:75], 0, v[90:91]
	v_lshl_add_u64 v[74:75], v[8:9], 1, s[52:53]
	global_load_dwordx2 v[92:93], v[106:107], off
	v_mfma_f32_16x16x32_bf16 v[38:41], v[94:97], v[102:105], v[152:155]
	v_add_u32_e32 v8, v114, v85
	v_lshl_add_u64 v[82:83], s[16:17], 0, v[86:87]
	v_cmp_gt_u32_e32 vcc, s14, v138
	v_mfma_f32_16x16x32_bf16 v[22:25], v[94:97], v[98:101], v[140:143]
	global_load_dwordx2 v[96:97], v[74:75], off
	v_lshl_add_u64 v[98:99], v[8:9], 1, s[52:53]
	global_load_dwordx2 v[100:101], v[98:99], off
	v_add_u32_e32 v8, v114, v131
	v_lshl_add_u64 v[74:75], v[76:77], 2, s[10:11]
	v_lshl_add_u64 v[102:103], v[8:9], 1, s[52:53]
	global_load_dwordx4 v[74:77], v[74:75], off
	v_add_u32_e32 v8, v114, v132
	global_load_dwordx2 v[108:109], v[102:103], off
	v_lshl_add_u64 v[86:87], s[18:19], 0, v[86:87]
	global_load_dwordx4 v[174:177], v[82:83], off offset:64
	global_load_dwordx4 v[178:181], v[82:83], off offset:128
	global_load_dwordx4 v[182:185], v[82:83], off offset:192
	global_load_dwordx4 v[186:189], v[86:87], off offset:64
	global_load_dwordx4 v[190:193], v[86:87], off offset:128
	global_load_dwordx4 v[194:197], v[86:87], off offset:192
	v_lshlrev_b32_e32 v154, 10, v135
	s_waitcnt vmcnt(4)
	v_lshlrev_b32_e32 v104, 16, v92
	v_and_b32_e32 v105, 0xffff0000, v92
	v_lshlrev_b32_e32 v110, 16, v93
	v_and_b32_e32 v111, 0xffff0000, v93
	s_waitcnt vmcnt(3)
	v_lshlrev_b32_e32 v94, 16, v96
	v_and_b32_e32 v95, 0xffff0000, v96
	v_lshlrev_b32_e32 v92, 16, v97
	v_and_b32_e32 v93, 0xffff0000, v97
	global_load_dwordx2 v[96:97], v[106:107], off offset:32
	s_waitcnt vmcnt(3)
	v_lshlrev_b32_e32 v98, 16, v100
	v_and_b32_e32 v99, 0xffff0000, v100
	s_waitcnt vmcnt(2)
	v_pk_add_f32 v[110:111], v[74:75], v[110:111] op_sel_hi:[0,1]
	s_waitcnt vmcnt(1)
	v_lshlrev_b32_e32 v102, 16, v108
	v_and_b32_e32 v103, 0xffff0000, v108
	v_pk_add_f32 v[104:105], v[74:75], v[104:105] op_sel_hi:[0,1]
	v_add_f32_e32 v148, v104, v105
	s_waitcnt vmcnt(0)
	v_lshlrev_b32_e32 v112, 16, v96
	v_and_b32_e32 v113, 0xffff0000, v96
	v_lshlrev_b32_e32 v116, 16, v97
	v_and_b32_e32 v117, 0xffff0000, v97
	v_lshlrev_b32_e32 v96, 16, v101
	v_and_b32_e32 v97, 0xffff0000, v101
	global_load_dwordx2 v[100:101], v[106:107], off offset:64
	v_pk_add_f32 v[116:117], v[74:75], v[116:117] op_sel:[1,0]
	global_load_dwordx2 v[106:107], v[106:107], off offset:96
	v_pk_add_f32 v[74:75], v[74:75], v[112:113] op_sel:[1,0]
	s_waitcnt vmcnt(1)
;     ...
;             s1 += (yv[ni][0] + yv[ni][1]) + (yv[ni][2] + yv[ni][3]);
;           }
;           const float mean = xrow16_sum(s1) * (1.f / 64.f);
;           float s2 = 0.f;
; #pragma unroll
;           for (int ni = 0; ni < 4; ni++)
; #pragma unroll
;             for (int j = 0; j < 4; j++) { yv[ni][j] -= mean; s2 += yv[ni][j] * yv[ni][j]; }
;           const float rstd = rsqrtf(xrow16_sum(s2) * (1.f / 64.f) + 64e-5f);
;           const float sb = e.sbp[row * 16u + hh];
	v_lshlrev_b32_e32 v118, 16, v100
	v_and_b32_e32 v119, 0xffff0000, v100
	v_lshlrev_b32_e32 v120, 16, v101
	v_and_b32_e32 v121, 0xffff0000, v101
	v_lshlrev_b32_e32 v100, 16, v109
	v_and_b32_e32 v101, 0xffff0000, v109
	v_lshl_add_u64 v[108:109], v[8:9], 1, s[52:53]
	global_load_dwordx2 v[136:137], v[108:109], off
	v_lshl_add_u32 v8, v135, 4, v133
	s_waitcnt vmcnt(1)
	v_lshlrev_b32_e32 v144, 16, v106
	v_and_b32_e32 v145, 0xffff0000, v106
	v_lshlrev_b32_e32 v146, 16, v107
	v_and_b32_e32 v147, 0xffff0000, v107
	v_add_f32_e32 v112, v74, v75
	v_pk_add_f32 v[120:121], v[76:77], v[120:121] op_sel_hi:[0,1]
	v_pk_add_f32 v[118:119], v[76:77], v[118:119] op_sel_hi:[0,1]
	v_add_f32_e32 v76, v118, v119
	s_waitcnt vmcnt(0)
	v_lshlrev_b32_e32 v108, 16, v136
	v_and_b32_e32 v109, 0xffff0000, v136
	v_lshlrev_b32_e32 v106, 16, v137
	v_and_b32_e32 v107, 0xffff0000, v137
	v_lshl_add_u64 v[136:137], v[8:9], 2, s[12:13]
	global_load_dword v114, v[136:137], off
	s_nop 0
	global_load_dwordx4 v[136:139], v[82:83], off
	global_load_dwordx4 v[140:143], v[86:87], off
	v_add_f32_e32 v8, v110, v111
	v_add_f32_e32 v8, v148, v8
	v_add_f32_e32 v150, 0, v8
	v_add_u32_e32 v8, v154, v84
	v_lshl_add_u64 v[148:149], v[8:9], 1, s[8:9]
	v_add_f32_e32 v8, v116, v117
	v_add_f32_e32 v8, v112, v8
	v_add_f32_e32 v150, v150, v8
	v_add_u32_e32 v8, v154, v85
	v_lshl_add_u64 v[112:113], v[8:9], 1, s[8:9]
	v_add_f32_e32 v8, v120, v121
	v_add_f32_e32 v8, v76, v8
	v_add_f32_e32 v152, v150, v8
	v_add_u32_e32 v8, v154, v131
	v_lshl_add_u64 v[150:151], v[8:9], 1, s[8:9]
	v_mov_b32_e32 v8, v77
	v_pk_add_f32 v[76:77], v[8:9], v[146:147] op_sel_hi:[0,1]
	v_pk_add_f32 v[144:145], v[8:9], v[144:145] op_sel_hi:[0,1]
	v_add_f32_e32 v8, v76, v77
	v_add_f32_e32 v146, v144, v145
	v_add_f32_e32 v8, v146, v8
	v_add_f32_e32 v8, v152, v8
	v_mov_b32_e32 v146, v8
	s_nop 1
	v_permlane16_swap_b32_e32 v8, v146
	v_add_f32_e32 v8, v8, v146
	v_mov_b32_e32 v146, v8
	s_nop 1
	v_permlane32_swap_b32_e32 v8, v146
	v_add_f32_e32 v8, v8, v146
	v_mul_f32_e32 v8, 0x3c800000, v8
	v_pk_add_f32 v[104:105], v[104:105], v[8:9] op_sel_hi:[1,0] neg_lo:[0,1] neg_hi:[0,1]
	v_pk_add_f32 v[110:111], v[110:111], v[8:9] op_sel_hi:[1,0] neg_lo:[0,1] neg_hi:[0,1]
	v_mul_f32_e32 v146, v105, v105
	v_pk_fma_f32 v[146:147], v[104:105], v[104:105], v[146:147] op_sel_hi:[1,1,0]
	v_mul_f32_e32 v152, v111, v111
	v_pk_fma_f32 v[146:147], v[110:111], v[110:111], v[146:147]
	v_pk_add_f32 v[116:117], v[116:117], v[8:9] op_sel_hi:[1,0] neg_lo:[0,1] neg_hi:[0,1]
	v_pk_add_f32 v[146:147], v[152:153], v[146:147] op_sel_hi:[0,1]
	v_pk_add_f32 v[152:153], v[74:75], v[8:9] op_sel_hi:[1,0] neg_lo:[0,1] neg_hi:[0,1]
	v_pk_add_f32 v[118:119], v[118:119], v[8:9] op_sel_hi:[1,0] neg_lo:[0,1] neg_hi:[0,1]
	v_pk_fma_f32 v[74:75], v[152:153], v[152:153], v[146:147]
	v_mul_f32_e32 v146, v153, v153
	v_pk_add_f32 v[74:75], v[146:147], v[74:75] op_sel_hi:[0,1]
	v_pk_fma_f32 v[74:75], v[116:117], v[116:117], v[74:75]
	v_mul_f32_e32 v146, v117, v117
	v_pk_add_f32 v[74:75], v[146:147], v[74:75] op_sel_hi:[0,1]
	v_pk_fma_f32 v[74:75], v[118:119], v[118:119], v[74:75]
	v_mul_f32_e32 v146, v119, v119
	v_pk_add_f32 v[74:75], v[146:147], v[74:75] op_sel_hi:[0,1]
	v_pk_add_f32 v[120:121], v[120:121], v[8:9] op_sel_hi:[1,0] neg_lo:[0,1] neg_hi:[0,1]
	v_pk_add_f32 v[144:145], v[144:145], v[8:9] op_sel_hi:[1,0] neg_lo:[0,1] neg_hi:[0,1]
	v_pk_fma_f32 v[74:75], v[120:121], v[120:121], v[74:75]
	v_mul_f32_e32 v146, v121, v121
	v_pk_add_f32 v[74:75], v[146:147], v[74:75] op_sel_hi:[0,1]
	v_pk_fma_f32 v[74:75], v[144:145], v[144:145], v[74:75]
	v_mul_f32_e32 v146, v145, v145
	v_pk_add_f32 v[74:75], v[146:147], v[74:75] op_sel_hi:[0,1]
	v_pk_add_f32 v[146:147], v[76:77], v[8:9] op_sel_hi:[1,0] neg_lo:[0,1] neg_hi:[0,1]
	s_nop 0
	v_pk_fma_f32 v[74:75], v[146:147], v[146:147], v[74:75]
	v_mul_f32_e32 v8, v147, v147
	v_pk_add_f32 v[74:75], v[8:9], v[74:75] op_sel_hi:[0,1]
	v_mov_b32_e32 v8, v74
	s_nop 1
	v_permlane16_swap_b32_e32 v74, v8
	v_add_f32_e32 v8, v74, v8
	v_mov_b32_e32 v74, v8
	s_nop 1
	v_permlane32_swap_b32_e32 v8, v74
	v_add_f32_e32 v8, v8, v74
	v_fmamk_f32 v8, v8, 0x3c800000, v206
	v_cmp_gt_f32_e64 s[0:1], s5, v8
	v_mul_f32_e32 v74, 0x4b800000, v8
	s_nop 0
	v_cndmask_b32_e64 v8, v8, v74, s[0:1]
	v_rsq_f32_e32 v8, v8
	s_nop 0
	v_mul_f32_e32 v74, 0x45800000, v8
	v_cndmask_b32_e64 v8, v8, v74, s[0:1]
	v_pk_mul_f32 v[74:75], v[104:105], v[8:9] op_sel_hi:[1,0]
	s_waitcnt vmcnt(0)
;     ...
; #pragma unroll
;           for (int ni = 0; ni < 4; ni++) {
;             const unsigned col = cb2 + ni * 16;
;             const float4 lw = *(const float4*)(e.lnw + col), lb = *(const float4*)(e.lnb + col);
;             const f32x4 a = acc[mi][ni];
;             uint2 o;
;             o.x = pack2(a[0] * (yv[ni][0] * rstd * lw.x + lb.x + sb * vv[ni][0]), a[1] * (yv[ni][1] * rstd * lw.y + lb.y + sb * vv[ni][1]));
;             o.y = pack2(a[2] * (yv[ni][2] * rstd * lw.z + lb.z + sb * vv[ni][2]), a[3] * (yv[ni][3] * rstd * lw.w + lb.w + sb * vv[ni][3]));
;             if (pr < PADR) { o.x = 0u; o.y = 0u; }
;             *(uint2*)(e.b0 + (row * (unsigned)D + col)) = o;
;           }
	v_pk_fma_f32 v[74:75], v[136:137], v[74:75], v[140:141]
	s_nop 0
	v_pk_fma_f32 v[74:75], v[114:115], v[94:95], v[74:75] op_sel_hi:[0,1,1]
	v_pk_mul_f32 v[70:71], v[70:71], v[74:75]
	s_nop 0
	v_cvt_pk_bf16_f32 v74, v70, v71
	v_pk_mul_f32 v[70:71], v[110:111], v[8:9] op_sel_hi:[1,0]
	s_nop 0
	v_pk_fma_f32 v[70:71], v[138:139], v[70:71], v[142:143]
	s_nop 0
	v_pk_fma_f32 v[70:71], v[114:115], v[92:93], v[70:71] op_sel_hi:[0,1,1]
	v_pk_mul_f32 v[70:71], v[72:73], v[70:71]
	v_pk_mul_f32 v[92:93], v[152:153], v[8:9] op_sel_hi:[1,0]
	v_cvt_pk_bf16_f32 v70, v70, v71
	v_cndmask_b32_e64 v71, v70, 0, vcc
	v_cndmask_b32_e64 v70, v74, 0, vcc
	v_lshl_add_u64 v[198:199], v[204:205], 0, v[148:149]
	v_mov_b32_e32 v200, v70
	v_mov_b32_e32 v201, v71
	s_nop 0
	s_nop 1
	v_mov_b32_e32 v70, v174
	v_mov_b32_e32 v71, v175
	v_mov_b32_e32 v72, v176
	v_mov_b32_e32 v73, v177
	v_mov_b32_e32 v74, v186
	v_mov_b32_e32 v75, v187
	v_mov_b32_e32 v76, v188
	v_mov_b32_e32 v77, v189
	v_pk_fma_f32 v[70:71], v[92:93], v[70:71], v[74:75]
	s_nop 0
	v_pk_fma_f32 v[70:71], v[114:115], v[98:99], v[70:71] op_sel_hi:[0,1,1]
	v_pk_mul_f32 v[66:67], v[66:67], v[70:71]
	v_pk_mul_f32 v[74:75], v[118:119], v[8:9] op_sel_hi:[1,0]
	v_cvt_pk_bf16_f32 v70, v66, v67
	v_pk_mul_f32 v[66:67], v[116:117], v[8:9] op_sel_hi:[1,0]
	s_nop 0
	v_pk_fma_f32 v[66:67], v[66:67], v[72:73], v[76:77]
	s_nop 0
	v_pk_fma_f32 v[66:67], v[114:115], v[96:97], v[66:67] op_sel_hi:[0,1,1]
	v_pk_mul_f32 v[66:67], v[68:69], v[66:67]
	s_nop 0
	v_cvt_pk_bf16_f32 v66, v66, v67
	v_cndmask_b32_e64 v67, v66, 0, vcc
	v_cndmask_b32_e64 v66, v70, 0, vcc
	v_mov_b32_e32 v202, v66
	v_mov_b32_e32 v203, v67
	s_nop 1
	v_permlane16_swap_b32 v200, v202
	v_permlane16_swap_b32 v201, v203
	s_nop 1
	global_store_dwordx4 v[198:199], v[200:203], off
	s_nop 0
	s_nop 1
	v_mov_b32_e32 v66, v178
	v_mov_b32_e32 v67, v179
	v_mov_b32_e32 v68, v180
	v_mov_b32_e32 v69, v181
	v_mov_b32_e32 v70, v190
	v_mov_b32_e32 v71, v191
	v_mov_b32_e32 v72, v192
	v_mov_b32_e32 v73, v193
	v_pk_fma_f32 v[66:67], v[74:75], v[66:67], v[70:71]
	s_nop 0
	v_pk_fma_f32 v[66:67], v[114:115], v[102:103], v[66:67] op_sel_hi:[0,1,1]
	v_pk_mul_f32 v[62:63], v[62:63], v[66:67]
	v_pk_mul_f32 v[70:71], v[144:145], v[8:9] op_sel_hi:[1,0]
	v_cvt_pk_bf16_f32 v66, v62, v63
	v_pk_mul_f32 v[62:63], v[120:121], v[8:9] op_sel_hi:[1,0]
	s_nop 0
	v_pk_fma_f32 v[62:63], v[62:63], v[68:69], v[72:73]
	s_nop 0
	v_pk_fma_f32 v[62:63], v[114:115], v[100:101], v[62:63] op_sel_hi:[0,1,1]
	v_pk_mul_f32 v[62:63], v[64:65], v[62:63]
	s_nop 0
	v_cvt_pk_bf16_f32 v62, v62, v63
	v_cndmask_b32_e64 v63, v62, 0, vcc
	v_cndmask_b32_e64 v62, v66, 0, vcc
	v_lshl_add_u64 v[198:199], v[204:205], 0, v[150:151]
	v_mov_b32_e32 v200, v62
	v_mov_b32_e32 v201, v63
	s_nop 0
	s_nop 1
	v_mov_b32_e32 v62, v182
	v_mov_b32_e32 v63, v183
	v_mov_b32_e32 v64, v184
	v_mov_b32_e32 v65, v185
	v_mov_b32_e32 v66, v194
	v_mov_b32_e32 v67, v195
	v_mov_b32_e32 v68, v196
	v_mov_b32_e32 v69, v197
	v_pk_fma_f32 v[62:63], v[70:71], v[62:63], v[66:67]
	s_nop 0
	v_pk_fma_f32 v[62:63], v[114:115], v[108:109], v[62:63] op_sel_hi:[0,1,1]
	v_pk_mul_f32 v[58:59], v[58:59], v[62:63]
	s_nop 0
	v_cvt_pk_bf16_f32 v62, v58, v59
	v_pk_mul_f32 v[58:59], v[146:147], v[8:9] op_sel_hi:[1,0]
	s_nop 0
	v_pk_fma_f32 v[58:59], v[58:59], v[64:65], v[68:69]
	s_nop 0
	v_pk_fma_f32 v[58:59], v[114:115], v[106:107], v[58:59] op_sel_hi:[0,1,1]
	v_pk_mul_f32 v[58:59], v[60:61], v[58:59]
	s_nop 0
	v_cvt_pk_bf16_f32 v8, v58, v59
	v_cndmask_b32_e64 v59, v8, 0, vcc
	v_add_u32_e32 v8, v154, v132
	v_cndmask_b32_e64 v58, v62, 0, vcc
	v_lshl_add_u64 v[60:61], v[8:9], 1, s[8:9]
	v_mov_b32_e32 v202, v58
	v_mov_b32_e32 v203, v59
	s_nop 1
	v_permlane16_swap_b32 v200, v202
	v_permlane16_swap_b32 v201, v203
	s_nop 1
	global_store_dwordx4 v[198:199], v[200:203], off
	v_or_b32_e32 v113, 16, v135
	v_mul_hi_u32 v8, v113, s24
	v_lshrrev_b32_e32 v8, 13, v8
	v_mul_u32_u24_e32 v8, 0x2080, v8
	v_sub_u32_e32 v117, v113, v8
	v_lshlrev_b32_e32 v8, 11, v117
	v_lshl_add_u64 v[58:59], v[88:89], 0, v[8:9]
	v_mul_lo_u32 v8, v113, s15
	v_add_u32_e32 v70, 0x800, v8
	v_lshl_add_u64 v[58:59], v[58:59], 0, v[90:91]
	v_add_u32_e32 v8, v70, v84
	global_load_dwordx2 v[92:93], v[58:59], off
	v_lshl_add_u64 v[60:61], v[8:9], 1, s[52:53]
	global_load_dwordx2 v[94:95], v[60:61], off
	global_load_dwordx2 v[96:97], v[58:59], off offset:32
	global_load_dwordx2 v[98:99], v[58:59], off offset:64
	global_load_dwordx2 v[100:101], v[58:59], off offset:96
	v_mov_b32_e32 v59, v9
	v_lshl_add_u32 v58, v113, 6, v134
	v_lshl_add_u64 v[58:59], v[58:59], 2, s[10:11]
	global_load_dwordx4 v[74:77], v[58:59], off
	s_nop 0
	global_load_dwordx4 v[58:61], v[82:83], off
	global_load_dwordx4 v[62:65], v[86:87], off
	v_add_u32_e32 v8, v70, v85
	v_lshl_add_u64 v[66:67], v[8:9], 1, s[52:53]
	v_add_u32_e32 v8, v70, v131
	v_lshl_add_u64 v[68:69], v[8:9], 1, s[52:53]
	v_add_u32_e32 v8, v70, v132
	v_lshl_add_u64 v[102:103], v[8:9], 1, s[52:53]
	v_lshl_add_u32 v8, v113, 4, v133
	v_lshl_add_u64 v[104:105], v[8:9], 2, s[12:13]
	global_load_dwordx2 v[72:73], v[66:67], off
	global_load_dwordx2 v[70:71], v[68:69], off
	s_nop 0
	global_load_dwordx2 v[68:69], v[102:103], off
	global_load_dword v66, v[104:105], off
	s_waitcnt vmcnt(10)
	v_lshlrev_b32_e32 v104, 16, v94
	v_lshlrev_b32_e32 v102, 16, v92
	v_and_b32_e32 v103, 0xffff0000, v92
	v_lshlrev_b32_e32 v92, 16, v93
	v_and_b32_e32 v93, 0xffff0000, v93
	s_waitcnt vmcnt(9)
	v_lshlrev_b32_e32 v106, 16, v96
	v_and_b32_e32 v107, 0xffff0000, v96
	v_lshlrev_b32_e32 v96, 16, v97
	v_and_b32_e32 v97, 0xffff0000, v97
	s_waitcnt vmcnt(7)
; __device__ __forceinline__ float bf2f(bf16_t h) { return __uint_as_float(((unsigned)h) << 16); }
;     ...
; #pragma unroll
;           for (int ni = 0; ni < 4; ni++) {
;             const unsigned col = cb2 + ni * 16;
;             const uint2 yu = *(const uint2*)(yb + (size_t)pr * D + col);
;             const uint2 vu = *(const uint2*)(e.c0 + (row * (unsigned)RKLD + 2048 + col));
;             const float m_ = e.mu[row * 64u + hh * 4u + ni];
;             yv[ni][0] = bf2f((bf16_t)(yu.x & 0xffff)) + m_; yv[ni][1] = bf2f((bf16_t)(yu.x >> 16)) + m_;
;             yv[ni][2] = bf2f((bf16_t)(yu.y & 0xffff)) + m_; yv[ni][3] = bf2f((bf16_t)(yu.y >> 16)) + m_;
;             vv[ni][0] = bf2f((bf16_t)(vu.x & 0xffff)); vv[ni][1] = bf2f((bf16_t)(vu.x >> 16));
;             vv[ni][2] = bf2f((bf16_t)(vu.y & 0xffff)); vv[ni][3] = bf2f((bf16_t)(vu.y >> 16));
;             s1 += (yv[ni][0] + yv[ni][1]) + (yv[ni][2] + yv[ni][3]);
;           }
;           const float mean = xrow16_sum(s1) * (1.f / 64.f);
;           float s2 = 0.f;
; #pragma unroll
;           for (int ni = 0; ni < 4; ni++)
; #pragma unroll
;             for (int j = 0; j < 4; j++) { yv[ni][j] -= mean; s2 += yv[ni][j] * yv[ni][j]; }
;           const float rstd = rsqrtf(xrow16_sum(s2) * (1.f / 64.f) + 64e-5f);
	v_lshlrev_b32_e32 v110, 16, v100
	v_and_b32_e32 v111, 0xffff0000, v100
	v_lshlrev_b32_e32 v100, 16, v101
	v_and_b32_e32 v101, 0xffff0000, v101
	s_waitcnt vmcnt(6)
	v_mov_b32_e32 v8, v77
	v_pk_add_f32 v[92:93], v[74:75], v[92:93] op_sel_hi:[0,1]
	v_pk_add_f32 v[102:103], v[74:75], v[102:103] op_sel_hi:[0,1]
	v_lshlrev_b32_e32 v108, 16, v98
	v_and_b32_e32 v109, 0xffff0000, v98
	v_lshlrev_b32_e32 v98, 16, v99
	v_and_b32_e32 v99, 0xffff0000, v99
	v_pk_add_f32 v[96:97], v[74:75], v[96:97] op_sel:[1,0]
	v_pk_add_f32 v[74:75], v[74:75], v[106:107] op_sel:[1,0]
	v_pk_add_f32 v[100:101], v[8:9], v[100:101] op_sel_hi:[0,1]
	v_pk_add_f32 v[106:107], v[8:9], v[110:111] op_sel_hi:[0,1]
	v_add_f32_e32 v8, v92, v93
	v_add_f32_e32 v67, v102, v103
	v_pk_add_f32 v[98:99], v[76:77], v[98:99] op_sel_hi:[0,1]
	v_pk_add_f32 v[76:77], v[76:77], v[108:109] op_sel_hi:[0,1]
	v_add_f32_e32 v108, v96, v97
	v_add_f32_e32 v109, v74, v75
	v_add_f32_e32 v8, v67, v8
	v_add_f32_e32 v110, v98, v99
	v_add_f32_e32 v111, v76, v77
	v_add_f32_e32 v67, v109, v108
	v_add_f32_e32 v8, 0, v8
	v_add_f32_e32 v112, v100, v101
	v_add_f32_e32 v114, v106, v107
	v_add_f32_e32 v108, v111, v110
	v_add_f32_e32 v8, v8, v67
	v_add_f32_e32 v109, v114, v112
	v_add_f32_e32 v8, v8, v108
	v_add_f32_e32 v8, v8, v109
	v_mov_b32_e32 v67, v8
	s_nop 1
	v_permlane16_swap_b32_e32 v8, v67
	v_add_f32_e32 v8, v8, v67
	v_mov_b32_e32 v67, v8
	s_nop 1
	v_permlane32_swap_b32_e32 v8, v67
	v_add_f32_e32 v8, v8, v67
	v_mul_f32_e32 v8, 0x3c800000, v8
	v_pk_add_f32 v[102:103], v[102:103], v[8:9] op_sel_hi:[1,0] neg_lo:[0,1] neg_hi:[0,1]
	v_pk_add_f32 v[92:93], v[92:93], v[8:9] op_sel_hi:[1,0] neg_lo:[0,1] neg_hi:[0,1]
	v_pk_add_f32 v[74:75], v[74:75], v[8:9] op_sel_hi:[1,0] neg_lo:[0,1] neg_hi:[0,1]
	v_pk_add_f32 v[96:97], v[96:97], v[8:9] op_sel_hi:[1,0] neg_lo:[0,1] neg_hi:[0,1]
	v_pk_add_f32 v[76:77], v[76:77], v[8:9] op_sel_hi:[1,0] neg_lo:[0,1] neg_hi:[0,1]
	v_pk_add_f32 v[98:99], v[98:99], v[8:9] op_sel_hi:[1,0] neg_lo:[0,1] neg_hi:[0,1]
	v_pk_add_f32 v[106:107], v[106:107], v[8:9] op_sel_hi:[1,0] neg_lo:[0,1] neg_hi:[0,1]
	v_pk_add_f32 v[100:101], v[100:101], v[8:9] op_sel_hi:[1,0] neg_lo:[0,1] neg_hi:[0,1]
	v_mul_f32_e32 v8, v103, v103
	v_pk_fma_f32 v[136:137], v[102:103], v[102:103], v[8:9] op_sel_hi:[1,1,0]
	v_mul_f32_e32 v108, v93, v93
	v_pk_fma_f32 v[136:137], v[92:93], v[92:93], v[136:137]
	v_mul_f32_e32 v110, v75, v75
	v_pk_add_f32 v[108:109], v[108:109], v[136:137] op_sel_hi:[0,1]
	v_pk_fma_f32 v[108:109], v[74:75], v[74:75], v[108:109]
	v_mul_f32_e32 v112, v97, v97
	v_pk_add_f32 v[108:109], v[110:111], v[108:109] op_sel_hi:[0,1]
	v_pk_fma_f32 v[108:109], v[96:97], v[96:97], v[108:109]
	v_mul_f32_e32 v114, v77, v77
	v_pk_add_f32 v[108:109], v[112:113], v[108:109] op_sel_hi:[0,1]
	v_pk_fma_f32 v[108:109], v[76:77], v[76:77], v[108:109]
	v_mul_f32_e32 v116, v99, v99
	v_pk_add_f32 v[108:109], v[114:115], v[108:109] op_sel_hi:[0,1]
	v_pk_fma_f32 v[108:109], v[98:99], v[98:99], v[108:109]
	v_mul_f32_e32 v118, v107, v107
	v_pk_add_f32 v[108:109], v[116:117], v[108:109] op_sel_hi:[0,1]
	v_pk_fma_f32 v[108:109], v[106:107], v[106:107], v[108:109]
	v_mul_f32_e32 v120, v101, v101
	v_pk_add_f32 v[108:109], v[118:119], v[108:109] op_sel_hi:[0,1]
	v_pk_fma_f32 v[108:109], v[100:101], v[100:101], v[108:109]
	v_lshlrev_b32_e32 v111, 10, v113
	v_pk_add_f32 v[108:109], v[120:121], v[108:109] op_sel_hi:[0,1]
	v_mov_b32_e32 v8, v108
	s_nop 1
	v_permlane16_swap_b32_e32 v108, v8
	v_add_f32_e32 v8, v108, v8
	v_mov_b32_e32 v67, v8
	s_nop 1
	v_permlane32_swap_b32_e32 v8, v67
	v_add_f32_e32 v8, v8, v67
	v_fmamk_f32 v8, v8, 0x3c800000, v206
	v_mul_f32_e32 v67, 0x4b800000, v8
	v_cmp_gt_f32_e32 vcc, s5, v8
	v_and_b32_e32 v105, 0xffff0000, v94
	v_lshlrev_b32_e32 v94, 16, v95
	v_cndmask_b32_e32 v8, v8, v67, vcc
	v_rsq_f32_e32 v67, v8
	v_add_u32_e32 v8, v111, v84
	v_lshl_add_u64 v[108:109], v[8:9], 1, s[8:9]
	v_and_b32_e32 v95, 0xffff0000, v95
	v_mul_f32_e32 v8, 0x45800000, v67
	v_cndmask_b32_e32 v110, v67, v8, vcc
	v_pk_mul_f32 v[102:103], v[102:103], v[110:111] op_sel_hi:[1,0]
	v_cmp_gt_u32_e32 vcc, s14, v117
	s_waitcnt vmcnt(4)
	v_pk_fma_f32 v[58:59], v[58:59], v[102:103], v[62:63]
	v_pk_mul_f32 v[74:75], v[74:75], v[110:111] op_sel_hi:[1,0]
	s_waitcnt vmcnt(0)
;     ...
; #pragma unroll
;           for (int ni = 0; ni < 4; ni++) {
;             const unsigned col = cb2 + ni * 16;
;             const float4 lw = *(const float4*)(e.lnw + col), lb = *(const float4*)(e.lnb + col);
;             const f32x4 a = acc[mi][ni];
;             uint2 o;
;             o.x = pack2(a[0] * (yv[ni][0] * rstd * lw.x + lb.x + sb * vv[ni][0]), a[1] * (yv[ni][1] * rstd * lw.y + lb.y + sb * vv[ni][1]));
;             o.y = pack2(a[2] * (yv[ni][2] * rstd * lw.z + lb.z + sb * vv[ni][2]), a[3] * (yv[ni][3] * rstd * lw.w + lb.w + sb * vv[ni][3]));
;             if (pr < PADR) { o.x = 0u; o.y = 0u; }
;             *(uint2*)(e.b0 + (row * (unsigned)D + col)) = o;
;           }
	v_pk_fma_f32 v[58:59], v[66:67], v[104:105], v[58:59] op_sel_hi:[0,1,1]
	v_pk_mul_f32 v[54:55], v[54:55], v[58:59]
	s_nop 0
	v_cvt_pk_bf16_f32 v8, v54, v55
	v_pk_mul_f32 v[54:55], v[92:93], v[110:111] op_sel_hi:[1,0]
	v_pk_mul_f32 v[92:93], v[96:97], v[110:111] op_sel_hi:[1,0]
	v_pk_fma_f32 v[54:55], v[60:61], v[54:55], v[64:65]
	v_lshlrev_b32_e32 v64, 16, v72
	v_pk_fma_f32 v[54:55], v[66:67], v[94:95], v[54:55] op_sel_hi:[0,1,1]
	v_pk_mul_f32 v[54:55], v[56:57], v[54:55]
	v_and_b32_e32 v65, 0xffff0000, v72
	v_cvt_pk_bf16_f32 v54, v54, v55
	v_cndmask_b32_e64 v55, v54, 0, vcc
	v_cndmask_b32_e64 v54, v8, 0, vcc
	v_lshl_add_u64 v[198:199], v[204:205], 0, v[108:109]
	v_mov_b32_e32 v200, v54
	v_mov_b32_e32 v201, v55
	s_nop 0
	v_lshlrev_b32_e32 v72, 16, v73
	v_and_b32_e32 v73, 0xffff0000, v73
	v_add_u32_e32 v8, v111, v85
	v_lshl_add_u64 v[62:63], v[8:9], 1, s[8:9]
	s_nop 1
	v_mov_b32_e32 v54, v174
	v_mov_b32_e32 v55, v175
	v_mov_b32_e32 v56, v176
	v_mov_b32_e32 v57, v177
	v_mov_b32_e32 v58, v186
	v_mov_b32_e32 v59, v187
	v_mov_b32_e32 v60, v188
	v_mov_b32_e32 v61, v189
	v_pk_fma_f32 v[54:55], v[74:75], v[54:55], v[58:59]
	v_pk_fma_f32 v[56:57], v[92:93], v[56:57], v[60:61]
	v_pk_fma_f32 v[54:55], v[66:67], v[64:65], v[54:55] op_sel_hi:[0,1,1]
	v_pk_fma_f32 v[56:57], v[66:67], v[72:73], v[56:57] op_sel_hi:[0,1,1]
	v_pk_mul_f32 v[50:51], v[50:51], v[54:55]
	v_pk_mul_f32 v[52:53], v[52:53], v[56:57]
	v_cvt_pk_bf16_f32 v8, v50, v51
	v_cvt_pk_bf16_f32 v50, v52, v53
	v_cndmask_b32_e64 v51, v50, 0, vcc
	v_cndmask_b32_e64 v50, v8, 0, vcc
	v_mov_b32_e32 v202, v50
	v_mov_b32_e32 v203, v51
	s_nop 1
	v_permlane16_swap_b32 v200, v202
	v_permlane16_swap_b32 v201, v203
	s_nop 1
	global_store_dwordx4 v[198:199], v[200:203], off
	s_nop 0
	v_lshlrev_b32_e32 v60, 16, v70
	v_and_b32_e32 v61, 0xffff0000, v70
	v_lshlrev_b32_e32 v62, 16, v71
	v_and_b32_e32 v63, 0xffff0000, v71
	v_pk_mul_f32 v[64:65], v[76:77], v[110:111] op_sel_hi:[1,0]
	v_pk_mul_f32 v[70:71], v[98:99], v[110:111] op_sel_hi:[1,0]
	v_add_u32_e32 v8, v111, v131
	v_lshl_add_u64 v[58:59], v[8:9], 1, s[8:9]
	s_nop 1
	v_mov_b32_e32 v50, v178
	v_mov_b32_e32 v51, v179
	v_mov_b32_e32 v52, v180
	v_mov_b32_e32 v53, v181
	v_mov_b32_e32 v54, v190
	v_mov_b32_e32 v55, v191
	v_mov_b32_e32 v56, v192
	v_mov_b32_e32 v57, v193
	v_pk_fma_f32 v[50:51], v[64:65], v[50:51], v[54:55]
	v_pk_fma_f32 v[52:53], v[70:71], v[52:53], v[56:57]
	v_pk_fma_f32 v[50:51], v[66:67], v[60:61], v[50:51] op_sel_hi:[0,1,1]
	v_pk_fma_f32 v[52:53], v[66:67], v[62:63], v[52:53] op_sel_hi:[0,1,1]
	v_pk_mul_f32 v[46:47], v[46:47], v[50:51]
	v_pk_mul_f32 v[48:49], v[48:49], v[52:53]
	v_cvt_pk_bf16_f32 v8, v46, v47
	v_cvt_pk_bf16_f32 v46, v48, v49
	v_cndmask_b32_e64 v47, v46, 0, vcc
	v_cndmask_b32_e64 v46, v8, 0, vcc
	v_lshl_add_u64 v[198:199], v[204:205], 0, v[58:59]
	v_mov_b32_e32 v200, v46
	v_mov_b32_e32 v201, v47
	s_nop 0
	v_pk_mul_f32 v[58:59], v[106:107], v[110:111] op_sel_hi:[1,0]
	v_pk_mul_f32 v[60:61], v[100:101], v[110:111] op_sel_hi:[1,0]
	v_lshlrev_b32_e32 v54, 16, v68
	v_and_b32_e32 v55, 0xffff0000, v68
	v_lshlrev_b32_e32 v56, 16, v69
	v_and_b32_e32 v57, 0xffff0000, v69
	v_add_u32_e32 v8, v111, v132
	s_nop 1
	v_mov_b32_e32 v46, v182
	v_mov_b32_e32 v47, v183
	v_mov_b32_e32 v48, v184
	v_mov_b32_e32 v49, v185
	v_mov_b32_e32 v50, v194
	v_mov_b32_e32 v51, v195
	v_mov_b32_e32 v52, v196
	v_mov_b32_e32 v53, v197
	v_pk_fma_f32 v[46:47], v[58:59], v[46:47], v[50:51]
	v_pk_fma_f32 v[48:49], v[60:61], v[48:49], v[52:53]
	v_pk_fma_f32 v[46:47], v[66:67], v[54:55], v[46:47] op_sel_hi:[0,1,1]
	v_pk_fma_f32 v[48:49], v[66:67], v[56:57], v[48:49] op_sel_hi:[0,1,1]
	v_pk_mul_f32 v[42:43], v[42:43], v[46:47]
	v_pk_mul_f32 v[44:45], v[44:45], v[48:49]
	v_cvt_pk_bf16_f32 v42, v42, v43
	v_cvt_pk_bf16_f32 v43, v44, v45
	v_cndmask_b32_e64 v43, v43, 0, vcc
	v_cndmask_b32_e64 v42, v42, 0, vcc
	v_lshl_add_u64 v[44:45], v[8:9], 1, s[8:9]
	v_mov_b32_e32 v202, v42
	v_mov_b32_e32 v203, v43
	s_nop 1
	v_permlane16_swap_b32 v200, v202
	v_permlane16_swap_b32 v201, v203
	s_nop 1
	global_store_dwordx4 v[198:199], v[200:203], off
	v_or_b32_e32 v97, 32, v135
	v_mul_hi_u32 v8, v97, s24
	v_lshrrev_b32_e32 v8, 13, v8
	v_mul_u32_u24_e32 v8, 0x2080, v8
	v_sub_u32_e32 v99, v97, v8
	v_lshlrev_b32_e32 v8, 11, v99
	v_lshl_add_u64 v[42:43], v[88:89], 0, v[8:9]
	v_mul_lo_u32 v8, v97, s15
	v_add_u32_e32 v54, 0x800, v8
	v_lshl_add_u64 v[42:43], v[42:43], 0, v[90:91]
	v_add_u32_e32 v8, v54, v84
	global_load_dwordx2 v[62:63], v[42:43], off
	v_lshl_add_u64 v[44:45], v[8:9], 1, s[52:53]
	global_load_dwordx2 v[64:65], v[44:45], off
	global_load_dwordx2 v[66:67], v[42:43], off offset:32
	global_load_dwordx2 v[68:69], v[42:43], off offset:64
	global_load_dwordx2 v[70:71], v[42:43], off offset:96
	v_mov_b32_e32 v43, v9
	v_lshl_add_u32 v42, v97, 6, v134
	v_lshl_add_u64 v[42:43], v[42:43], 2, s[10:11]
	global_load_dwordx4 v[58:61], v[42:43], off
	s_nop 0
	global_load_dwordx4 v[42:45], v[82:83], off
	global_load_dwordx4 v[46:49], v[86:87], off
	v_add_u32_e32 v8, v54, v85
	v_lshl_add_u64 v[50:51], v[8:9], 1, s[52:53]
	v_add_u32_e32 v8, v54, v131
	v_lshl_add_u64 v[52:53], v[8:9], 1, s[52:53]
	v_add_u32_e32 v8, v54, v132
	v_lshl_add_u64 v[72:73], v[8:9], 1, s[52:53]
	v_lshl_add_u32 v8, v97, 4, v133
	v_lshl_add_u64 v[74:75], v[8:9], 2, s[12:13]
	global_load_dwordx2 v[56:57], v[50:51], off
	global_load_dwordx2 v[54:55], v[52:53], off
	s_nop 0
	global_load_dwordx2 v[52:53], v[72:73], off
	global_load_dword v50, v[74:75], off
	s_waitcnt vmcnt(10)
	v_lshlrev_b32_e32 v74, 16, v64
	v_lshlrev_b32_e32 v72, 16, v62
	v_and_b32_e32 v73, 0xffff0000, v62
	v_lshlrev_b32_e32 v62, 16, v63
	v_and_b32_e32 v63, 0xffff0000, v63
	s_waitcnt vmcnt(9)
; __device__ __forceinline__ float bf2f(bf16_t h) { return __uint_as_float(((unsigned)h) << 16); }
;     ...
; #pragma unroll
;           for (int ni = 0; ni < 4; ni++) {
;             const unsigned col = cb2 + ni * 16;
;             const uint2 yu = *(const uint2*)(yb + (size_t)pr * D + col);
;             const uint2 vu = *(const uint2*)(e.c0 + (row * (unsigned)RKLD + 2048 + col));
;             const float m_ = e.mu[row * 64u + hh * 4u + ni];
;             yv[ni][0] = bf2f((bf16_t)(yu.x & 0xffff)) + m_; yv[ni][1] = bf2f((bf16_t)(yu.x >> 16)) + m_;
;             yv[ni][2] = bf2f((bf16_t)(yu.y & 0xffff)) + m_; yv[ni][3] = bf2f((bf16_t)(yu.y >> 16)) + m_;
;             vv[ni][0] = bf2f((bf16_t)(vu.x & 0xffff)); vv[ni][1] = bf2f((bf16_t)(vu.x >> 16));
;             vv[ni][2] = bf2f((bf16_t)(vu.y & 0xffff)); vv[ni][3] = bf2f((bf16_t)(vu.y >> 16));
;             s1 += (yv[ni][0] + yv[ni][1]) + (yv[ni][2] + yv[ni][3]);
;           }
;           const float mean = xrow16_sum(s1) * (1.f / 64.f);
;           float s2 = 0.f;
; #pragma unroll
;           for (int ni = 0; ni < 4; ni++)
; #pragma unroll
;             for (int j = 0; j < 4; j++) { yv[ni][j] -= mean; s2 += yv[ni][j] * yv[ni][j]; }
;           const float rstd = rsqrtf(xrow16_sum(s2) * (1.f / 64.f) + 64e-5f);
	v_lshlrev_b32_e32 v76, 16, v66
	v_and_b32_e32 v77, 0xffff0000, v66
	v_lshlrev_b32_e32 v66, 16, v67
	v_and_b32_e32 v67, 0xffff0000, v67
	s_waitcnt vmcnt(7)
	v_lshlrev_b32_e32 v94, 16, v70
	v_and_b32_e32 v95, 0xffff0000, v70
	v_lshlrev_b32_e32 v70, 16, v71
	v_and_b32_e32 v71, 0xffff0000, v71
	s_waitcnt vmcnt(6)
	v_mov_b32_e32 v8, v61
	v_pk_add_f32 v[62:63], v[58:59], v[62:63] op_sel_hi:[0,1]
	v_pk_add_f32 v[72:73], v[58:59], v[72:73] op_sel_hi:[0,1]
	v_lshlrev_b32_e32 v92, 16, v68
	v_and_b32_e32 v93, 0xffff0000, v68
	v_lshlrev_b32_e32 v68, 16, v69
	v_and_b32_e32 v69, 0xffff0000, v69
	v_pk_add_f32 v[66:67], v[58:59], v[66:67] op_sel:[1,0]
	v_pk_add_f32 v[58:59], v[58:59], v[76:77] op_sel:[1,0]
	v_pk_add_f32 v[70:71], v[8:9], v[70:71] op_sel_hi:[0,1]
	v_pk_add_f32 v[76:77], v[8:9], v[94:95] op_sel_hi:[0,1]
	v_add_f32_e32 v8, v62, v63
	v_add_f32_e32 v51, v72, v73
	v_pk_add_f32 v[68:69], v[60:61], v[68:69] op_sel_hi:[0,1]
	v_pk_add_f32 v[60:61], v[60:61], v[92:93] op_sel_hi:[0,1]
	v_add_f32_e32 v92, v66, v67
	v_add_f32_e32 v93, v58, v59
	v_add_f32_e32 v8, v51, v8
	v_add_f32_e32 v94, v68, v69
	v_add_f32_e32 v95, v60, v61
	v_add_f32_e32 v51, v93, v92
	v_add_f32_e32 v8, 0, v8
	v_add_f32_e32 v96, v70, v71
	v_add_f32_e32 v98, v76, v77
	v_add_f32_e32 v92, v95, v94
	v_add_f32_e32 v8, v8, v51
	v_add_f32_e32 v93, v98, v96
	v_add_f32_e32 v8, v8, v92
	v_add_f32_e32 v8, v8, v93
	v_mov_b32_e32 v51, v8
	s_nop 1
	v_permlane16_swap_b32_e32 v8, v51
	v_add_f32_e32 v8, v8, v51
	v_mov_b32_e32 v51, v8
	s_nop 1
	v_permlane32_swap_b32_e32 v8, v51
	v_add_f32_e32 v8, v8, v51
	v_mul_f32_e32 v8, 0x3c800000, v8
	v_pk_add_f32 v[72:73], v[72:73], v[8:9] op_sel_hi:[1,0] neg_lo:[0,1] neg_hi:[0,1]
	v_pk_add_f32 v[62:63], v[62:63], v[8:9] op_sel_hi:[1,0] neg_lo:[0,1] neg_hi:[0,1]
	v_pk_add_f32 v[58:59], v[58:59], v[8:9] op_sel_hi:[1,0] neg_lo:[0,1] neg_hi:[0,1]
	v_pk_add_f32 v[66:67], v[66:67], v[8:9] op_sel_hi:[1,0] neg_lo:[0,1] neg_hi:[0,1]
	v_pk_add_f32 v[60:61], v[60:61], v[8:9] op_sel_hi:[1,0] neg_lo:[0,1] neg_hi:[0,1]
	v_pk_add_f32 v[68:69], v[68:69], v[8:9] op_sel_hi:[1,0] neg_lo:[0,1] neg_hi:[0,1]
	v_pk_add_f32 v[76:77], v[76:77], v[8:9] op_sel_hi:[1,0] neg_lo:[0,1] neg_hi:[0,1]
	v_pk_add_f32 v[70:71], v[70:71], v[8:9] op_sel_hi:[1,0] neg_lo:[0,1] neg_hi:[0,1]
	v_mul_f32_e32 v8, v73, v73
	v_pk_fma_f32 v[106:107], v[72:73], v[72:73], v[8:9] op_sel_hi:[1,1,0]
	v_mul_f32_e32 v92, v63, v63
	v_pk_fma_f32 v[106:107], v[62:63], v[62:63], v[106:107]
	v_mul_f32_e32 v94, v59, v59
	v_pk_add_f32 v[92:93], v[92:93], v[106:107] op_sel_hi:[0,1]
	v_pk_fma_f32 v[92:93], v[58:59], v[58:59], v[92:93]
	v_mul_f32_e32 v96, v67, v67
	v_pk_add_f32 v[92:93], v[94:95], v[92:93] op_sel_hi:[0,1]
	v_pk_fma_f32 v[92:93], v[66:67], v[66:67], v[92:93]
	v_mul_f32_e32 v98, v61, v61
	v_pk_add_f32 v[92:93], v[96:97], v[92:93] op_sel_hi:[0,1]
	v_pk_fma_f32 v[92:93], v[60:61], v[60:61], v[92:93]
	v_mul_f32_e32 v100, v69, v69
	v_pk_add_f32 v[92:93], v[98:99], v[92:93] op_sel_hi:[0,1]
	v_pk_fma_f32 v[92:93], v[68:69], v[68:69], v[92:93]
	v_mul_f32_e32 v102, v77, v77
	v_pk_add_f32 v[92:93], v[100:101], v[92:93] op_sel_hi:[0,1]
	v_pk_fma_f32 v[92:93], v[76:77], v[76:77], v[92:93]
	v_mul_f32_e32 v104, v71, v71
	v_pk_add_f32 v[92:93], v[102:103], v[92:93] op_sel_hi:[0,1]
	v_pk_fma_f32 v[92:93], v[70:71], v[70:71], v[92:93]
	v_lshlrev_b32_e32 v95, 10, v97
	v_pk_add_f32 v[92:93], v[104:105], v[92:93] op_sel_hi:[0,1]
	v_mov_b32_e32 v8, v92
	s_nop 1
	v_permlane16_swap_b32_e32 v92, v8
	v_add_f32_e32 v8, v92, v8
	v_mov_b32_e32 v51, v8
	s_nop 1
	v_permlane32_swap_b32_e32 v8, v51
	v_add_f32_e32 v8, v8, v51
	v_fmamk_f32 v8, v8, 0x3c800000, v206
	v_mul_f32_e32 v51, 0x4b800000, v8
	v_cmp_gt_f32_e32 vcc, s5, v8
	v_and_b32_e32 v75, 0xffff0000, v64
	v_lshlrev_b32_e32 v64, 16, v65
	v_cndmask_b32_e32 v8, v8, v51, vcc
	v_rsq_f32_e32 v51, v8
	v_add_u32_e32 v8, v95, v84
	v_lshl_add_u64 v[92:93], v[8:9], 1, s[8:9]
	v_and_b32_e32 v65, 0xffff0000, v65
	v_mul_f32_e32 v8, 0x45800000, v51
	v_cndmask_b32_e32 v94, v51, v8, vcc
	v_pk_mul_f32 v[72:73], v[72:73], v[94:95] op_sel_hi:[1,0]
	v_cmp_gt_u32_e32 vcc, s14, v99
	s_waitcnt vmcnt(4)
	v_pk_fma_f32 v[42:43], v[42:43], v[72:73], v[46:47]
	v_pk_mul_f32 v[58:59], v[58:59], v[94:95] op_sel_hi:[1,0]
	s_waitcnt vmcnt(0)
;     ...
; #pragma unroll
;           for (int ni = 0; ni < 4; ni++) {
;             const unsigned col = cb2 + ni * 16;
;             const float4 lw = *(const float4*)(e.lnw + col), lb = *(const float4*)(e.lnb + col);
;             const f32x4 a = acc[mi][ni];
;             uint2 o;
;             o.x = pack2(a[0] * (yv[ni][0] * rstd * lw.x + lb.x + sb * vv[ni][0]), a[1] * (yv[ni][1] * rstd * lw.y + lb.y + sb * vv[ni][1]));
;             o.y = pack2(a[2] * (yv[ni][2] * rstd * lw.z + lb.z + sb * vv[ni][2]), a[3] * (yv[ni][3] * rstd * lw.w + lb.w + sb * vv[ni][3]));
;             if (pr < PADR) { o.x = 0u; o.y = 0u; }
;             *(uint2*)(e.b0 + (row * (unsigned)D + col)) = o;
;           }
	v_pk_fma_f32 v[42:43], v[50:51], v[74:75], v[42:43] op_sel_hi:[0,1,1]
	v_pk_mul_f32 v[38:39], v[38:39], v[42:43]
	s_nop 0
	v_cvt_pk_bf16_f32 v8, v38, v39
	v_pk_mul_f32 v[38:39], v[62:63], v[94:95] op_sel_hi:[1,0]
	v_pk_mul_f32 v[62:63], v[66:67], v[94:95] op_sel_hi:[1,0]
	v_pk_fma_f32 v[38:39], v[44:45], v[38:39], v[48:49]
	v_lshlrev_b32_e32 v48, 16, v56
	v_pk_fma_f32 v[38:39], v[50:51], v[64:65], v[38:39] op_sel_hi:[0,1,1]
	v_pk_mul_f32 v[38:39], v[40:41], v[38:39]
	v_and_b32_e32 v49, 0xffff0000, v56
	v_cvt_pk_bf16_f32 v38, v38, v39
	v_cndmask_b32_e64 v39, v38, 0, vcc
	v_cndmask_b32_e64 v38, v8, 0, vcc
	v_lshl_add_u64 v[198:199], v[204:205], 0, v[92:93]
	v_mov_b32_e32 v200, v38
	v_mov_b32_e32 v201, v39
	s_nop 0
	v_lshlrev_b32_e32 v56, 16, v57
	v_and_b32_e32 v57, 0xffff0000, v57
	v_add_u32_e32 v8, v95, v85
	v_lshl_add_u64 v[46:47], v[8:9], 1, s[8:9]
	s_nop 1
	v_mov_b32_e32 v38, v174
	v_mov_b32_e32 v39, v175
	v_mov_b32_e32 v40, v176
	v_mov_b32_e32 v41, v177
	v_mov_b32_e32 v42, v186
	v_mov_b32_e32 v43, v187
	v_mov_b32_e32 v44, v188
	v_mov_b32_e32 v45, v189
	v_pk_fma_f32 v[38:39], v[58:59], v[38:39], v[42:43]
	v_pk_fma_f32 v[40:41], v[62:63], v[40:41], v[44:45]
	v_pk_fma_f32 v[38:39], v[50:51], v[48:49], v[38:39] op_sel_hi:[0,1,1]
	v_pk_fma_f32 v[40:41], v[50:51], v[56:57], v[40:41] op_sel_hi:[0,1,1]
	v_pk_mul_f32 v[34:35], v[34:35], v[38:39]
	v_pk_mul_f32 v[36:37], v[36:37], v[40:41]
	v_cvt_pk_bf16_f32 v8, v34, v35
	v_cvt_pk_bf16_f32 v34, v36, v37
	v_cndmask_b32_e64 v35, v34, 0, vcc
	v_cndmask_b32_e64 v34, v8, 0, vcc
	v_mov_b32_e32 v202, v34
	v_mov_b32_e32 v203, v35
	s_nop 1
	v_permlane16_swap_b32 v200, v202
	v_permlane16_swap_b32 v201, v203
	s_nop 1
	global_store_dwordx4 v[198:199], v[200:203], off
	s_nop 0
	v_lshlrev_b32_e32 v44, 16, v54
	v_and_b32_e32 v45, 0xffff0000, v54
	v_lshlrev_b32_e32 v46, 16, v55
	v_and_b32_e32 v47, 0xffff0000, v55
	v_pk_mul_f32 v[48:49], v[60:61], v[94:95] op_sel_hi:[1,0]
	v_pk_mul_f32 v[54:55], v[68:69], v[94:95] op_sel_hi:[1,0]
	v_add_u32_e32 v8, v95, v131
	v_lshl_add_u64 v[42:43], v[8:9], 1, s[8:9]
	s_nop 1
	v_mov_b32_e32 v34, v178
	v_mov_b32_e32 v35, v179
	v_mov_b32_e32 v36, v180
	v_mov_b32_e32 v37, v181
	v_mov_b32_e32 v38, v190
	v_mov_b32_e32 v39, v191
	v_mov_b32_e32 v40, v192
	v_mov_b32_e32 v41, v193
	v_pk_fma_f32 v[34:35], v[48:49], v[34:35], v[38:39]
	v_pk_fma_f32 v[36:37], v[54:55], v[36:37], v[40:41]
	v_pk_fma_f32 v[34:35], v[50:51], v[44:45], v[34:35] op_sel_hi:[0,1,1]
	v_pk_fma_f32 v[36:37], v[50:51], v[46:47], v[36:37] op_sel_hi:[0,1,1]
	v_pk_mul_f32 v[30:31], v[30:31], v[34:35]
	v_pk_mul_f32 v[32:33], v[32:33], v[36:37]
	v_cvt_pk_bf16_f32 v8, v30, v31
	v_cvt_pk_bf16_f32 v30, v32, v33
	v_cndmask_b32_e64 v31, v30, 0, vcc
	v_cndmask_b32_e64 v30, v8, 0, vcc
	v_lshl_add_u64 v[198:199], v[204:205], 0, v[42:43]
	v_mov_b32_e32 v200, v30
	v_mov_b32_e32 v201, v31
	s_nop 0
	v_pk_mul_f32 v[42:43], v[76:77], v[94:95] op_sel_hi:[1,0]
	v_pk_mul_f32 v[44:45], v[70:71], v[94:95] op_sel_hi:[1,0]
	v_lshlrev_b32_e32 v38, 16, v52
	v_and_b32_e32 v39, 0xffff0000, v52
	v_lshlrev_b32_e32 v40, 16, v53
	v_and_b32_e32 v41, 0xffff0000, v53
	v_add_u32_e32 v8, v95, v132
	s_nop 1
	v_mov_b32_e32 v30, v182
	v_mov_b32_e32 v31, v183
	v_mov_b32_e32 v32, v184
	v_mov_b32_e32 v33, v185
	v_mov_b32_e32 v34, v194
	v_mov_b32_e32 v35, v195
	v_mov_b32_e32 v36, v196
	v_mov_b32_e32 v37, v197
	v_pk_fma_f32 v[30:31], v[42:43], v[30:31], v[34:35]
	v_pk_fma_f32 v[32:33], v[44:45], v[32:33], v[36:37]
	v_pk_fma_f32 v[30:31], v[50:51], v[38:39], v[30:31] op_sel_hi:[0,1,1]
	v_pk_fma_f32 v[32:33], v[50:51], v[40:41], v[32:33] op_sel_hi:[0,1,1]
	v_pk_mul_f32 v[26:27], v[26:27], v[30:31]
	v_pk_mul_f32 v[28:29], v[28:29], v[32:33]
	v_cvt_pk_bf16_f32 v26, v26, v27
	v_cvt_pk_bf16_f32 v27, v28, v29
	v_cndmask_b32_e64 v27, v27, 0, vcc
	v_cndmask_b32_e64 v26, v26, 0, vcc
	v_lshl_add_u64 v[28:29], v[8:9], 1, s[8:9]
	v_mov_b32_e32 v202, v26
	v_mov_b32_e32 v203, v27
	s_nop 1
	v_permlane16_swap_b32 v200, v202
	v_permlane16_swap_b32 v201, v203
	s_nop 1
	global_store_dwordx4 v[198:199], v[200:203], off
	v_or_b32_e32 v67, 48, v135
	v_mul_hi_u32 v8, v67, s24
	v_lshrrev_b32_e32 v8, 13, v8
	v_mul_u32_u24_e32 v8, 0x2080, v8
	v_sub_u32_e32 v69, v67, v8
	v_lshlrev_b32_e32 v8, 11, v69
	v_lshl_add_u64 v[26:27], v[88:89], 0, v[8:9]
	v_mul_lo_u32 v8, v67, s15
	v_add_u32_e32 v30, 0x800, v8
	v_add_u32_e32 v8, v30, v84
	v_lshl_add_u64 v[26:27], v[26:27], 0, v[90:91]
	v_lshl_add_u64 v[28:29], v[8:9], 1, s[52:53]
	global_load_dwordx2 v[44:45], v[26:27], off
	global_load_dwordx2 v[46:47], v[28:29], off
	global_load_dwordx2 v[48:49], v[26:27], off offset:32
	global_load_dwordx2 v[50:51], v[26:27], off offset:64
	v_mov_b32_e32 v29, v9
	v_lshl_add_u32 v28, v67, 6, v134
	global_load_dwordx2 v[52:53], v[26:27], off offset:96
	v_lshl_add_u64 v[26:27], v[28:29], 2, s[10:11]
	global_load_dwordx4 v[32:35], v[26:27], off
	global_load_dwordx4 v[36:39], v[82:83], off
	global_load_dwordx4 v[40:43], v[86:87], off
	v_add_u32_e32 v8, v30, v85
	v_lshl_add_u64 v[26:27], v[8:9], 1, s[52:53]
	v_add_u32_e32 v8, v30, v131
	v_lshl_add_u64 v[28:29], v[8:9], 1, s[52:53]
	v_add_u32_e32 v8, v30, v132
	v_lshl_add_u64 v[54:55], v[8:9], 1, s[52:53]
	v_lshl_add_u32 v8, v67, 4, v133
	v_lshl_add_u64 v[56:57], v[8:9], 2, s[12:13]
	global_load_dwordx2 v[58:59], v[26:27], off
	global_load_dwordx2 v[30:31], v[28:29], off
	s_nop 0
	global_load_dwordx2 v[28:29], v[54:55], off
	global_load_dword v26, v[56:57], off
	s_waitcnt vmcnt(10)
	v_lshlrev_b32_e32 v56, 16, v46
	v_lshlrev_b32_e32 v54, 16, v44
	v_and_b32_e32 v55, 0xffff0000, v44
	v_lshlrev_b32_e32 v44, 16, v45
	v_and_b32_e32 v45, 0xffff0000, v45
	s_waitcnt vmcnt(8)
; __device__ __forceinline__ float bf2f(bf16_t h) { return __uint_as_float(((unsigned)h) << 16); }
;     ...
; #pragma unroll
;           for (int ni = 0; ni < 4; ni++) {
;             const unsigned col = cb2 + ni * 16;
;             const uint2 yu = *(const uint2*)(yb + (size_t)pr * D + col);
;             const uint2 vu = *(const uint2*)(e.c0 + (row * (unsigned)RKLD + 2048 + col));
;             const float m_ = e.mu[row * 64u + hh * 4u + ni];
;             yv[ni][0] = bf2f((bf16_t)(yu.x & 0xffff)) + m_; yv[ni][1] = bf2f((bf16_t)(yu.x >> 16)) + m_;
;             yv[ni][2] = bf2f((bf16_t)(yu.y & 0xffff)) + m_; yv[ni][3] = bf2f((bf16_t)(yu.y >> 16)) + m_;
;             vv[ni][0] = bf2f((bf16_t)(vu.x & 0xffff)); vv[ni][1] = bf2f((bf16_t)(vu.x >> 16));
;             vv[ni][2] = bf2f((bf16_t)(vu.y & 0xffff)); vv[ni][3] = bf2f((bf16_t)(vu.y >> 16));
;             s1 += (yv[ni][0] + yv[ni][1]) + (yv[ni][2] + yv[ni][3]);
;           }
;           const float mean = xrow16_sum(s1) * (1.f / 64.f);
;           float s2 = 0.f;
; #pragma unroll
;           for (int ni = 0; ni < 4; ni++)
; #pragma unroll
;             for (int j = 0; j < 4; j++) { yv[ni][j] -= mean; s2 += yv[ni][j] * yv[ni][j]; }
;           const float rstd = rsqrtf(xrow16_sum(s2) * (1.f / 64.f) + 64e-5f);
	v_lshlrev_b32_e32 v62, 16, v50
	v_and_b32_e32 v63, 0xffff0000, v50
	v_lshlrev_b32_e32 v50, 16, v51
	v_and_b32_e32 v51, 0xffff0000, v51
	s_waitcnt vmcnt(7)
	v_lshlrev_b32_e32 v64, 16, v52
	v_and_b32_e32 v65, 0xffff0000, v52
	s_waitcnt vmcnt(6)
	v_mov_b32_e32 v8, v35
	v_lshlrev_b32_e32 v52, 16, v53
	v_and_b32_e32 v53, 0xffff0000, v53
	v_lshlrev_b32_e32 v60, 16, v48
	v_and_b32_e32 v61, 0xffff0000, v48
	v_lshlrev_b32_e32 v48, 16, v49
	v_and_b32_e32 v49, 0xffff0000, v49
	v_pk_add_f32 v[62:63], v[34:35], v[62:63] op_sel_hi:[0,1]
	v_pk_add_f32 v[34:35], v[34:35], v[50:51] op_sel_hi:[0,1]
	v_pk_add_f32 v[50:51], v[8:9], v[64:65] op_sel_hi:[0,1]
	v_pk_add_f32 v[52:53], v[8:9], v[52:53] op_sel_hi:[0,1]
	v_pk_add_f32 v[44:45], v[32:33], v[44:45] op_sel_hi:[0,1]
	v_pk_add_f32 v[54:55], v[32:33], v[54:55] op_sel_hi:[0,1]
	v_pk_add_f32 v[48:49], v[32:33], v[48:49] op_sel:[1,0]
	v_pk_add_f32 v[32:33], v[32:33], v[60:61] op_sel:[1,0]
	v_add_f32_e32 v8, v34, v35
	v_add_f32_e32 v27, v62, v63
	v_add_f32_e32 v60, v52, v53
	v_add_f32_e32 v61, v50, v51
	v_add_f32_e32 v64, v44, v45
	v_add_f32_e32 v65, v54, v55
	v_add_f32_e32 v66, v48, v49
	v_add_f32_e32 v68, v32, v33
	v_add_f32_e32 v8, v27, v8
	v_add_f32_e32 v27, v61, v60
	v_add_f32_e32 v60, v65, v64
	v_add_f32_e32 v61, v68, v66
	v_add_f32_e32 v60, 0, v60
	v_add_f32_e32 v60, v60, v61
	v_add_f32_e32 v8, v60, v8
	v_add_f32_e32 v8, v8, v27
	v_mov_b32_e32 v27, v8
	s_nop 1
	v_permlane16_swap_b32_e32 v8, v27
	v_add_f32_e32 v8, v8, v27
	v_mov_b32_e32 v27, v8
	s_nop 1
	v_permlane32_swap_b32_e32 v8, v27
	v_add_f32_e32 v8, v8, v27
	v_mul_f32_e32 v8, 0x3c800000, v8
	v_pk_add_f32 v[54:55], v[54:55], v[8:9] op_sel_hi:[1,0] neg_lo:[0,1] neg_hi:[0,1]
	v_pk_add_f32 v[44:45], v[44:45], v[8:9] op_sel_hi:[1,0] neg_lo:[0,1] neg_hi:[0,1]
	v_pk_add_f32 v[60:61], v[32:33], v[8:9] op_sel_hi:[1,0] neg_lo:[0,1] neg_hi:[0,1]
	v_pk_add_f32 v[48:49], v[48:49], v[8:9] op_sel_hi:[1,0] neg_lo:[0,1] neg_hi:[0,1]
	v_pk_add_f32 v[62:63], v[62:63], v[8:9] op_sel_hi:[1,0] neg_lo:[0,1] neg_hi:[0,1]
	v_pk_add_f32 v[64:65], v[34:35], v[8:9] op_sel_hi:[1,0] neg_lo:[0,1] neg_hi:[0,1]
	v_pk_add_f32 v[50:51], v[50:51], v[8:9] op_sel_hi:[1,0] neg_lo:[0,1] neg_hi:[0,1]
	v_pk_add_f32 v[52:53], v[52:53], v[8:9] op_sel_hi:[1,0] neg_lo:[0,1] neg_hi:[0,1]
	v_mul_f32_e32 v8, v55, v55
	v_pk_fma_f32 v[76:77], v[54:55], v[54:55], v[8:9] op_sel_hi:[1,1,0]
	v_mul_f32_e32 v32, v45, v45
	v_pk_fma_f32 v[76:77], v[44:45], v[44:45], v[76:77]
	v_mul_f32_e32 v34, v61, v61
	v_pk_add_f32 v[32:33], v[32:33], v[76:77] op_sel_hi:[0,1]
	v_pk_fma_f32 v[32:33], v[60:61], v[60:61], v[32:33]
	v_mul_f32_e32 v66, v49, v49
	v_pk_add_f32 v[32:33], v[34:35], v[32:33] op_sel_hi:[0,1]
	v_pk_fma_f32 v[32:33], v[48:49], v[48:49], v[32:33]
	v_mul_f32_e32 v68, v63, v63
	v_pk_add_f32 v[32:33], v[66:67], v[32:33] op_sel_hi:[0,1]
	v_pk_fma_f32 v[32:33], v[62:63], v[62:63], v[32:33]
	v_mul_f32_e32 v70, v65, v65
	v_pk_add_f32 v[32:33], v[68:69], v[32:33] op_sel_hi:[0,1]
	v_pk_fma_f32 v[32:33], v[64:65], v[64:65], v[32:33]
	v_mul_f32_e32 v72, v51, v51
	v_pk_add_f32 v[32:33], v[70:71], v[32:33] op_sel_hi:[0,1]
	v_pk_fma_f32 v[32:33], v[50:51], v[50:51], v[32:33]
	v_mul_f32_e32 v74, v53, v53
	v_pk_add_f32 v[32:33], v[72:73], v[32:33] op_sel_hi:[0,1]
	v_pk_fma_f32 v[32:33], v[52:53], v[52:53], v[32:33]
	v_lshlrev_b32_e32 v67, 10, v67
	v_pk_add_f32 v[32:33], v[74:75], v[32:33] op_sel_hi:[0,1]
	v_mov_b32_e32 v8, v32
	s_nop 1
	v_permlane16_swap_b32_e32 v32, v8
	v_add_f32_e32 v8, v32, v8
	v_mov_b32_e32 v27, v8
	s_nop 1
	v_permlane32_swap_b32_e32 v8, v27
	v_add_f32_e32 v8, v8, v27
	v_fmamk_f32 v8, v8, 0x3c800000, v206
	v_mul_f32_e32 v27, 0x4b800000, v8
	v_cmp_gt_f32_e32 vcc, s5, v8
	v_and_b32_e32 v57, 0xffff0000, v46
	v_lshlrev_b32_e32 v46, 16, v47
	v_cndmask_b32_e32 v8, v8, v27, vcc
	v_rsq_f32_e32 v27, v8
	v_add_u32_e32 v8, v67, v84
	v_lshl_add_u64 v[32:33], v[8:9], 1, s[8:9]
	v_and_b32_e32 v47, 0xffff0000, v47
	v_mul_f32_e32 v8, 0x45800000, v27
	v_cndmask_b32_e32 v66, v27, v8, vcc
	v_pk_mul_f32 v[34:35], v[54:55], v[66:67] op_sel_hi:[1,0]
	v_cmp_gt_u32_e32 vcc, s14, v69
	s_waitcnt vmcnt(4)
	v_pk_fma_f32 v[34:35], v[36:37], v[34:35], v[40:41]
	s_waitcnt vmcnt(3)
;     ...
; #pragma unroll
;           for (int ni = 0; ni < 4; ni++) {
;             const unsigned col = cb2 + ni * 16;
;             const float4 lw = *(const float4*)(e.lnw + col), lb = *(const float4*)(e.lnb + col);
;             const f32x4 a = acc[mi][ni];
;             uint2 o;
;             o.x = pack2(a[0] * (yv[ni][0] * rstd * lw.x + lb.x + sb * vv[ni][0]), a[1] * (yv[ni][1] * rstd * lw.y + lb.y + sb * vv[ni][1]));
;             o.y = pack2(a[2] * (yv[ni][2] * rstd * lw.z + lb.z + sb * vv[ni][2]), a[3] * (yv[ni][3] * rstd * lw.w + lb.w + sb * vv[ni][3]));
;             if (pr < PADR) { o.x = 0u; o.y = 0u; }
;             *(uint2*)(e.b0 + (row * (unsigned)D + col)) = o;
;           }
	v_lshlrev_b32_e32 v40, 16, v59
	s_waitcnt vmcnt(0)
	v_pk_fma_f32 v[34:35], v[26:27], v[56:57], v[34:35] op_sel_hi:[0,1,1]
	v_pk_mul_f32 v[22:23], v[22:23], v[34:35]
	v_and_b32_e32 v41, 0xffff0000, v59
	v_cvt_pk_bf16_f32 v8, v22, v23
	v_pk_mul_f32 v[22:23], v[44:45], v[66:67] op_sel_hi:[1,0]
	v_pk_mul_f32 v[44:45], v[48:49], v[66:67] op_sel_hi:[1,0]
	v_pk_fma_f32 v[22:23], v[38:39], v[22:23], v[42:43]
	v_pk_mul_f32 v[42:43], v[60:61], v[66:67] op_sel_hi:[1,0]
	v_pk_fma_f32 v[22:23], v[26:27], v[46:47], v[22:23] op_sel_hi:[0,1,1]
	v_pk_mul_f32 v[22:23], v[24:25], v[22:23]
	v_lshlrev_b32_e32 v38, 16, v58
	v_cvt_pk_bf16_f32 v22, v22, v23
	v_cndmask_b32_e64 v23, v22, 0, vcc
	v_cndmask_b32_e64 v22, v8, 0, vcc
	v_lshl_add_u64 v[198:199], v[204:205], 0, v[32:33]
	v_mov_b32_e32 v200, v22
	v_mov_b32_e32 v201, v23
	s_nop 0
	v_and_b32_e32 v39, 0xffff0000, v58
	v_add_u32_e32 v8, v67, v85
	v_lshl_add_u64 v[36:37], v[8:9], 1, s[8:9]
	s_nop 1
	v_mov_b32_e32 v22, v174
	v_mov_b32_e32 v23, v175
	v_mov_b32_e32 v24, v176
	v_mov_b32_e32 v25, v177
	v_mov_b32_e32 v32, v186
	v_mov_b32_e32 v33, v187
	v_mov_b32_e32 v34, v188
	v_mov_b32_e32 v35, v189
	v_pk_fma_f32 v[22:23], v[42:43], v[22:23], v[32:33]
	v_pk_fma_f32 v[24:25], v[44:45], v[24:25], v[34:35]
	v_pk_fma_f32 v[22:23], v[26:27], v[38:39], v[22:23] op_sel_hi:[0,1,1]
	v_pk_fma_f32 v[24:25], v[26:27], v[40:41], v[24:25] op_sel_hi:[0,1,1]
	v_pk_mul_f32 v[18:19], v[18:19], v[22:23]
	v_pk_mul_f32 v[20:21], v[20:21], v[24:25]
	v_cvt_pk_bf16_f32 v8, v18, v19
	v_cvt_pk_bf16_f32 v18, v20, v21
	v_cndmask_b32_e64 v19, v18, 0, vcc
	v_cndmask_b32_e64 v18, v8, 0, vcc
	v_mov_b32_e32 v202, v18
	v_mov_b32_e32 v203, v19
	s_nop 1
	v_permlane16_swap_b32 v200, v202
	v_permlane16_swap_b32 v201, v203
	s_nop 1
	global_store_dwordx4 v[198:199], v[200:203], off
	s_nop 0
	v_pk_mul_f32 v[36:37], v[62:63], v[66:67] op_sel_hi:[1,0]
	v_pk_mul_f32 v[38:39], v[64:65], v[66:67] op_sel_hi:[1,0]
	v_lshlrev_b32_e32 v34, 16, v30
	v_and_b32_e32 v35, 0xffff0000, v30
	v_lshlrev_b32_e32 v30, 16, v31
	v_and_b32_e32 v31, 0xffff0000, v31
	v_add_u32_e32 v8, v67, v131
	v_lshl_add_u64 v[32:33], v[8:9], 1, s[8:9]
	s_nop 1
	v_mov_b32_e32 v18, v178
	v_mov_b32_e32 v19, v179
	v_mov_b32_e32 v20, v180
	v_mov_b32_e32 v21, v181
	v_mov_b32_e32 v22, v190
	v_mov_b32_e32 v23, v191
	v_mov_b32_e32 v24, v192
	v_mov_b32_e32 v25, v193
	v_pk_fma_f32 v[18:19], v[36:37], v[18:19], v[22:23]
	v_pk_fma_f32 v[20:21], v[38:39], v[20:21], v[24:25]
	v_pk_fma_f32 v[18:19], v[26:27], v[34:35], v[18:19] op_sel_hi:[0,1,1]
	v_pk_fma_f32 v[20:21], v[26:27], v[30:31], v[20:21] op_sel_hi:[0,1,1]
	v_pk_mul_f32 v[14:15], v[14:15], v[18:19]
	v_pk_mul_f32 v[16:17], v[16:17], v[20:21]
	v_cvt_pk_bf16_f32 v8, v14, v15
	v_cvt_pk_bf16_f32 v14, v16, v17
	v_cndmask_b32_e64 v15, v14, 0, vcc
	v_cndmask_b32_e64 v14, v8, 0, vcc
	v_lshl_add_u64 v[198:199], v[204:205], 0, v[32:33]
	v_mov_b32_e32 v200, v14
	v_mov_b32_e32 v201, v15
	s_nop 0
	v_lshlrev_b32_e32 v22, 16, v28
	v_and_b32_e32 v23, 0xffff0000, v28
	v_lshlrev_b32_e32 v24, 16, v29
	v_and_b32_e32 v25, 0xffff0000, v29
	v_pk_mul_f32 v[28:29], v[50:51], v[66:67] op_sel_hi:[1,0]
	v_pk_mul_f32 v[30:31], v[52:53], v[66:67] op_sel_hi:[1,0]
	v_add_u32_e32 v8, v67, v132
	s_nop 1
	v_mov_b32_e32 v14, v182
	v_mov_b32_e32 v15, v183
	v_mov_b32_e32 v16, v184
	v_mov_b32_e32 v17, v185
	v_mov_b32_e32 v18, v194
	v_mov_b32_e32 v19, v195
	v_mov_b32_e32 v20, v196
	v_mov_b32_e32 v21, v197
	v_pk_fma_f32 v[14:15], v[28:29], v[14:15], v[18:19]
	v_pk_fma_f32 v[16:17], v[30:31], v[16:17], v[20:21]
	v_pk_fma_f32 v[14:15], v[26:27], v[22:23], v[14:15] op_sel_hi:[0,1,1]
	v_pk_fma_f32 v[16:17], v[26:27], v[24:25], v[16:17] op_sel_hi:[0,1,1]
	v_pk_mul_f32 v[10:11], v[10:11], v[14:15]
	v_pk_mul_f32 v[12:13], v[12:13], v[16:17]
	v_cvt_pk_bf16_f32 v10, v10, v11
	v_cvt_pk_bf16_f32 v11, v12, v13
	v_cndmask_b32_e64 v11, v11, 0, vcc
	v_cndmask_b32_e64 v10, v10, 0, vcc
	v_lshl_add_u64 v[12:13], v[8:9], 1, s[8:9]
	v_mov_b32_e32 v202, v10
	v_mov_b32_e32 v203, v11
	s_nop 1
	v_permlane16_swap_b32 v200, v202
	v_permlane16_swap_b32 v201, v203
	s_nop 1
	global_store_dwordx4 v[198:199], v[200:203], off
	s_add_i32 s4, s4, 1
	s_addk_i32 s2, 0x200
	s_mov_b64 s[0:1], 0

; __device__ __forceinline__ float softplusf_(float x) { return x > 20.f ? x : __logf(1.f + __expf(x)); }
;     ...
;     GLDS(ap, 0, 0, 0)
;     asm volatile("s_waitcnt vmcnt(0)" ::: "memory");
;     __syncthreads();
;     for (int kt = 0; kt < KT; kt++) {
;       const int cur = (kt & 1) * 16384;
;       if (kt + 1 < KT) {
;         const bf16_t* apx = ap;
;         int kc = (kt + 1) * 64;
;         if (SHIFT && kc >= 1024) { apx = ap - lda; kc -= 1024; }
;         const int nxt = ((kt + 1) & 1) * 16384;
;         GLDS(apx, kc, (kt + 1) * 64, nxt)
;       }
; #pragma unroll
;       for (int kk = 0; kk < 2; kk++) {
;         bf16x8 af[4], bfr[4];
;         const int csw = (((kk * 4 + fq) ^ fsw) << 3);
; #pragma unroll
;         for (int mi = 0; mi < 4; mi++) af[mi] = *(const bf16x8*)(smem + cur + (wm * 64 + mi * 16 + fr) * 64 + csw);
; #pragma unroll
;         for (int ni = 0; ni < 4; ni++) bfr[ni] = *(const bf16x8*)(smem + cur + 8192 + (wn * 64 + ni * 16 + fr) * 64 + csw);
; #pragma unroll
;         for (int mi = 0; mi < 4; mi++)
; #pragma unroll
;           for (int ni = 0; ni < 4; ni++)
;             acc[mi][ni] = TR ? __builtin_amdgcn_mfma_f32_16x16x32_bf16(bfr[ni], af[mi], acc[mi][ni], 0, 0, 0)
;                              : __builtin_amdgcn_mfma_f32_16x16x32_bf16(af[mi], bfr[ni], acc[mi][ni], 0, 0, 0);
;       }
;     ...
;             } else if constexpr (EPI == EPI_LW) {
;               const float4 w0v = *(const float4*)(e.v0 + col);
;               uint2 o;
;               o.x = pack2(__expf(-softplusf_(-(w0v.x + a[0])) - 0.5f), __expf(-softplusf_(-(w0v.y + a[1])) - 0.5f));
;               o.y = pack2(__expf(-softplusf_(-(w0v.z + a[2])) - 0.5f), __expf(-softplusf_(-(w0v.w + a[3])) - 0.5f));
;               *(uint2*)(e.b0 + (row * (unsigned)D + col)) = o;
.LBB0_584:
	v_bfe_u32 v194, v2, 4, 1
	v_mov_b32_e32 v195, 0
	v_mul_u32_u24_e32 v194, 24, v194
	s_lshl_b32 s0, s12, 7
	v_add_u32_e32 v8, s0, v80
	s_lshl_b32 s1, s9, 7
	v_mad_i64_i32 v[10:11], s[8:9], v8, s45, v[74:75]
	v_readfirstlane_b32 s8, v81
	s_mov_b32 m0, s8
	s_mov_b64 s[8:9], 0x5000
	v_add_u32_e32 v8, 0x1000, v81
	v_lshl_add_u64 v[14:15], v[10:11], 0, s[8:9]
	v_readfirstlane_b32 s8, v8
	global_load_lds_dwordx4 v[10:11], off
	s_mov_b32 m0, s8
	s_mov_b64 s[8:9], 0xa000
	v_add_u32_e32 v8, 0x2000, v81
	global_load_lds_dwordx4 v[14:15], off
	v_lshl_add_u64 v[14:15], v[10:11], 0, s[8:9]
	v_readfirstlane_b32 s8, v8
	v_add_u32_e32 v12, s1, v80
	s_mov_b32 m0, s8
	s_mov_b64 s[8:9], 0xf000
	v_add_u32_e32 v8, 0x3000, v81
	v_ashrrev_i32_e32 v13, 31, v12
	v_lshl_add_u64 v[10:11], v[10:11], 0, s[8:9]
	v_readfirstlane_b32 s8, v8
	v_add_u32_e32 v8, 0x4000, v81
	v_lshlrev_b64 v[12:13], 7, v[12:13]
	global_load_lds_dwordx4 v[14:15], off
	s_mov_b32 m0, s8
	v_readfirstlane_b32 s8, v8
	v_lshl_add_u64 v[12:13], v[76:77], 0, v[12:13]
	global_load_lds_dwordx4 v[10:11], off
	s_mov_b32 m0, s8
	s_mov_b64 s[8:9], 0x1000
	v_add_u32_e32 v8, 0x5000, v81
	v_lshl_add_u64 v[10:11], v[12:13], 0, s[8:9]
	v_readfirstlane_b32 s8, v8
	global_load_lds_dwordx4 v[12:13], off
	s_mov_b32 m0, s8
	s_mov_b64 s[8:9], 0x2000
	v_add_u32_e32 v8, 0x6000, v81
	global_load_lds_dwordx4 v[10:11], off
	v_lshl_add_u64 v[10:11], v[12:13], 0, s[8:9]
	v_readfirstlane_b32 s8, v8
	s_mov_b32 m0, s8
	s_mov_b64 s[8:9], 0x3000
	v_add_u32_e32 v8, 0x7000, v81
	global_load_lds_dwordx4 v[10:11], off
	v_lshl_add_u64 v[10:11], v[12:13], 0, s[8:9]
	v_readfirstlane_b32 s8, v8
	s_mov_b32 m0, s8
	v_or_b32_e32 v8, s1, v82
	v_lshl_add_u64 v[78:79], v[8:9], 2, s[78:79]
	global_load_dwordx4 v[166:169], v[78:79], off
	global_load_dwordx4 v[170:173], v[78:79], off offset:64
	global_load_dwordx4 v[174:177], v[78:79], off offset:128
	global_load_dwordx4 v[178:181], v[78:79], off offset:192
	global_load_lds_dwordx4 v[10:11], off
	s_waitcnt vmcnt(0)
	s_waitcnt vmcnt(0) lgkmcnt(0)
	s_barrier
	ds_read_b128 v[10:13], v84
	ds_read_b128 v[14:17], v84 offset:2048
	ds_read_b128 v[18:21], v84 offset:4096
	ds_read_b128 v[22:25], v84 offset:6144
	ds_read_b128 v[26:29], v85 offset:16384
	ds_read_b128 v[30:33], v85 offset:18432
	ds_read_b128 v[34:37], v85 offset:20480
	ds_read_b128 v[38:41], v85 offset:22528
	s_waitcnt lgkmcnt(3)
	v_mfma_f32_16x16x32_bf16 v[42:45], v[26:29], v[10:13], 0
	v_lshl_add_u64 v[78:79], v[8:9], 2, s[78:79]
	s_mov_b32 s14, 0x800000
	s_mov_b32 s16, 0x3f317217
	s_waitcnt lgkmcnt(2)
	v_mfma_f32_16x16x32_bf16 v[46:49], v[30:33], v[10:13], 0
	s_mov_b32 s17, 0x7f800000
	s_mov_b32 s15, 0xc1a00000
	v_readlane_b32 s12, v247, 25
	s_waitcnt lgkmcnt(1)
	v_mfma_f32_16x16x32_bf16 v[50:53], v[34:37], v[10:13], 0
	v_readlane_b32 s13, v247, 26
	v_mfma_f32_16x16x32_bf16 v[54:57], v[26:29], v[14:17], 0
	v_mfma_f32_16x16x32_bf16 v[88:91], v[30:33], v[14:17], 0
	v_mfma_f32_16x16x32_bf16 v[92:95], v[34:37], v[14:17], 0
	v_mfma_f32_16x16x32_bf16 v[96:99], v[26:29], v[18:21], 0
	v_mfma_f32_16x16x32_bf16 v[108:111], v[26:29], v[22:25], 0
	v_mfma_f32_16x16x32_bf16 v[112:115], v[30:33], v[22:25], 0
	v_mfma_f32_16x16x32_bf16 v[116:119], v[34:37], v[22:25], 0
	s_waitcnt lgkmcnt(0)
	v_mfma_f32_16x16x32_bf16 v[120:123], v[38:41], v[22:25], 0
	ds_read_b128 v[22:25], v86
	ds_read_b128 v[26:29], v86 offset:2048
	ds_read_b128 v[124:127], v86 offset:4096
	ds_read_b128 v[128:131], v86 offset:6144
	ds_read_b128 v[132:135], v87 offset:16384
	ds_read_b128 v[136:139], v87 offset:18432
	ds_read_b128 v[140:143], v87 offset:20480
	ds_read_b128 v[144:147], v87 offset:22528
	s_waitcnt vmcnt(0)
	s_waitcnt lgkmcnt(0)
	v_mfma_f32_16x16x32_bf16 v[66:69], v[136:139], v[22:25], v[46:49]
	s_barrier
	v_mfma_f32_16x16x32_bf16 v[62:65], v[140:143], v[22:25], v[50:53]
	v_mfma_f32_16x16x32_bf16 v[50:53], v[136:139], v[26:29], v[88:91]
	v_mfma_f32_16x16x32_bf16 v[46:49], v[140:143], v[26:29], v[92:95]
	s_nop 1
	v_add_lshl_u32 v88, v83, s0, 10
	v_mfma_f32_16x16x32_bf16 v[70:73], v[132:135], v[22:25], v[42:45]
	v_mfma_f32_16x16x32_bf16 v[10:13], v[38:41], v[10:13], 0
	v_mfma_f32_16x16x32_bf16 v[58:61], v[144:147], v[22:25], v[10:13]
	v_mov_b32_e32 v90, v166
	v_mov_b32_e32 v91, v167
	v_mov_b32_e32 v92, v168
	v_mov_b32_e32 v93, v169
	s_nop 4
	v_add_f32_e32 v70, v70, v90
	v_mul_f32_e32 v89, 0xbfb8aa3b, v70
	v_exp_f32_e32 v89, v89
	v_cmp_gt_f32_e32 vcc, s15, v70
	v_add_f32_e32 v71, v71, v91
	v_mfma_f32_16x16x32_bf16 v[14:17], v[38:41], v[14:17], 0
	v_add_f32_e32 v89, 1.0, v89
	v_cmp_gt_f32_e64 s[0:1], s14, v89
	v_mfma_f32_16x16x32_bf16 v[100:103], v[30:33], v[18:21], 0
	s_nop 0
	v_cndmask_b32_e64 v90, 0, 32, s[0:1]
	v_ldexp_f32 v89, v89, v90
	v_log_f32_e32 v89, v89
	v_mfma_f32_16x16x32_bf16 v[104:107], v[34:37], v[18:21], 0
	v_mul_f32_e32 v90, 0x3f317217, v89
	v_fma_f32 v90, v89, s16, -v90
	v_fmac_f32_e32 v90, 0x3377d1cf, v89
	v_fmac_f32_e32 v90, 0x3f317217, v89
	v_cmp_lt_f32_e64 s[8:9], |v89|, s17
	v_mfma_f32_16x16x32_bf16 v[18:21], v[38:41], v[18:21], 0
	s_nop 0
	v_cndmask_b32_e64 v89, v89, v90, s[8:9]
	v_cndmask_b32_e64 v90, 0, v213, s[0:1]
	v_sub_f32_e32 v89, v89, v90
	v_cndmask_b32_e64 v70, v89, -v70, vcc
	v_mul_f32_e32 v89, 0xbfb8aa3b, v71
	v_exp_f32_e32 v89, v89
	v_cmp_gt_f32_e32 vcc, s15, v71
	v_sub_f32_e32 v70, -0.5, v70
	v_mul_f32_e32 v70, 0x3fb8aa3b, v70
	v_add_f32_e32 v89, 1.0, v89
	v_cmp_gt_f32_e64 s[0:1], s14, v89
	v_exp_f32_e32 v70, v70
	v_mfma_f32_16x16x32_bf16 v[54:57], v[132:135], v[26:29], v[54:57]
	v_cndmask_b32_e64 v90, 0, 32, s[0:1]
	v_ldexp_f32 v89, v89, v90
	v_log_f32_e32 v89, v89
	v_mfma_f32_16x16x32_bf16 v[42:45], v[144:147], v[26:29], v[14:17]
; __device__ __forceinline__ float softplusf_(float x) { return x > 20.f ? x : __logf(1.f + __expf(x)); }
;     ...
;             } else if constexpr (EPI == EPI_LW) {
;               const float4 w0v = *(const float4*)(e.v0 + col);
;               uint2 o;
;               o.x = pack2(__expf(-softplusf_(-(w0v.x + a[0])) - 0.5f), __expf(-softplusf_(-(w0v.y + a[1])) - 0.5f));
;               o.y = pack2(__expf(-softplusf_(-(w0v.z + a[2])) - 0.5f), __expf(-softplusf_(-(w0v.w + a[3])) - 0.5f));
;               *(uint2*)(e.b0 + (row * (unsigned)D + col)) = o;
	v_mul_f32_e32 v90, 0x3f317217, v89
	v_fma_f32 v90, v89, s16, -v90
	v_fmac_f32_e32 v90, 0x3377d1cf, v89
	v_fmac_f32_e32 v90, 0x3f317217, v89
	v_cmp_lt_f32_e64 s[8:9], |v89|, s17
	v_mfma_f32_16x16x32_bf16 v[38:41], v[132:135], v[124:127], v[96:99]
	s_nop 0
	v_cndmask_b32_e64 v89, v89, v90, s[8:9]
	v_cndmask_b32_e64 v90, 0, v213, s[0:1]
	v_sub_f32_e32 v89, v89, v90
	v_cndmask_b32_e64 v71, v89, -v71, vcc
	v_sub_f32_e32 v71, -0.5, v71
	v_mul_f32_e32 v71, 0x3fb8aa3b, v71
	v_exp_f32_e32 v71, v71
	v_mfma_f32_16x16x32_bf16 v[34:37], v[136:139], v[124:127], v[100:103]
	v_cvt_pk_bf16_f32 v70, v70, v71
	v_add_f32_e32 v71, v72, v92
	v_mul_f32_e32 v72, 0xbfb8aa3b, v71
	v_exp_f32_e32 v72, v72
	v_cmp_gt_f32_e32 vcc, s15, v71
	v_mfma_f32_16x16x32_bf16 v[30:33], v[140:143], v[124:127], v[104:107]
	v_add_f32_e32 v72, 1.0, v72
	v_cmp_gt_f32_e64 s[0:1], s14, v72
	v_mfma_f32_16x16x32_bf16 v[26:29], v[144:147], v[124:127], v[18:21]
	s_nop 0
	v_cndmask_b32_e64 v89, 0, 32, s[0:1]
	v_ldexp_f32 v72, v72, v89
	v_log_f32_e32 v72, v72
	v_mfma_f32_16x16x32_bf16 v[22:25], v[132:135], v[128:131], v[108:111]
	v_mul_f32_e32 v89, 0x3f317217, v72
	v_fma_f32 v89, v72, s16, -v89
	v_fmac_f32_e32 v89, 0x3377d1cf, v72
	v_fmac_f32_e32 v89, 0x3f317217, v72
	v_cmp_lt_f32_e64 s[8:9], |v72|, s17
	v_mfma_f32_16x16x32_bf16 v[18:21], v[136:139], v[128:131], v[112:115]
	s_nop 0
	v_cndmask_b32_e64 v72, v72, v89, s[8:9]
	v_cndmask_b32_e64 v89, 0, v213, s[0:1]
	v_sub_f32_e32 v72, v72, v89
	v_cndmask_b32_e64 v71, v72, -v71, vcc
	v_add_f32_e32 v72, v73, v93
	v_mul_f32_e32 v73, 0xbfb8aa3b, v72
	v_exp_f32_e32 v73, v73
	v_cmp_gt_f32_e32 vcc, s15, v72
	v_sub_f32_e32 v71, -0.5, v71
	v_mul_f32_e32 v71, 0x3fb8aa3b, v71
	v_add_f32_e32 v73, 1.0, v73
	v_cmp_gt_f32_e64 s[0:1], s14, v73
	v_exp_f32_e32 v71, v71
	v_mfma_f32_16x16x32_bf16 v[14:17], v[140:143], v[128:131], v[116:119]
	v_cndmask_b32_e64 v89, 0, 32, s[0:1]
	v_ldexp_f32 v73, v73, v89
	v_log_f32_e32 v73, v73
	v_mfma_f32_16x16x32_bf16 v[10:13], v[144:147], v[128:131], v[120:123]
	v_mul_f32_e32 v89, 0x3f317217, v73
	v_fma_f32 v89, v73, s16, -v89
	v_fmac_f32_e32 v89, 0x3377d1cf, v73
	v_fmac_f32_e32 v89, 0x3f317217, v73
	v_cmp_lt_f32_e64 s[8:9], |v73|, s17
	s_nop 1
	v_cndmask_b32_e64 v73, v73, v89, s[8:9]
	v_cndmask_b32_e64 v89, 0, v213, s[0:1]
	v_sub_f32_e32 v73, v73, v89
	v_cndmask_b32_e64 v72, v73, -v72, vcc
	v_sub_f32_e32 v72, -0.5, v72
	v_mul_f32_e32 v72, 0x3fb8aa3b, v72
	v_exp_f32_e32 v72, v72
	v_mov_b32_e32 v73, v9
	v_cvt_pk_bf16_f32 v71, v71, v72
	v_add_u32_e32 v72, v88, v8
	v_lshl_add_u64 v[72:73], v[72:73], 1, s[12:13]
	v_lshl_add_u64 v[182:183], v[194:195], 0, v[72:73]
	v_mov_b32_e32 v186, v70
	v_mov_b32_e32 v187, v71
	v_or_b32_e32 v71, 16, v8
	v_mov_b32_e32 v90, v170
	v_mov_b32_e32 v91, v171
	v_mov_b32_e32 v92, v172
	v_mov_b32_e32 v93, v173
	v_add_f32_e32 v66, v66, v90
	v_mul_f32_e32 v70, 0xbfb8aa3b, v66
	v_exp_f32_e32 v70, v70
	v_cmp_gt_f32_e32 vcc, s15, v66
	v_add_f32_e32 v67, v67, v91
	v_add_f32_e32 v70, 1.0, v70
	v_cmp_gt_f32_e64 s[0:1], s14, v70
	s_nop 1
	v_cndmask_b32_e64 v72, 0, 32, s[0:1]
	v_ldexp_f32 v70, v70, v72
	v_log_f32_e32 v70, v70
	s_nop 0
	v_mul_f32_e32 v72, 0x3f317217, v70
	v_fma_f32 v72, v70, s16, -v72
	v_fmac_f32_e32 v72, 0x3377d1cf, v70
	v_fmac_f32_e32 v72, 0x3f317217, v70
	v_cmp_lt_f32_e64 s[8:9], |v70|, s17
	s_nop 1
	v_cndmask_b32_e64 v70, v70, v72, s[8:9]
	v_cndmask_b32_e64 v72, 0, v213, s[0:1]
	v_sub_f32_e32 v70, v70, v72
	v_cndmask_b32_e64 v66, v70, -v66, vcc
	v_mul_f32_e32 v70, 0xbfb8aa3b, v67
	v_exp_f32_e32 v70, v70
	v_cmp_gt_f32_e32 vcc, s15, v67
	v_sub_f32_e32 v66, -0.5, v66
	v_mul_f32_e32 v66, 0x3fb8aa3b, v66
	v_add_f32_e32 v70, 1.0, v70
	v_cmp_gt_f32_e64 s[0:1], s14, v70
	v_exp_f32_e32 v66, v66
	s_nop 0
	v_cndmask_b32_e64 v72, 0, 32, s[0:1]
	v_ldexp_f32 v70, v70, v72
	v_log_f32_e32 v70, v70
	s_nop 0
	v_mul_f32_e32 v72, 0x3f317217, v70
	v_fma_f32 v72, v70, s16, -v72
	v_fmac_f32_e32 v72, 0x3377d1cf, v70
	v_fmac_f32_e32 v72, 0x3f317217, v70
	v_cmp_lt_f32_e64 s[8:9], |v70|, s17
	s_nop 1
	v_cndmask_b32_e64 v70, v70, v72, s[8:9]
	v_cndmask_b32_e64 v72, 0, v213, s[0:1]
	v_sub_f32_e32 v70, v70, v72
	v_cndmask_b32_e64 v67, v70, -v67, vcc
	v_sub_f32_e32 v67, -0.5, v67
	v_mul_f32_e32 v67, 0x3fb8aa3b, v67
	v_exp_f32_e32 v67, v67
	s_nop 0
	v_cvt_pk_bf16_f32 v66, v66, v67
	v_add_f32_e32 v67, v68, v92
	v_mul_f32_e32 v68, 0xbfb8aa3b, v67
	v_exp_f32_e32 v68, v68
	v_cmp_gt_f32_e32 vcc, s15, v67
	v_add_f32_e32 v68, 1.0, v68
	v_cmp_gt_f32_e64 s[0:1], s14, v68
	s_nop 1
	v_cndmask_b32_e64 v70, 0, 32, s[0:1]
	v_ldexp_f32 v68, v68, v70
	v_log_f32_e32 v68, v68
	s_nop 0
	v_mul_f32_e32 v70, 0x3f317217, v68
	v_fma_f32 v70, v68, s16, -v70
	v_fmac_f32_e32 v70, 0x3377d1cf, v68
	v_fmac_f32_e32 v70, 0x3f317217, v68
	v_cmp_lt_f32_e64 s[8:9], |v68|, s17
	s_nop 1
	v_cndmask_b32_e64 v68, v68, v70, s[8:9]
	v_cndmask_b32_e64 v70, 0, v213, s[0:1]
	v_sub_f32_e32 v68, v68, v70
	v_cndmask_b32_e64 v67, v68, -v67, vcc
	v_add_f32_e32 v68, v69, v93
	v_mul_f32_e32 v69, 0xbfb8aa3b, v68
	v_exp_f32_e32 v69, v69
	v_cmp_gt_f32_e32 vcc, s15, v68
	v_sub_f32_e32 v67, -0.5, v67
	v_mul_f32_e32 v67, 0x3fb8aa3b, v67
	v_add_f32_e32 v69, 1.0, v69
	v_cmp_gt_f32_e64 s[0:1], s14, v69
	v_exp_f32_e32 v67, v67
	s_nop 0
	v_cndmask_b32_e64 v70, 0, 32, s[0:1]
	v_ldexp_f32 v69, v69, v70
	v_log_f32_e32 v69, v69
	s_nop 0
	v_mul_f32_e32 v70, 0x3f317217, v69
	v_fma_f32 v70, v69, s16, -v70
	v_fmac_f32_e32 v70, 0x3377d1cf, v69
	v_fmac_f32_e32 v70, 0x3f317217, v69
	v_cmp_lt_f32_e64 s[8:9], |v69|, s17
	s_nop 1
	v_cndmask_b32_e64 v69, v69, v70, s[8:9]
	v_cndmask_b32_e64 v70, 0, v213, s[0:1]
	v_sub_f32_e32 v69, v69, v70
	v_cndmask_b32_e64 v68, v69, -v68, vcc
	v_sub_f32_e32 v68, -0.5, v68
; __device__ __forceinline__ float softplusf_(float x) { return x > 20.f ? x : __logf(1.f + __expf(x)); }
;     ...
;             } else if constexpr (EPI == EPI_LW) {
;               const float4 w0v = *(const float4*)(e.v0 + col);
;               uint2 o;
;               o.x = pack2(__expf(-softplusf_(-(w0v.x + a[0])) - 0.5f), __expf(-softplusf_(-(w0v.y + a[1])) - 0.5f));
;               o.y = pack2(__expf(-softplusf_(-(w0v.z + a[2])) - 0.5f), __expf(-softplusf_(-(w0v.w + a[3])) - 0.5f));
;               *(uint2*)(e.b0 + (row * (unsigned)D + col)) = o;
	v_mul_f32_e32 v68, 0x3fb8aa3b, v68
	v_exp_f32_e32 v68, v68
	v_mov_b32_e32 v69, v9
	v_or_b32_e32 v70, 32, v8
	v_cvt_pk_bf16_f32 v67, v67, v68
	v_add_u32_e32 v68, v88, v71
	v_lshl_add_u64 v[68:69], v[68:69], 1, s[12:13]
	v_mov_b32_e32 v188, v66
	v_mov_b32_e32 v189, v67
	s_nop 1
	v_permlane16_swap_b32 v186, v188
	v_permlane16_swap_b32 v187, v189
	s_nop 1
	global_store_dwordx4 v[182:183], v[186:189], off
	v_mov_b32_e32 v66, v174
	v_mov_b32_e32 v67, v175
	v_mov_b32_e32 v68, v176
	v_mov_b32_e32 v69, v177
	v_add_f32_e32 v62, v62, v66
	v_mul_f32_e32 v66, 0xbfb8aa3b, v62
	v_exp_f32_e32 v66, v66
	v_cmp_gt_f32_e32 vcc, s15, v62
	v_add_f32_e32 v63, v63, v67
	v_add_f32_e32 v66, 1.0, v66
	v_cmp_gt_f32_e64 s[0:1], s14, v66
	s_nop 1
	v_cndmask_b32_e64 v72, 0, 32, s[0:1]
	v_ldexp_f32 v66, v66, v72
	v_log_f32_e32 v66, v66
	s_nop 0
	v_mul_f32_e32 v72, 0x3f317217, v66
	v_fma_f32 v72, v66, s16, -v72
	v_fmac_f32_e32 v72, 0x3377d1cf, v66
	v_fmac_f32_e32 v72, 0x3f317217, v66
	v_cmp_lt_f32_e64 s[8:9], |v66|, s17
	s_nop 1
	v_cndmask_b32_e64 v66, v66, v72, s[8:9]
	v_cndmask_b32_e64 v72, 0, v213, s[0:1]
	v_sub_f32_e32 v66, v66, v72
	v_cndmask_b32_e64 v62, v66, -v62, vcc
	v_mul_f32_e32 v66, 0xbfb8aa3b, v63
	v_exp_f32_e32 v66, v66
	v_cmp_gt_f32_e32 vcc, s15, v63
	v_sub_f32_e32 v62, -0.5, v62
	v_mul_f32_e32 v62, 0x3fb8aa3b, v62
	v_add_f32_e32 v66, 1.0, v66
	v_cmp_gt_f32_e64 s[0:1], s14, v66
	v_exp_f32_e32 v62, v62
	s_nop 0
	v_cndmask_b32_e64 v67, 0, 32, s[0:1]
	v_ldexp_f32 v66, v66, v67
	v_log_f32_e32 v66, v66
	s_nop 0
	v_mul_f32_e32 v67, 0x3f317217, v66
	v_fma_f32 v67, v66, s16, -v67
	v_fmac_f32_e32 v67, 0x3377d1cf, v66
	v_fmac_f32_e32 v67, 0x3f317217, v66
	v_cmp_lt_f32_e64 s[8:9], |v66|, s17
	s_nop 1
	v_cndmask_b32_e64 v66, v66, v67, s[8:9]
	v_cndmask_b32_e64 v67, 0, v213, s[0:1]
	v_sub_f32_e32 v66, v66, v67
	v_cndmask_b32_e64 v63, v66, -v63, vcc
	v_sub_f32_e32 v63, -0.5, v63
	v_mul_f32_e32 v63, 0x3fb8aa3b, v63
	v_exp_f32_e32 v63, v63
	s_nop 0
	v_cvt_pk_bf16_f32 v62, v62, v63
	v_add_f32_e32 v63, v64, v68
	v_mul_f32_e32 v64, 0xbfb8aa3b, v63
	v_exp_f32_e32 v64, v64
	v_cmp_gt_f32_e32 vcc, s15, v63
	v_add_f32_e32 v64, 1.0, v64
	v_cmp_gt_f32_e64 s[0:1], s14, v64
	s_nop 1
	v_cndmask_b32_e64 v66, 0, 32, s[0:1]
	v_ldexp_f32 v64, v64, v66
	v_log_f32_e32 v64, v64
	s_nop 0
	v_mul_f32_e32 v66, 0x3f317217, v64
	v_fma_f32 v66, v64, s16, -v66
	v_fmac_f32_e32 v66, 0x3377d1cf, v64
	v_fmac_f32_e32 v66, 0x3f317217, v64
	v_cmp_lt_f32_e64 s[8:9], |v64|, s17
	s_nop 1
	v_cndmask_b32_e64 v64, v64, v66, s[8:9]
	v_cndmask_b32_e64 v66, 0, v213, s[0:1]
	v_sub_f32_e32 v64, v64, v66
	v_cndmask_b32_e64 v63, v64, -v63, vcc
	v_add_f32_e32 v64, v65, v69
	v_mul_f32_e32 v65, 0xbfb8aa3b, v64
	v_exp_f32_e32 v65, v65
	v_cmp_gt_f32_e32 vcc, s15, v64
	v_sub_f32_e32 v63, -0.5, v63
	v_mul_f32_e32 v63, 0x3fb8aa3b, v63
	v_add_f32_e32 v65, 1.0, v65
	v_cmp_gt_f32_e64 s[0:1], s14, v65
	v_exp_f32_e32 v63, v63
	s_nop 0
	v_cndmask_b32_e64 v66, 0, 32, s[0:1]
	v_ldexp_f32 v65, v65, v66
	v_log_f32_e32 v65, v65
	s_nop 0
	v_mul_f32_e32 v66, 0x3f317217, v65
	v_fma_f32 v66, v65, s16, -v66
	v_fmac_f32_e32 v66, 0x3377d1cf, v65
	v_fmac_f32_e32 v66, 0x3f317217, v65
	v_cmp_lt_f32_e64 s[8:9], |v65|, s17
	s_nop 1
	v_cndmask_b32_e64 v65, v65, v66, s[8:9]
	v_cndmask_b32_e64 v66, 0, v213, s[0:1]
	v_sub_f32_e32 v65, v65, v66
	v_cndmask_b32_e64 v64, v65, -v64, vcc
	v_sub_f32_e32 v64, -0.5, v64
	v_mul_f32_e32 v64, 0x3fb8aa3b, v64
	v_exp_f32_e32 v64, v64
	v_mov_b32_e32 v65, v9
	v_or_b32_e32 v66, 48, v8
	v_cvt_pk_bf16_f32 v63, v63, v64
	v_add_u32_e32 v64, v88, v70
	v_lshl_add_u64 v[64:65], v[64:65], 1, s[12:13]
	v_lshl_add_u64 v[184:185], v[194:195], 0, v[64:65]
	v_mov_b32_e32 v190, v62
	v_mov_b32_e32 v191, v63
	v_mov_b32_e32 v62, v178
	v_mov_b32_e32 v63, v179
	v_mov_b32_e32 v64, v180
	v_mov_b32_e32 v65, v181
	v_add_f32_e32 v58, v58, v62
	v_mul_f32_e32 v62, 0xbfb8aa3b, v58
	v_exp_f32_e32 v62, v62
	v_cmp_gt_f32_e32 vcc, s15, v58
	v_add_f32_e32 v59, v59, v63
	v_add_f32_e32 v62, 1.0, v62
	v_cmp_gt_f32_e64 s[0:1], s14, v62
	s_nop 1
	v_cndmask_b32_e64 v67, 0, 32, s[0:1]
	v_ldexp_f32 v62, v62, v67
	v_log_f32_e32 v62, v62
	s_nop 0
	v_mul_f32_e32 v67, 0x3f317217, v62
	v_fma_f32 v67, v62, s16, -v67
	v_fmac_f32_e32 v67, 0x3377d1cf, v62
	v_fmac_f32_e32 v67, 0x3f317217, v62
	v_cmp_lt_f32_e64 s[8:9], |v62|, s17
	s_nop 1
	v_cndmask_b32_e64 v62, v62, v67, s[8:9]
	v_cndmask_b32_e64 v67, 0, v213, s[0:1]
	v_sub_f32_e32 v62, v62, v67
	v_cndmask_b32_e64 v58, v62, -v58, vcc
	v_mul_f32_e32 v62, 0xbfb8aa3b, v59
	v_exp_f32_e32 v62, v62
	v_cmp_gt_f32_e32 vcc, s15, v59
	v_sub_f32_e32 v58, -0.5, v58
	v_mul_f32_e32 v58, 0x3fb8aa3b, v58
	v_add_f32_e32 v62, 1.0, v62
	v_cmp_gt_f32_e64 s[0:1], s14, v62
	v_exp_f32_e32 v58, v58
	s_nop 0
	v_cndmask_b32_e64 v63, 0, 32, s[0:1]
	v_ldexp_f32 v62, v62, v63
	v_log_f32_e32 v62, v62
	s_nop 0
	v_mul_f32_e32 v63, 0x3f317217, v62
	v_fma_f32 v63, v62, s16, -v63
	v_fmac_f32_e32 v63, 0x3377d1cf, v62
	v_fmac_f32_e32 v63, 0x3f317217, v62
	v_cmp_lt_f32_e64 s[8:9], |v62|, s17
	s_nop 1
	v_cndmask_b32_e64 v62, v62, v63, s[8:9]
	v_cndmask_b32_e64 v63, 0, v213, s[0:1]
	v_sub_f32_e32 v62, v62, v63
	v_cndmask_b32_e64 v59, v62, -v59, vcc
	v_sub_f32_e32 v59, -0.5, v59
	v_mul_f32_e32 v59, 0x3fb8aa3b, v59
	v_exp_f32_e32 v59, v59
	s_nop 0
	v_cvt_pk_bf16_f32 v58, v58, v59
	v_add_f32_e32 v59, v60, v64
	v_mul_f32_e32 v60, 0xbfb8aa3b, v59
	v_exp_f32_e32 v60, v60
	v_cmp_gt_f32_e32 vcc, s15, v59
	v_add_f32_e32 v60, 1.0, v60
	v_cmp_gt_f32_e64 s[0:1], s14, v60
	s_nop 1
	v_cndmask_b32_e64 v62, 0, 32, s[0:1]
	v_ldexp_f32 v60, v60, v62
	v_log_f32_e32 v60, v60
	s_nop 0
	v_mul_f32_e32 v62, 0x3f317217, v60
	v_fma_f32 v62, v60, s16, -v62
	v_fmac_f32_e32 v62, 0x3377d1cf, v60
; __device__ __forceinline__ float softplusf_(float x) { return x > 20.f ? x : __logf(1.f + __expf(x)); }
;     ...
;             } else if constexpr (EPI == EPI_LW) {
;               const float4 w0v = *(const float4*)(e.v0 + col);
;               uint2 o;
;               o.x = pack2(__expf(-softplusf_(-(w0v.x + a[0])) - 0.5f), __expf(-softplusf_(-(w0v.y + a[1])) - 0.5f));
;               o.y = pack2(__expf(-softplusf_(-(w0v.z + a[2])) - 0.5f), __expf(-softplusf_(-(w0v.w + a[3])) - 0.5f));
;               *(uint2*)(e.b0 + (row * (unsigned)D + col)) = o;
	v_fmac_f32_e32 v62, 0x3f317217, v60
	v_cmp_lt_f32_e64 s[8:9], |v60|, s17
	s_nop 1
	v_cndmask_b32_e64 v60, v60, v62, s[8:9]
	v_cndmask_b32_e64 v62, 0, v213, s[0:1]
	v_sub_f32_e32 v60, v60, v62
	v_cndmask_b32_e64 v59, v60, -v59, vcc
	v_add_f32_e32 v60, v61, v65
	v_mul_f32_e32 v61, 0xbfb8aa3b, v60
	v_exp_f32_e32 v61, v61
	v_cmp_gt_f32_e32 vcc, s15, v60
	v_sub_f32_e32 v59, -0.5, v59
	v_mul_f32_e32 v59, 0x3fb8aa3b, v59
	v_add_f32_e32 v61, 1.0, v61
	v_cmp_gt_f32_e64 s[0:1], s14, v61
	v_exp_f32_e32 v59, v59
	s_nop 0
	v_cndmask_b32_e64 v62, 0, 32, s[0:1]
	v_ldexp_f32 v61, v61, v62
	v_log_f32_e32 v61, v61
	s_nop 0
	v_mul_f32_e32 v62, 0x3f317217, v61
	v_fma_f32 v62, v61, s16, -v62
	v_fmac_f32_e32 v62, 0x3377d1cf, v61
	v_fmac_f32_e32 v62, 0x3f317217, v61
	v_cmp_lt_f32_e64 s[8:9], |v61|, s17
	s_nop 1
	v_cndmask_b32_e64 v61, v61, v62, s[8:9]
	v_cndmask_b32_e64 v62, 0, v213, s[0:1]
	v_sub_f32_e32 v61, v61, v62
	v_cndmask_b32_e64 v60, v61, -v60, vcc
	v_sub_f32_e32 v60, -0.5, v60
	v_mul_f32_e32 v60, 0x3fb8aa3b, v60
	v_exp_f32_e32 v60, v60
	v_mov_b32_e32 v61, v9
	v_cvt_pk_bf16_f32 v59, v59, v60
	v_add_u32_e32 v60, v88, v66
	v_lshl_add_u64 v[60:61], v[60:61], 1, s[12:13]
	v_mov_b32_e32 v192, v58
	v_mov_b32_e32 v193, v59
	s_nop 1
	v_permlane16_swap_b32 v190, v192
	v_permlane16_swap_b32 v191, v193
	s_nop 1
	global_store_dwordx4 v[184:185], v[190:193], off
	v_or_b32_e32 v58, 0x4000, v88
	v_mov_b32_e32 v60, v166
	v_mov_b32_e32 v61, v167
	v_mov_b32_e32 v62, v168
	v_mov_b32_e32 v63, v169
	v_add_f32_e32 v54, v54, v60
	v_mul_f32_e32 v59, 0xbfb8aa3b, v54
	v_exp_f32_e32 v59, v59
	v_cmp_gt_f32_e32 vcc, s15, v54
	v_add_f32_e32 v55, v55, v61
	v_add_f32_e32 v59, 1.0, v59
	v_cmp_gt_f32_e64 s[0:1], s14, v59
	s_nop 1
	v_cndmask_b32_e64 v60, 0, 32, s[0:1]
	v_ldexp_f32 v59, v59, v60
	v_log_f32_e32 v59, v59
	s_nop 0
	v_mul_f32_e32 v60, 0x3f317217, v59
	v_fma_f32 v60, v59, s16, -v60
	v_fmac_f32_e32 v60, 0x3377d1cf, v59
	v_fmac_f32_e32 v60, 0x3f317217, v59
	v_cmp_lt_f32_e64 s[8:9], |v59|, s17
	s_nop 1
	v_cndmask_b32_e64 v59, v59, v60, s[8:9]
	v_cndmask_b32_e64 v60, 0, v213, s[0:1]
	v_sub_f32_e32 v59, v59, v60
	v_cndmask_b32_e64 v54, v59, -v54, vcc
	v_mul_f32_e32 v59, 0xbfb8aa3b, v55
	v_exp_f32_e32 v59, v59
	v_cmp_gt_f32_e32 vcc, s15, v55
	v_sub_f32_e32 v54, -0.5, v54
	v_mul_f32_e32 v54, 0x3fb8aa3b, v54
	v_add_f32_e32 v59, 1.0, v59
	v_cmp_gt_f32_e64 s[0:1], s14, v59
	v_exp_f32_e32 v54, v54
	s_nop 0
	v_cndmask_b32_e64 v60, 0, 32, s[0:1]
	v_ldexp_f32 v59, v59, v60
	v_log_f32_e32 v59, v59
	s_nop 0
	v_mul_f32_e32 v60, 0x3f317217, v59
	v_fma_f32 v60, v59, s16, -v60
	v_fmac_f32_e32 v60, 0x3377d1cf, v59
	v_fmac_f32_e32 v60, 0x3f317217, v59
	v_cmp_lt_f32_e64 s[8:9], |v59|, s17
	s_nop 1
	v_cndmask_b32_e64 v59, v59, v60, s[8:9]
	v_cndmask_b32_e64 v60, 0, v213, s[0:1]
	v_sub_f32_e32 v59, v59, v60
	v_cndmask_b32_e64 v55, v59, -v55, vcc
	v_sub_f32_e32 v55, -0.5, v55
	v_mul_f32_e32 v55, 0x3fb8aa3b, v55
	v_exp_f32_e32 v55, v55
	s_nop 0
	v_cvt_pk_bf16_f32 v54, v54, v55
	v_add_f32_e32 v55, v56, v62
	v_mul_f32_e32 v56, 0xbfb8aa3b, v55
	v_exp_f32_e32 v56, v56
	v_cmp_gt_f32_e32 vcc, s15, v55
	v_add_f32_e32 v56, 1.0, v56
	v_cmp_gt_f32_e64 s[0:1], s14, v56
	s_nop 1
	v_cndmask_b32_e64 v59, 0, 32, s[0:1]
	v_ldexp_f32 v56, v56, v59
	v_log_f32_e32 v56, v56
	s_nop 0
	v_mul_f32_e32 v59, 0x3f317217, v56
	v_fma_f32 v59, v56, s16, -v59
	v_fmac_f32_e32 v59, 0x3377d1cf, v56
	v_fmac_f32_e32 v59, 0x3f317217, v56
	v_cmp_lt_f32_e64 s[8:9], |v56|, s17
	s_nop 1
	v_cndmask_b32_e64 v56, v56, v59, s[8:9]
	v_cndmask_b32_e64 v59, 0, v213, s[0:1]
	v_sub_f32_e32 v56, v56, v59
	v_cndmask_b32_e64 v55, v56, -v55, vcc
	v_add_f32_e32 v56, v57, v63
	v_mul_f32_e32 v57, 0xbfb8aa3b, v56
	v_exp_f32_e32 v57, v57
	v_cmp_gt_f32_e32 vcc, s15, v56
	v_sub_f32_e32 v55, -0.5, v55
	v_mul_f32_e32 v55, 0x3fb8aa3b, v55
	v_add_f32_e32 v57, 1.0, v57
	v_cmp_gt_f32_e64 s[0:1], s14, v57
	v_exp_f32_e32 v55, v55
	s_nop 0
	v_cndmask_b32_e64 v59, 0, 32, s[0:1]
	v_ldexp_f32 v57, v57, v59
	v_log_f32_e32 v57, v57
	s_nop 0
	v_mul_f32_e32 v59, 0x3f317217, v57
	v_fma_f32 v59, v57, s16, -v59
	v_fmac_f32_e32 v59, 0x3377d1cf, v57
	v_fmac_f32_e32 v59, 0x3f317217, v57
	v_cmp_lt_f32_e64 s[8:9], |v57|, s17
	s_nop 1
	v_cndmask_b32_e64 v57, v57, v59, s[8:9]
	v_cndmask_b32_e64 v59, 0, v213, s[0:1]
	v_sub_f32_e32 v57, v57, v59
	v_cndmask_b32_e64 v56, v57, -v56, vcc
	v_sub_f32_e32 v56, -0.5, v56
	v_mul_f32_e32 v56, 0x3fb8aa3b, v56
	v_exp_f32_e32 v56, v56
	v_mov_b32_e32 v57, v9
	v_cvt_pk_bf16_f32 v55, v55, v56
	v_add_u32_e32 v56, v58, v8
	v_lshl_add_u64 v[56:57], v[56:57], 1, s[12:13]
	v_lshl_add_u64 v[182:183], v[194:195], 0, v[56:57]
	v_mov_b32_e32 v186, v54
	v_mov_b32_e32 v187, v55
	v_mov_b32_e32 v54, v170
	v_mov_b32_e32 v55, v171
	v_mov_b32_e32 v56, v172
	v_mov_b32_e32 v57, v173
	v_add_f32_e32 v50, v50, v54
	v_mul_f32_e32 v54, 0xbfb8aa3b, v50
	v_exp_f32_e32 v54, v54
	v_cmp_gt_f32_e32 vcc, s15, v50
	v_add_f32_e32 v51, v51, v55
	v_add_f32_e32 v54, 1.0, v54
	v_cmp_gt_f32_e64 s[0:1], s14, v54
	s_nop 1
	v_cndmask_b32_e64 v59, 0, 32, s[0:1]
	v_ldexp_f32 v54, v54, v59
	v_log_f32_e32 v54, v54
	s_nop 0
	v_mul_f32_e32 v59, 0x3f317217, v54
	v_fma_f32 v59, v54, s16, -v59
	v_fmac_f32_e32 v59, 0x3377d1cf, v54
	v_fmac_f32_e32 v59, 0x3f317217, v54
	v_cmp_lt_f32_e64 s[8:9], |v54|, s17
	s_nop 1
	v_cndmask_b32_e64 v54, v54, v59, s[8:9]
	v_cndmask_b32_e64 v59, 0, v213, s[0:1]
	v_sub_f32_e32 v54, v54, v59
	v_cndmask_b32_e64 v50, v54, -v50, vcc
	v_mul_f32_e32 v54, 0xbfb8aa3b, v51
	v_exp_f32_e32 v54, v54
	v_cmp_gt_f32_e32 vcc, s15, v51
	v_sub_f32_e32 v50, -0.5, v50
	v_mul_f32_e32 v50, 0x3fb8aa3b, v50
	v_add_f32_e32 v54, 1.0, v54
	v_cmp_gt_f32_e64 s[0:1], s14, v54
	v_exp_f32_e32 v50, v50
; __device__ __forceinline__ float softplusf_(float x) { return x > 20.f ? x : __logf(1.f + __expf(x)); }
;     ...
;             } else if constexpr (EPI == EPI_LW) {
;               const float4 w0v = *(const float4*)(e.v0 + col);
;               uint2 o;
;               o.x = pack2(__expf(-softplusf_(-(w0v.x + a[0])) - 0.5f), __expf(-softplusf_(-(w0v.y + a[1])) - 0.5f));
;               o.y = pack2(__expf(-softplusf_(-(w0v.z + a[2])) - 0.5f), __expf(-softplusf_(-(w0v.w + a[3])) - 0.5f));
;               *(uint2*)(e.b0 + (row * (unsigned)D + col)) = o;
	s_nop 0
	v_cndmask_b32_e64 v55, 0, 32, s[0:1]
	v_ldexp_f32 v54, v54, v55
	v_log_f32_e32 v54, v54
	s_nop 0
	v_mul_f32_e32 v55, 0x3f317217, v54
	v_fma_f32 v55, v54, s16, -v55
	v_fmac_f32_e32 v55, 0x3377d1cf, v54
	v_fmac_f32_e32 v55, 0x3f317217, v54
	v_cmp_lt_f32_e64 s[8:9], |v54|, s17
	s_nop 1
	v_cndmask_b32_e64 v54, v54, v55, s[8:9]
	v_cndmask_b32_e64 v55, 0, v213, s[0:1]
	v_sub_f32_e32 v54, v54, v55
	v_cndmask_b32_e64 v51, v54, -v51, vcc
	v_sub_f32_e32 v51, -0.5, v51
	v_mul_f32_e32 v51, 0x3fb8aa3b, v51
	v_exp_f32_e32 v51, v51
	s_nop 0
	v_cvt_pk_bf16_f32 v50, v50, v51
	v_add_f32_e32 v51, v52, v56
	v_mul_f32_e32 v52, 0xbfb8aa3b, v51
	v_exp_f32_e32 v52, v52
	v_cmp_gt_f32_e32 vcc, s15, v51
	v_add_f32_e32 v52, 1.0, v52
	v_cmp_gt_f32_e64 s[0:1], s14, v52
	s_nop 1
	v_cndmask_b32_e64 v54, 0, 32, s[0:1]
	v_ldexp_f32 v52, v52, v54
	v_log_f32_e32 v52, v52
	s_nop 0
	v_mul_f32_e32 v54, 0x3f317217, v52
	v_fma_f32 v54, v52, s16, -v54
	v_fmac_f32_e32 v54, 0x3377d1cf, v52
	v_fmac_f32_e32 v54, 0x3f317217, v52
	v_cmp_lt_f32_e64 s[8:9], |v52|, s17
	s_nop 1
	v_cndmask_b32_e64 v52, v52, v54, s[8:9]
	v_cndmask_b32_e64 v54, 0, v213, s[0:1]
	v_sub_f32_e32 v52, v52, v54
	v_cndmask_b32_e64 v51, v52, -v51, vcc
	v_add_f32_e32 v52, v53, v57
	v_mul_f32_e32 v53, 0xbfb8aa3b, v52
	v_exp_f32_e32 v53, v53
	v_cmp_gt_f32_e32 vcc, s15, v52
	v_sub_f32_e32 v51, -0.5, v51
	v_mul_f32_e32 v51, 0x3fb8aa3b, v51
	v_add_f32_e32 v53, 1.0, v53
	v_cmp_gt_f32_e64 s[0:1], s14, v53
	v_exp_f32_e32 v51, v51
	s_nop 0
	v_cndmask_b32_e64 v54, 0, 32, s[0:1]
	v_ldexp_f32 v53, v53, v54
	v_log_f32_e32 v53, v53
	s_nop 0
	v_mul_f32_e32 v54, 0x3f317217, v53
	v_fma_f32 v54, v53, s16, -v54
	v_fmac_f32_e32 v54, 0x3377d1cf, v53
	v_fmac_f32_e32 v54, 0x3f317217, v53
	v_cmp_lt_f32_e64 s[8:9], |v53|, s17
	s_nop 1
	v_cndmask_b32_e64 v53, v53, v54, s[8:9]
	v_cndmask_b32_e64 v54, 0, v213, s[0:1]
	v_sub_f32_e32 v53, v53, v54
	v_cndmask_b32_e64 v52, v53, -v52, vcc
	v_sub_f32_e32 v52, -0.5, v52
	v_mul_f32_e32 v52, 0x3fb8aa3b, v52
	v_exp_f32_e32 v52, v52
	v_mov_b32_e32 v53, v9
	v_cvt_pk_bf16_f32 v51, v51, v52
	v_add_u32_e32 v52, v58, v71
	v_lshl_add_u64 v[52:53], v[52:53], 1, s[12:13]
	v_mov_b32_e32 v188, v50
	v_mov_b32_e32 v189, v51
	s_nop 1
	v_permlane16_swap_b32 v186, v188
	v_permlane16_swap_b32 v187, v189
	s_nop 1
	global_store_dwordx4 v[182:183], v[186:189], off
	v_mov_b32_e32 v50, v174
	v_mov_b32_e32 v51, v175
	v_mov_b32_e32 v52, v176
	v_mov_b32_e32 v53, v177
	v_add_f32_e32 v46, v46, v50
	v_mul_f32_e32 v50, 0xbfb8aa3b, v46
	v_exp_f32_e32 v50, v50
	v_cmp_gt_f32_e32 vcc, s15, v46
	v_add_f32_e32 v47, v47, v51
	v_add_f32_e32 v50, 1.0, v50
	v_cmp_gt_f32_e64 s[0:1], s14, v50
	s_nop 1
	v_cndmask_b32_e64 v54, 0, 32, s[0:1]
	v_ldexp_f32 v50, v50, v54
	v_log_f32_e32 v50, v50
	s_nop 0
	v_mul_f32_e32 v54, 0x3f317217, v50
	v_fma_f32 v54, v50, s16, -v54
	v_fmac_f32_e32 v54, 0x3377d1cf, v50
	v_fmac_f32_e32 v54, 0x3f317217, v50
	v_cmp_lt_f32_e64 s[8:9], |v50|, s17
	s_nop 1
	v_cndmask_b32_e64 v50, v50, v54, s[8:9]
	v_cndmask_b32_e64 v54, 0, v213, s[0:1]
	v_sub_f32_e32 v50, v50, v54
	v_cndmask_b32_e64 v46, v50, -v46, vcc
	v_mul_f32_e32 v50, 0xbfb8aa3b, v47
	v_exp_f32_e32 v50, v50
	v_cmp_gt_f32_e32 vcc, s15, v47
	v_sub_f32_e32 v46, -0.5, v46
	v_mul_f32_e32 v46, 0x3fb8aa3b, v46
	v_add_f32_e32 v50, 1.0, v50
	v_cmp_gt_f32_e64 s[0:1], s14, v50
	v_exp_f32_e32 v46, v46
	s_nop 0
	v_cndmask_b32_e64 v51, 0, 32, s[0:1]
	v_ldexp_f32 v50, v50, v51
	v_log_f32_e32 v50, v50
	s_nop 0
	v_mul_f32_e32 v51, 0x3f317217, v50
	v_fma_f32 v51, v50, s16, -v51
	v_fmac_f32_e32 v51, 0x3377d1cf, v50
	v_fmac_f32_e32 v51, 0x3f317217, v50
	v_cmp_lt_f32_e64 s[8:9], |v50|, s17
	s_nop 1
	v_cndmask_b32_e64 v50, v50, v51, s[8:9]
	v_cndmask_b32_e64 v51, 0, v213, s[0:1]
	v_sub_f32_e32 v50, v50, v51
	v_cndmask_b32_e64 v47, v50, -v47, vcc
	v_sub_f32_e32 v47, -0.5, v47
	v_mul_f32_e32 v47, 0x3fb8aa3b, v47
	v_exp_f32_e32 v47, v47
	s_nop 0
	v_cvt_pk_bf16_f32 v46, v46, v47
	v_add_f32_e32 v47, v48, v52
	v_mul_f32_e32 v48, 0xbfb8aa3b, v47
	v_exp_f32_e32 v48, v48
	v_cmp_gt_f32_e32 vcc, s15, v47
	v_add_f32_e32 v48, 1.0, v48
	v_cmp_gt_f32_e64 s[0:1], s14, v48
	s_nop 1
	v_cndmask_b32_e64 v50, 0, 32, s[0:1]
	v_ldexp_f32 v48, v48, v50
	v_log_f32_e32 v48, v48
	s_nop 0
	v_mul_f32_e32 v50, 0x3f317217, v48
	v_fma_f32 v50, v48, s16, -v50
	v_fmac_f32_e32 v50, 0x3377d1cf, v48
	v_fmac_f32_e32 v50, 0x3f317217, v48
	v_cmp_lt_f32_e64 s[8:9], |v48|, s17
	s_nop 1
	v_cndmask_b32_e64 v48, v48, v50, s[8:9]
	v_cndmask_b32_e64 v50, 0, v213, s[0:1]
	v_sub_f32_e32 v48, v48, v50
	v_cndmask_b32_e64 v47, v48, -v47, vcc
	v_add_f32_e32 v48, v49, v53
	v_mul_f32_e32 v49, 0xbfb8aa3b, v48
	v_exp_f32_e32 v49, v49
	v_cmp_gt_f32_e32 vcc, s15, v48
	v_sub_f32_e32 v47, -0.5, v47
	v_mul_f32_e32 v47, 0x3fb8aa3b, v47
	v_add_f32_e32 v49, 1.0, v49
	v_cmp_gt_f32_e64 s[0:1], s14, v49
	v_exp_f32_e32 v47, v47
	s_nop 0
	v_cndmask_b32_e64 v50, 0, 32, s[0:1]
	v_ldexp_f32 v49, v49, v50
	v_log_f32_e32 v49, v49
	s_nop 0
	v_mul_f32_e32 v50, 0x3f317217, v49
	v_fma_f32 v50, v49, s16, -v50
	v_fmac_f32_e32 v50, 0x3377d1cf, v49
	v_fmac_f32_e32 v50, 0x3f317217, v49
	v_cmp_lt_f32_e64 s[8:9], |v49|, s17
	s_nop 1
	v_cndmask_b32_e64 v49, v49, v50, s[8:9]
	v_cndmask_b32_e64 v50, 0, v213, s[0:1]
	v_sub_f32_e32 v49, v49, v50
	v_cndmask_b32_e64 v48, v49, -v48, vcc
	v_sub_f32_e32 v48, -0.5, v48
	v_mul_f32_e32 v48, 0x3fb8aa3b, v48
	v_exp_f32_e32 v48, v48
	v_mov_b32_e32 v49, v9
	v_cvt_pk_bf16_f32 v47, v47, v48
	v_add_u32_e32 v48, v58, v70
	v_lshl_add_u64 v[48:49], v[48:49], 1, s[12:13]
	v_lshl_add_u64 v[184:185], v[194:195], 0, v[48:49]
	v_mov_b32_e32 v190, v46
	v_mov_b32_e32 v191, v47
	v_mov_b32_e32 v46, v178
	v_mov_b32_e32 v47, v179
; __device__ __forceinline__ float softplusf_(float x) { return x > 20.f ? x : __logf(1.f + __expf(x)); }
;     ...
;             } else if constexpr (EPI == EPI_LW) {
;               const float4 w0v = *(const float4*)(e.v0 + col);
;               uint2 o;
;               o.x = pack2(__expf(-softplusf_(-(w0v.x + a[0])) - 0.5f), __expf(-softplusf_(-(w0v.y + a[1])) - 0.5f));
;               o.y = pack2(__expf(-softplusf_(-(w0v.z + a[2])) - 0.5f), __expf(-softplusf_(-(w0v.w + a[3])) - 0.5f));
;               *(uint2*)(e.b0 + (row * (unsigned)D + col)) = o;
	v_mov_b32_e32 v48, v180
	v_mov_b32_e32 v49, v181
	v_add_f32_e32 v42, v42, v46
	v_mul_f32_e32 v46, 0xbfb8aa3b, v42
	v_exp_f32_e32 v46, v46
	v_cmp_gt_f32_e32 vcc, s15, v42
	v_add_f32_e32 v43, v43, v47
	v_add_f32_e32 v46, 1.0, v46
	v_cmp_gt_f32_e64 s[0:1], s14, v46
	s_nop 1
	v_cndmask_b32_e64 v50, 0, 32, s[0:1]
	v_ldexp_f32 v46, v46, v50
	v_log_f32_e32 v46, v46
	s_nop 0
	v_mul_f32_e32 v50, 0x3f317217, v46
	v_fma_f32 v50, v46, s16, -v50
	v_fmac_f32_e32 v50, 0x3377d1cf, v46
	v_fmac_f32_e32 v50, 0x3f317217, v46
	v_cmp_lt_f32_e64 s[8:9], |v46|, s17
	s_nop 1
	v_cndmask_b32_e64 v46, v46, v50, s[8:9]
	v_cndmask_b32_e64 v50, 0, v213, s[0:1]
	v_sub_f32_e32 v46, v46, v50
	v_cndmask_b32_e64 v42, v46, -v42, vcc
	v_mul_f32_e32 v46, 0xbfb8aa3b, v43
	v_exp_f32_e32 v46, v46
	v_cmp_gt_f32_e32 vcc, s15, v43
	v_sub_f32_e32 v42, -0.5, v42
	v_mul_f32_e32 v42, 0x3fb8aa3b, v42
	v_add_f32_e32 v46, 1.0, v46
	v_cmp_gt_f32_e64 s[0:1], s14, v46
	v_exp_f32_e32 v42, v42
	s_nop 0
	v_cndmask_b32_e64 v47, 0, 32, s[0:1]
	v_ldexp_f32 v46, v46, v47
	v_log_f32_e32 v46, v46
	s_nop 0
	v_mul_f32_e32 v47, 0x3f317217, v46
	v_fma_f32 v47, v46, s16, -v47
	v_fmac_f32_e32 v47, 0x3377d1cf, v46
	v_fmac_f32_e32 v47, 0x3f317217, v46
	v_cmp_lt_f32_e64 s[8:9], |v46|, s17
	s_nop 1
	v_cndmask_b32_e64 v46, v46, v47, s[8:9]
	v_cndmask_b32_e64 v47, 0, v213, s[0:1]
	v_sub_f32_e32 v46, v46, v47
	v_cndmask_b32_e64 v43, v46, -v43, vcc
	v_sub_f32_e32 v43, -0.5, v43
	v_mul_f32_e32 v43, 0x3fb8aa3b, v43
	v_exp_f32_e32 v43, v43
	s_nop 0
	v_cvt_pk_bf16_f32 v42, v42, v43
	v_add_f32_e32 v43, v44, v48
	v_mul_f32_e32 v44, 0xbfb8aa3b, v43
	v_exp_f32_e32 v44, v44
	v_cmp_gt_f32_e32 vcc, s15, v43
	v_add_f32_e32 v44, 1.0, v44
	v_cmp_gt_f32_e64 s[0:1], s14, v44
	s_nop 1
	v_cndmask_b32_e64 v46, 0, 32, s[0:1]
	v_ldexp_f32 v44, v44, v46
	v_log_f32_e32 v44, v44
	s_nop 0
	v_mul_f32_e32 v46, 0x3f317217, v44
	v_fma_f32 v46, v44, s16, -v46
	v_fmac_f32_e32 v46, 0x3377d1cf, v44
	v_fmac_f32_e32 v46, 0x3f317217, v44
	v_cmp_lt_f32_e64 s[8:9], |v44|, s17
	s_nop 1
	v_cndmask_b32_e64 v44, v44, v46, s[8:9]
	v_cndmask_b32_e64 v46, 0, v213, s[0:1]
	v_sub_f32_e32 v44, v44, v46
	v_cndmask_b32_e64 v43, v44, -v43, vcc
	v_add_f32_e32 v44, v45, v49
	v_mul_f32_e32 v45, 0xbfb8aa3b, v44
	v_exp_f32_e32 v45, v45
	v_cmp_gt_f32_e32 vcc, s15, v44
	v_sub_f32_e32 v43, -0.5, v43
	v_mul_f32_e32 v43, 0x3fb8aa3b, v43
	v_add_f32_e32 v45, 1.0, v45
	v_cmp_gt_f32_e64 s[0:1], s14, v45
	v_exp_f32_e32 v43, v43
	s_nop 0
	v_cndmask_b32_e64 v46, 0, 32, s[0:1]
	v_ldexp_f32 v45, v45, v46
	v_log_f32_e32 v45, v45
	s_nop 0
	v_mul_f32_e32 v46, 0x3f317217, v45
	v_fma_f32 v46, v45, s16, -v46
	v_fmac_f32_e32 v46, 0x3377d1cf, v45
	v_fmac_f32_e32 v46, 0x3f317217, v45
	v_cmp_lt_f32_e64 s[8:9], |v45|, s17
	s_nop 1
	v_cndmask_b32_e64 v45, v45, v46, s[8:9]
	v_cndmask_b32_e64 v46, 0, v213, s[0:1]
	v_sub_f32_e32 v45, v45, v46
	v_cndmask_b32_e64 v44, v45, -v44, vcc
	v_sub_f32_e32 v44, -0.5, v44
	v_mul_f32_e32 v44, 0x3fb8aa3b, v44
	v_exp_f32_e32 v44, v44
	v_mov_b32_e32 v45, v9
	v_cvt_pk_bf16_f32 v43, v43, v44
	v_add_u32_e32 v44, v58, v66
	v_lshl_add_u64 v[44:45], v[44:45], 1, s[12:13]
	v_mov_b32_e32 v192, v42
	v_mov_b32_e32 v193, v43
	s_nop 1
	v_permlane16_swap_b32 v190, v192
	v_permlane16_swap_b32 v191, v193
	s_nop 1
	global_store_dwordx4 v[184:185], v[190:193], off
	v_or_b32_e32 v42, 0x8000, v88
	v_mov_b32_e32 v44, v166
	v_mov_b32_e32 v45, v167
	v_mov_b32_e32 v46, v168
	v_mov_b32_e32 v47, v169
	v_add_f32_e32 v38, v38, v44
	v_mul_f32_e32 v43, 0xbfb8aa3b, v38
	v_exp_f32_e32 v43, v43
	v_cmp_gt_f32_e32 vcc, s15, v38
	v_add_f32_e32 v39, v39, v45
	v_add_f32_e32 v43, 1.0, v43
	v_cmp_gt_f32_e64 s[0:1], s14, v43
	s_nop 1
	v_cndmask_b32_e64 v44, 0, 32, s[0:1]
	v_ldexp_f32 v43, v43, v44
	v_log_f32_e32 v43, v43
	s_nop 0
	v_mul_f32_e32 v44, 0x3f317217, v43
	v_fma_f32 v44, v43, s16, -v44
	v_fmac_f32_e32 v44, 0x3377d1cf, v43
	v_fmac_f32_e32 v44, 0x3f317217, v43
	v_cmp_lt_f32_e64 s[8:9], |v43|, s17
	s_nop 1
	v_cndmask_b32_e64 v43, v43, v44, s[8:9]
	v_cndmask_b32_e64 v44, 0, v213, s[0:1]
	v_sub_f32_e32 v43, v43, v44
	v_cndmask_b32_e64 v38, v43, -v38, vcc
	v_mul_f32_e32 v43, 0xbfb8aa3b, v39
	v_exp_f32_e32 v43, v43
	v_cmp_gt_f32_e32 vcc, s15, v39
	v_sub_f32_e32 v38, -0.5, v38
	v_mul_f32_e32 v38, 0x3fb8aa3b, v38
	v_add_f32_e32 v43, 1.0, v43
	v_cmp_gt_f32_e64 s[0:1], s14, v43
	v_exp_f32_e32 v38, v38
	s_nop 0
	v_cndmask_b32_e64 v44, 0, 32, s[0:1]
	v_ldexp_f32 v43, v43, v44
	v_log_f32_e32 v43, v43
	s_nop 0
	v_mul_f32_e32 v44, 0x3f317217, v43
	v_fma_f32 v44, v43, s16, -v44
	v_fmac_f32_e32 v44, 0x3377d1cf, v43
	v_fmac_f32_e32 v44, 0x3f317217, v43
	v_cmp_lt_f32_e64 s[8:9], |v43|, s17
	s_nop 1
	v_cndmask_b32_e64 v43, v43, v44, s[8:9]
	v_cndmask_b32_e64 v44, 0, v213, s[0:1]
	v_sub_f32_e32 v43, v43, v44
	v_cndmask_b32_e64 v39, v43, -v39, vcc
	v_sub_f32_e32 v39, -0.5, v39
	v_mul_f32_e32 v39, 0x3fb8aa3b, v39
	v_exp_f32_e32 v39, v39
	s_nop 0
	v_cvt_pk_bf16_f32 v38, v38, v39
	v_add_f32_e32 v39, v40, v46
	v_mul_f32_e32 v40, 0xbfb8aa3b, v39
	v_exp_f32_e32 v40, v40
	v_cmp_gt_f32_e32 vcc, s15, v39
	v_add_f32_e32 v40, 1.0, v40
	v_cmp_gt_f32_e64 s[0:1], s14, v40
	s_nop 1
	v_cndmask_b32_e64 v43, 0, 32, s[0:1]
	v_ldexp_f32 v40, v40, v43
	v_log_f32_e32 v40, v40
	s_nop 0
	v_mul_f32_e32 v43, 0x3f317217, v40
	v_fma_f32 v43, v40, s16, -v43
	v_fmac_f32_e32 v43, 0x3377d1cf, v40
	v_fmac_f32_e32 v43, 0x3f317217, v40
	v_cmp_lt_f32_e64 s[8:9], |v40|, s17
	s_nop 1
	v_cndmask_b32_e64 v40, v40, v43, s[8:9]
	v_cndmask_b32_e64 v43, 0, v213, s[0:1]
	v_sub_f32_e32 v40, v40, v43
	v_cndmask_b32_e64 v39, v40, -v39, vcc
	v_add_f32_e32 v40, v41, v47
	v_mul_f32_e32 v41, 0xbfb8aa3b, v40
	v_exp_f32_e32 v41, v41
	v_cmp_gt_f32_e32 vcc, s15, v40
; __device__ __forceinline__ float softplusf_(float x) { return x > 20.f ? x : __logf(1.f + __expf(x)); }
;     ...
;             } else if constexpr (EPI == EPI_LW) {
;               const float4 w0v = *(const float4*)(e.v0 + col);
;               uint2 o;
;               o.x = pack2(__expf(-softplusf_(-(w0v.x + a[0])) - 0.5f), __expf(-softplusf_(-(w0v.y + a[1])) - 0.5f));
;               o.y = pack2(__expf(-softplusf_(-(w0v.z + a[2])) - 0.5f), __expf(-softplusf_(-(w0v.w + a[3])) - 0.5f));
;               *(uint2*)(e.b0 + (row * (unsigned)D + col)) = o;
	v_sub_f32_e32 v39, -0.5, v39
	v_mul_f32_e32 v39, 0x3fb8aa3b, v39
	v_add_f32_e32 v41, 1.0, v41
	v_cmp_gt_f32_e64 s[0:1], s14, v41
	v_exp_f32_e32 v39, v39
	s_nop 0
	v_cndmask_b32_e64 v43, 0, 32, s[0:1]
	v_ldexp_f32 v41, v41, v43
	v_log_f32_e32 v41, v41
	s_nop 0
	v_mul_f32_e32 v43, 0x3f317217, v41
	v_fma_f32 v43, v41, s16, -v43
	v_fmac_f32_e32 v43, 0x3377d1cf, v41
	v_fmac_f32_e32 v43, 0x3f317217, v41
	v_cmp_lt_f32_e64 s[8:9], |v41|, s17
	s_nop 1
	v_cndmask_b32_e64 v41, v41, v43, s[8:9]
	v_cndmask_b32_e64 v43, 0, v213, s[0:1]
	v_sub_f32_e32 v41, v41, v43
	v_cndmask_b32_e64 v40, v41, -v40, vcc
	v_sub_f32_e32 v40, -0.5, v40
	v_mul_f32_e32 v40, 0x3fb8aa3b, v40
	v_exp_f32_e32 v40, v40
	v_mov_b32_e32 v41, v9
	v_cvt_pk_bf16_f32 v39, v39, v40
	v_add_u32_e32 v40, v42, v8
	v_lshl_add_u64 v[40:41], v[40:41], 1, s[12:13]
	v_lshl_add_u64 v[182:183], v[194:195], 0, v[40:41]
	v_mov_b32_e32 v186, v38
	v_mov_b32_e32 v187, v39
	v_mov_b32_e32 v38, v170
	v_mov_b32_e32 v39, v171
	v_mov_b32_e32 v40, v172
	v_mov_b32_e32 v41, v173
	v_add_f32_e32 v34, v34, v38
	v_mul_f32_e32 v38, 0xbfb8aa3b, v34
	v_exp_f32_e32 v38, v38
	v_cmp_gt_f32_e32 vcc, s15, v34
	v_add_f32_e32 v35, v35, v39
	v_add_f32_e32 v38, 1.0, v38
	v_cmp_gt_f32_e64 s[0:1], s14, v38
	s_nop 1
	v_cndmask_b32_e64 v43, 0, 32, s[0:1]
	v_ldexp_f32 v38, v38, v43
	v_log_f32_e32 v38, v38
	s_nop 0
	v_mul_f32_e32 v43, 0x3f317217, v38
	v_fma_f32 v43, v38, s16, -v43
	v_fmac_f32_e32 v43, 0x3377d1cf, v38
	v_fmac_f32_e32 v43, 0x3f317217, v38
	v_cmp_lt_f32_e64 s[8:9], |v38|, s17
	s_nop 1
	v_cndmask_b32_e64 v38, v38, v43, s[8:9]
	v_cndmask_b32_e64 v43, 0, v213, s[0:1]
	v_sub_f32_e32 v38, v38, v43
	v_cndmask_b32_e64 v34, v38, -v34, vcc
	v_mul_f32_e32 v38, 0xbfb8aa3b, v35
	v_exp_f32_e32 v38, v38
	v_cmp_gt_f32_e32 vcc, s15, v35
	v_sub_f32_e32 v34, -0.5, v34
	v_mul_f32_e32 v34, 0x3fb8aa3b, v34
	v_add_f32_e32 v38, 1.0, v38
	v_cmp_gt_f32_e64 s[0:1], s14, v38
	v_exp_f32_e32 v34, v34
	s_nop 0
	v_cndmask_b32_e64 v39, 0, 32, s[0:1]
	v_ldexp_f32 v38, v38, v39
	v_log_f32_e32 v38, v38
	s_nop 0
	v_mul_f32_e32 v39, 0x3f317217, v38
	v_fma_f32 v39, v38, s16, -v39
	v_fmac_f32_e32 v39, 0x3377d1cf, v38
	v_fmac_f32_e32 v39, 0x3f317217, v38
	v_cmp_lt_f32_e64 s[8:9], |v38|, s17
	s_nop 1
	v_cndmask_b32_e64 v38, v38, v39, s[8:9]
	v_cndmask_b32_e64 v39, 0, v213, s[0:1]
	v_sub_f32_e32 v38, v38, v39
	v_cndmask_b32_e64 v35, v38, -v35, vcc
	v_sub_f32_e32 v35, -0.5, v35
	v_mul_f32_e32 v35, 0x3fb8aa3b, v35
	v_exp_f32_e32 v35, v35
	s_nop 0
	v_cvt_pk_bf16_f32 v34, v34, v35
	v_add_f32_e32 v35, v36, v40
	v_mul_f32_e32 v36, 0xbfb8aa3b, v35
	v_exp_f32_e32 v36, v36
	v_cmp_gt_f32_e32 vcc, s15, v35
	v_add_f32_e32 v36, 1.0, v36
	v_cmp_gt_f32_e64 s[0:1], s14, v36
	s_nop 1
	v_cndmask_b32_e64 v38, 0, 32, s[0:1]
	v_ldexp_f32 v36, v36, v38
	v_log_f32_e32 v36, v36
	s_nop 0
	v_mul_f32_e32 v38, 0x3f317217, v36
	v_fma_f32 v38, v36, s16, -v38
	v_fmac_f32_e32 v38, 0x3377d1cf, v36
	v_fmac_f32_e32 v38, 0x3f317217, v36
	v_cmp_lt_f32_e64 s[8:9], |v36|, s17
	s_nop 1
	v_cndmask_b32_e64 v36, v36, v38, s[8:9]
	v_cndmask_b32_e64 v38, 0, v213, s[0:1]
	v_sub_f32_e32 v36, v36, v38
	v_cndmask_b32_e64 v35, v36, -v35, vcc
	v_add_f32_e32 v36, v37, v41
	v_mul_f32_e32 v37, 0xbfb8aa3b, v36
	v_exp_f32_e32 v37, v37
	v_cmp_gt_f32_e32 vcc, s15, v36
	v_sub_f32_e32 v35, -0.5, v35
	v_mul_f32_e32 v35, 0x3fb8aa3b, v35
	v_add_f32_e32 v37, 1.0, v37
	v_cmp_gt_f32_e64 s[0:1], s14, v37
	v_exp_f32_e32 v35, v35
	s_nop 0
	v_cndmask_b32_e64 v38, 0, 32, s[0:1]
	v_ldexp_f32 v37, v37, v38
	v_log_f32_e32 v37, v37
	s_nop 0
	v_mul_f32_e32 v38, 0x3f317217, v37
	v_fma_f32 v38, v37, s16, -v38
	v_fmac_f32_e32 v38, 0x3377d1cf, v37
	v_fmac_f32_e32 v38, 0x3f317217, v37
	v_cmp_lt_f32_e64 s[8:9], |v37|, s17
	s_nop 1
	v_cndmask_b32_e64 v37, v37, v38, s[8:9]
	v_cndmask_b32_e64 v38, 0, v213, s[0:1]
	v_sub_f32_e32 v37, v37, v38
	v_cndmask_b32_e64 v36, v37, -v36, vcc
	v_sub_f32_e32 v36, -0.5, v36
	v_mul_f32_e32 v36, 0x3fb8aa3b, v36
	v_exp_f32_e32 v36, v36
	v_mov_b32_e32 v37, v9
	v_cvt_pk_bf16_f32 v35, v35, v36
	v_add_u32_e32 v36, v42, v71
	v_lshl_add_u64 v[36:37], v[36:37], 1, s[12:13]
	v_mov_b32_e32 v188, v34
	v_mov_b32_e32 v189, v35
	s_nop 1
	v_permlane16_swap_b32 v186, v188
	v_permlane16_swap_b32 v187, v189
	s_nop 1
	global_store_dwordx4 v[182:183], v[186:189], off
	v_mov_b32_e32 v34, v174
	v_mov_b32_e32 v35, v175
	v_mov_b32_e32 v36, v176
	v_mov_b32_e32 v37, v177
	v_add_f32_e32 v30, v30, v34
	v_mul_f32_e32 v34, 0xbfb8aa3b, v30
	v_exp_f32_e32 v34, v34
	v_cmp_gt_f32_e32 vcc, s15, v30
	v_add_f32_e32 v31, v31, v35
	v_add_f32_e32 v34, 1.0, v34
	v_cmp_gt_f32_e64 s[0:1], s14, v34
	s_nop 1
	v_cndmask_b32_e64 v38, 0, 32, s[0:1]
	v_ldexp_f32 v34, v34, v38
	v_log_f32_e32 v34, v34
	s_nop 0
	v_mul_f32_e32 v38, 0x3f317217, v34
	v_fma_f32 v38, v34, s16, -v38
	v_fmac_f32_e32 v38, 0x3377d1cf, v34
	v_fmac_f32_e32 v38, 0x3f317217, v34
	v_cmp_lt_f32_e64 s[8:9], |v34|, s17
	s_nop 1
	v_cndmask_b32_e64 v34, v34, v38, s[8:9]
	v_cndmask_b32_e64 v38, 0, v213, s[0:1]
	v_sub_f32_e32 v34, v34, v38
	v_cndmask_b32_e64 v30, v34, -v30, vcc
	v_mul_f32_e32 v34, 0xbfb8aa3b, v31
	v_exp_f32_e32 v34, v34
	v_cmp_gt_f32_e32 vcc, s15, v31
	v_sub_f32_e32 v30, -0.5, v30
	v_mul_f32_e32 v30, 0x3fb8aa3b, v30
	v_add_f32_e32 v34, 1.0, v34
	v_cmp_gt_f32_e64 s[0:1], s14, v34
	v_exp_f32_e32 v30, v30
	s_nop 0
	v_cndmask_b32_e64 v35, 0, 32, s[0:1]
	v_ldexp_f32 v34, v34, v35
	v_log_f32_e32 v34, v34
	s_nop 0
	v_mul_f32_e32 v35, 0x3f317217, v34
	v_fma_f32 v35, v34, s16, -v35
	v_fmac_f32_e32 v35, 0x3377d1cf, v34
	v_fmac_f32_e32 v35, 0x3f317217, v34
	v_cmp_lt_f32_e64 s[8:9], |v34|, s17
	s_nop 1
	v_cndmask_b32_e64 v34, v34, v35, s[8:9]
	v_cndmask_b32_e64 v35, 0, v213, s[0:1]
; __device__ __forceinline__ float softplusf_(float x) { return x > 20.f ? x : __logf(1.f + __expf(x)); }
;     ...
;             } else if constexpr (EPI == EPI_LW) {
;               const float4 w0v = *(const float4*)(e.v0 + col);
;               uint2 o;
;               o.x = pack2(__expf(-softplusf_(-(w0v.x + a[0])) - 0.5f), __expf(-softplusf_(-(w0v.y + a[1])) - 0.5f));
;               o.y = pack2(__expf(-softplusf_(-(w0v.z + a[2])) - 0.5f), __expf(-softplusf_(-(w0v.w + a[3])) - 0.5f));
;               *(uint2*)(e.b0 + (row * (unsigned)D + col)) = o;
	v_sub_f32_e32 v34, v34, v35
	v_cndmask_b32_e64 v31, v34, -v31, vcc
	v_sub_f32_e32 v31, -0.5, v31
	v_mul_f32_e32 v31, 0x3fb8aa3b, v31
	v_exp_f32_e32 v31, v31
	s_nop 0
	v_cvt_pk_bf16_f32 v30, v30, v31
	v_add_f32_e32 v31, v32, v36
	v_mul_f32_e32 v32, 0xbfb8aa3b, v31
	v_exp_f32_e32 v32, v32
	v_cmp_gt_f32_e32 vcc, s15, v31
	v_add_f32_e32 v32, 1.0, v32
	v_cmp_gt_f32_e64 s[0:1], s14, v32
	s_nop 1
	v_cndmask_b32_e64 v34, 0, 32, s[0:1]
	v_ldexp_f32 v32, v32, v34
	v_log_f32_e32 v32, v32
	s_nop 0
	v_mul_f32_e32 v34, 0x3f317217, v32
	v_fma_f32 v34, v32, s16, -v34
	v_fmac_f32_e32 v34, 0x3377d1cf, v32
	v_fmac_f32_e32 v34, 0x3f317217, v32
	v_cmp_lt_f32_e64 s[8:9], |v32|, s17
	s_nop 1
	v_cndmask_b32_e64 v32, v32, v34, s[8:9]
	v_cndmask_b32_e64 v34, 0, v213, s[0:1]
	v_sub_f32_e32 v32, v32, v34
	v_cndmask_b32_e64 v31, v32, -v31, vcc
	v_add_f32_e32 v32, v33, v37
	v_mul_f32_e32 v33, 0xbfb8aa3b, v32
	v_exp_f32_e32 v33, v33
	v_cmp_gt_f32_e32 vcc, s15, v32
	v_sub_f32_e32 v31, -0.5, v31
	v_mul_f32_e32 v31, 0x3fb8aa3b, v31
	v_add_f32_e32 v33, 1.0, v33
	v_cmp_gt_f32_e64 s[0:1], s14, v33
	v_exp_f32_e32 v31, v31
	s_nop 0
	v_cndmask_b32_e64 v34, 0, 32, s[0:1]
	v_ldexp_f32 v33, v33, v34
	v_log_f32_e32 v33, v33
	s_nop 0
	v_mul_f32_e32 v34, 0x3f317217, v33
	v_fma_f32 v34, v33, s16, -v34
	v_fmac_f32_e32 v34, 0x3377d1cf, v33
	v_fmac_f32_e32 v34, 0x3f317217, v33
	v_cmp_lt_f32_e64 s[8:9], |v33|, s17
	s_nop 1
	v_cndmask_b32_e64 v33, v33, v34, s[8:9]
	v_cndmask_b32_e64 v34, 0, v213, s[0:1]
	v_sub_f32_e32 v33, v33, v34
	v_cndmask_b32_e64 v32, v33, -v32, vcc
	v_sub_f32_e32 v32, -0.5, v32
	v_mul_f32_e32 v32, 0x3fb8aa3b, v32
	v_exp_f32_e32 v32, v32
	v_mov_b32_e32 v33, v9
	v_cvt_pk_bf16_f32 v31, v31, v32
	v_add_u32_e32 v32, v42, v70
	v_lshl_add_u64 v[32:33], v[32:33], 1, s[12:13]
	v_lshl_add_u64 v[184:185], v[194:195], 0, v[32:33]
	v_mov_b32_e32 v190, v30
	v_mov_b32_e32 v191, v31
	v_mov_b32_e32 v30, v178
	v_mov_b32_e32 v31, v179
	v_mov_b32_e32 v32, v180
	v_mov_b32_e32 v33, v181
	v_add_f32_e32 v26, v26, v30
	v_mul_f32_e32 v30, 0xbfb8aa3b, v26
	v_exp_f32_e32 v30, v30
	v_cmp_gt_f32_e32 vcc, s15, v26
	v_add_f32_e32 v27, v27, v31
	v_add_f32_e32 v30, 1.0, v30
	v_cmp_gt_f32_e64 s[0:1], s14, v30
	s_nop 1
	v_cndmask_b32_e64 v34, 0, 32, s[0:1]
	v_ldexp_f32 v30, v30, v34
	v_log_f32_e32 v30, v30
	s_nop 0
	v_mul_f32_e32 v34, 0x3f317217, v30
	v_fma_f32 v34, v30, s16, -v34
	v_fmac_f32_e32 v34, 0x3377d1cf, v30
	v_fmac_f32_e32 v34, 0x3f317217, v30
	v_cmp_lt_f32_e64 s[8:9], |v30|, s17
	s_nop 1
	v_cndmask_b32_e64 v30, v30, v34, s[8:9]
	v_cndmask_b32_e64 v34, 0, v213, s[0:1]
	v_sub_f32_e32 v30, v30, v34
	v_cndmask_b32_e64 v26, v30, -v26, vcc
	v_mul_f32_e32 v30, 0xbfb8aa3b, v27
	v_exp_f32_e32 v30, v30
	v_cmp_gt_f32_e32 vcc, s15, v27
	v_sub_f32_e32 v26, -0.5, v26
	v_mul_f32_e32 v26, 0x3fb8aa3b, v26
	v_add_f32_e32 v30, 1.0, v30
	v_cmp_gt_f32_e64 s[0:1], s14, v30
	v_exp_f32_e32 v26, v26
	s_nop 0
	v_cndmask_b32_e64 v31, 0, 32, s[0:1]
	v_ldexp_f32 v30, v30, v31
	v_log_f32_e32 v30, v30
	s_nop 0
	v_mul_f32_e32 v31, 0x3f317217, v30
	v_fma_f32 v31, v30, s16, -v31
	v_fmac_f32_e32 v31, 0x3377d1cf, v30
	v_fmac_f32_e32 v31, 0x3f317217, v30
	v_cmp_lt_f32_e64 s[8:9], |v30|, s17
	s_nop 1
	v_cndmask_b32_e64 v30, v30, v31, s[8:9]
	v_cndmask_b32_e64 v31, 0, v213, s[0:1]
	v_sub_f32_e32 v30, v30, v31
	v_cndmask_b32_e64 v27, v30, -v27, vcc
	v_sub_f32_e32 v27, -0.5, v27
	v_mul_f32_e32 v27, 0x3fb8aa3b, v27
	v_exp_f32_e32 v27, v27
	s_nop 0
	v_cvt_pk_bf16_f32 v26, v26, v27
	v_add_f32_e32 v27, v28, v32
	v_mul_f32_e32 v28, 0xbfb8aa3b, v27
	v_exp_f32_e32 v28, v28
	v_cmp_gt_f32_e32 vcc, s15, v27
	v_add_f32_e32 v28, 1.0, v28
	v_cmp_gt_f32_e64 s[0:1], s14, v28
	s_nop 1
	v_cndmask_b32_e64 v30, 0, 32, s[0:1]
	v_ldexp_f32 v28, v28, v30
	v_log_f32_e32 v28, v28
	s_nop 0
	v_mul_f32_e32 v30, 0x3f317217, v28
	v_fma_f32 v30, v28, s16, -v30
	v_fmac_f32_e32 v30, 0x3377d1cf, v28
	v_fmac_f32_e32 v30, 0x3f317217, v28
	v_cmp_lt_f32_e64 s[8:9], |v28|, s17
	s_nop 1
	v_cndmask_b32_e64 v28, v28, v30, s[8:9]
	v_cndmask_b32_e64 v30, 0, v213, s[0:1]
	v_sub_f32_e32 v28, v28, v30
	v_cndmask_b32_e64 v27, v28, -v27, vcc
	v_add_f32_e32 v28, v29, v33
	v_mul_f32_e32 v29, 0xbfb8aa3b, v28
	v_exp_f32_e32 v29, v29
	v_cmp_gt_f32_e32 vcc, s15, v28
	v_sub_f32_e32 v27, -0.5, v27
	v_mul_f32_e32 v27, 0x3fb8aa3b, v27
	v_add_f32_e32 v29, 1.0, v29
	v_cmp_gt_f32_e64 s[0:1], s14, v29
	v_exp_f32_e32 v27, v27
	s_nop 0
	v_cndmask_b32_e64 v30, 0, 32, s[0:1]
	v_ldexp_f32 v29, v29, v30
	v_log_f32_e32 v29, v29
	s_nop 0
	v_mul_f32_e32 v30, 0x3f317217, v29
	v_fma_f32 v30, v29, s16, -v30
	v_fmac_f32_e32 v30, 0x3377d1cf, v29
	v_fmac_f32_e32 v30, 0x3f317217, v29
	v_cmp_lt_f32_e64 s[8:9], |v29|, s17
	s_nop 1
	v_cndmask_b32_e64 v29, v29, v30, s[8:9]
	v_cndmask_b32_e64 v30, 0, v213, s[0:1]
	v_sub_f32_e32 v29, v29, v30
	v_cndmask_b32_e64 v28, v29, -v28, vcc
	v_sub_f32_e32 v28, -0.5, v28
	v_mul_f32_e32 v28, 0x3fb8aa3b, v28
	v_exp_f32_e32 v28, v28
	v_mov_b32_e32 v29, v9
	v_cvt_pk_bf16_f32 v27, v27, v28
	v_add_u32_e32 v28, v42, v66
	v_lshl_add_u64 v[28:29], v[28:29], 1, s[12:13]
	v_mov_b32_e32 v192, v26
	v_mov_b32_e32 v193, v27
	s_nop 1
	v_permlane16_swap_b32 v190, v192
	v_permlane16_swap_b32 v191, v193
	s_nop 1
	global_store_dwordx4 v[184:185], v[190:193], off
	v_or_b32_e32 v30, 0xc000, v88
	v_add_u32_e32 v8, v30, v8
	v_mov_b32_e32 v26, v166
	v_mov_b32_e32 v27, v167
	v_mov_b32_e32 v28, v168
	v_mov_b32_e32 v29, v169
	v_add_f32_e32 v22, v22, v26
	v_mul_f32_e32 v26, 0xbfb8aa3b, v22
	v_exp_f32_e32 v26, v26
	v_cmp_gt_f32_e32 vcc, s15, v22
	v_add_f32_e32 v23, v23, v27
	v_add_f32_e32 v26, 1.0, v26
	v_cmp_gt_f32_e64 s[0:1], s14, v26
	s_nop 1
	v_cndmask_b32_e64 v31, 0, 32, s[0:1]
	v_ldexp_f32 v26, v26, v31
; __device__ __forceinline__ float softplusf_(float x) { return x > 20.f ? x : __logf(1.f + __expf(x)); }
;     ...
;             } else if constexpr (EPI == EPI_LW) {
;               const float4 w0v = *(const float4*)(e.v0 + col);
;               uint2 o;
;               o.x = pack2(__expf(-softplusf_(-(w0v.x + a[0])) - 0.5f), __expf(-softplusf_(-(w0v.y + a[1])) - 0.5f));
;               o.y = pack2(__expf(-softplusf_(-(w0v.z + a[2])) - 0.5f), __expf(-softplusf_(-(w0v.w + a[3])) - 0.5f));
;               *(uint2*)(e.b0 + (row * (unsigned)D + col)) = o;
	v_log_f32_e32 v26, v26
	s_nop 0
	v_mul_f32_e32 v31, 0x3f317217, v26
	v_fma_f32 v31, v26, s16, -v31
	v_fmac_f32_e32 v31, 0x3377d1cf, v26
	v_fmac_f32_e32 v31, 0x3f317217, v26
	v_cmp_lt_f32_e64 s[8:9], |v26|, s17
	s_nop 1
	v_cndmask_b32_e64 v26, v26, v31, s[8:9]
	v_cndmask_b32_e64 v31, 0, v213, s[0:1]
	v_sub_f32_e32 v26, v26, v31
	v_cndmask_b32_e64 v22, v26, -v22, vcc
	v_mul_f32_e32 v26, 0xbfb8aa3b, v23
	v_exp_f32_e32 v26, v26
	v_cmp_gt_f32_e32 vcc, s15, v23
	v_sub_f32_e32 v22, -0.5, v22
	v_mul_f32_e32 v22, 0x3fb8aa3b, v22
	v_add_f32_e32 v26, 1.0, v26
	v_cmp_gt_f32_e64 s[0:1], s14, v26
	v_exp_f32_e32 v22, v22
	s_nop 0
	v_cndmask_b32_e64 v27, 0, 32, s[0:1]
	v_ldexp_f32 v26, v26, v27
	v_log_f32_e32 v26, v26
	s_nop 0
	v_mul_f32_e32 v27, 0x3f317217, v26
	v_fma_f32 v27, v26, s16, -v27
	v_fmac_f32_e32 v27, 0x3377d1cf, v26
	v_fmac_f32_e32 v27, 0x3f317217, v26
	v_cmp_lt_f32_e64 s[8:9], |v26|, s17
	s_nop 1
	v_cndmask_b32_e64 v26, v26, v27, s[8:9]
	v_cndmask_b32_e64 v27, 0, v213, s[0:1]
	v_sub_f32_e32 v26, v26, v27
	v_cndmask_b32_e64 v23, v26, -v23, vcc
	v_sub_f32_e32 v23, -0.5, v23
	v_mul_f32_e32 v23, 0x3fb8aa3b, v23
	v_exp_f32_e32 v23, v23
	s_nop 0
	v_cvt_pk_bf16_f32 v22, v22, v23
	v_add_f32_e32 v23, v24, v28
	v_mul_f32_e32 v24, 0xbfb8aa3b, v23
	v_exp_f32_e32 v24, v24
	v_cmp_gt_f32_e32 vcc, s15, v23
	v_add_f32_e32 v24, 1.0, v24
	v_cmp_gt_f32_e64 s[0:1], s14, v24
	s_nop 1
	v_cndmask_b32_e64 v26, 0, 32, s[0:1]
	v_ldexp_f32 v24, v24, v26
	v_log_f32_e32 v24, v24
	s_nop 0
	v_mul_f32_e32 v26, 0x3f317217, v24
	v_fma_f32 v26, v24, s16, -v26
	v_fmac_f32_e32 v26, 0x3377d1cf, v24
	v_fmac_f32_e32 v26, 0x3f317217, v24
	v_cmp_lt_f32_e64 s[8:9], |v24|, s17
	s_nop 1
	v_cndmask_b32_e64 v24, v24, v26, s[8:9]
	v_cndmask_b32_e64 v26, 0, v213, s[0:1]
	v_sub_f32_e32 v24, v24, v26
	v_cndmask_b32_e64 v23, v24, -v23, vcc
	v_add_f32_e32 v24, v25, v29
	v_mul_f32_e32 v25, 0xbfb8aa3b, v24
	v_exp_f32_e32 v25, v25
	v_cmp_gt_f32_e32 vcc, s15, v24
	v_sub_f32_e32 v23, -0.5, v23
	v_mul_f32_e32 v23, 0x3fb8aa3b, v23
	v_add_f32_e32 v25, 1.0, v25
	v_cmp_gt_f32_e64 s[0:1], s14, v25
	v_exp_f32_e32 v23, v23
	s_nop 0
	v_cndmask_b32_e64 v26, 0, 32, s[0:1]
	v_ldexp_f32 v25, v25, v26
	v_log_f32_e32 v25, v25
	s_nop 0
	v_mul_f32_e32 v26, 0x3f317217, v25
	v_fma_f32 v26, v25, s16, -v26
	v_fmac_f32_e32 v26, 0x3377d1cf, v25
	v_fmac_f32_e32 v26, 0x3f317217, v25
	v_cmp_lt_f32_e64 s[8:9], |v25|, s17
	s_nop 1
	v_cndmask_b32_e64 v25, v25, v26, s[8:9]
	v_cndmask_b32_e64 v26, 0, v213, s[0:1]
	v_sub_f32_e32 v25, v25, v26
	v_cndmask_b32_e64 v24, v25, -v24, vcc
	v_sub_f32_e32 v24, -0.5, v24
	v_mul_f32_e32 v24, 0x3fb8aa3b, v24
	v_exp_f32_e32 v24, v24
	s_nop 0
	v_cvt_pk_bf16_f32 v23, v23, v24
	v_lshl_add_u64 v[24:25], v[8:9], 1, s[12:13]
	v_lshl_add_u64 v[182:183], v[194:195], 0, v[24:25]
	v_mov_b32_e32 v186, v22
	v_mov_b32_e32 v187, v23
	v_mov_b32_e32 v22, v170
	v_mov_b32_e32 v23, v171
	v_mov_b32_e32 v24, v172
	v_mov_b32_e32 v25, v173
	v_add_f32_e32 v8, v18, v22
	v_mul_f32_e32 v18, 0xbfb8aa3b, v8
	v_exp_f32_e32 v18, v18
	v_cmp_gt_f32_e32 vcc, s15, v8
	v_add_f32_e32 v18, 1.0, v18
	v_cmp_gt_f32_e64 s[0:1], s14, v18
	s_nop 1
	v_cndmask_b32_e64 v22, 0, 32, s[0:1]
	v_ldexp_f32 v18, v18, v22
	v_log_f32_e32 v18, v18
	s_nop 0
	v_mul_f32_e32 v22, 0x3f317217, v18
	v_fma_f32 v22, v18, s16, -v22
	v_fmac_f32_e32 v22, 0x3377d1cf, v18
	v_fmac_f32_e32 v22, 0x3f317217, v18
	v_cmp_lt_f32_e64 s[8:9], |v18|, s17
	s_nop 1
	v_cndmask_b32_e64 v18, v18, v22, s[8:9]
	v_cndmask_b32_e64 v22, 0, v213, s[0:1]
	v_sub_f32_e32 v18, v18, v22
	v_cndmask_b32_e64 v8, v18, -v8, vcc
	v_add_f32_e32 v18, v19, v23
	v_mul_f32_e32 v19, 0xbfb8aa3b, v18
	v_exp_f32_e32 v19, v19
	v_cmp_gt_f32_e32 vcc, s15, v18
	v_sub_f32_e32 v8, -0.5, v8
	v_mul_f32_e32 v8, 0x3fb8aa3b, v8
	v_add_f32_e32 v19, 1.0, v19
	v_cmp_gt_f32_e64 s[0:1], s14, v19
	v_exp_f32_e32 v8, v8
	s_nop 0
	v_cndmask_b32_e64 v22, 0, 32, s[0:1]
	v_ldexp_f32 v19, v19, v22
	v_log_f32_e32 v19, v19
	s_nop 0
	v_mul_f32_e32 v22, 0x3f317217, v19
	v_fma_f32 v22, v19, s16, -v22
	v_fmac_f32_e32 v22, 0x3377d1cf, v19
	v_fmac_f32_e32 v22, 0x3f317217, v19
	v_cmp_lt_f32_e64 s[8:9], |v19|, s17
	s_nop 1
	v_cndmask_b32_e64 v19, v19, v22, s[8:9]
	v_cndmask_b32_e64 v22, 0, v213, s[0:1]
	v_sub_f32_e32 v19, v19, v22
	v_cndmask_b32_e64 v18, v19, -v18, vcc
	v_sub_f32_e32 v18, -0.5, v18
	v_mul_f32_e32 v18, 0x3fb8aa3b, v18
	v_exp_f32_e32 v18, v18
	s_nop 0
	v_cvt_pk_bf16_f32 v18, v8, v18
	v_add_f32_e32 v8, v20, v24
	v_mul_f32_e32 v19, 0xbfb8aa3b, v8
	v_exp_f32_e32 v19, v19
	v_cmp_gt_f32_e32 vcc, s15, v8
	v_add_f32_e32 v19, 1.0, v19
	v_cmp_gt_f32_e64 s[0:1], s14, v19
	s_nop 1
	v_cndmask_b32_e64 v20, 0, 32, s[0:1]
	v_ldexp_f32 v19, v19, v20
	v_log_f32_e32 v19, v19
	s_nop 0
	v_mul_f32_e32 v20, 0x3f317217, v19
	v_fma_f32 v20, v19, s16, -v20
	v_fmac_f32_e32 v20, 0x3377d1cf, v19
	v_fmac_f32_e32 v20, 0x3f317217, v19
	v_cmp_lt_f32_e64 s[8:9], |v19|, s17
	s_nop 1
	v_cndmask_b32_e64 v19, v19, v20, s[8:9]
	v_cndmask_b32_e64 v20, 0, v213, s[0:1]
	v_sub_f32_e32 v19, v19, v20
	v_cndmask_b32_e64 v8, v19, -v8, vcc
	v_add_f32_e32 v19, v21, v25
	v_mul_f32_e32 v20, 0xbfb8aa3b, v19
	v_exp_f32_e32 v20, v20
	v_cmp_gt_f32_e32 vcc, s15, v19
	v_sub_f32_e32 v8, -0.5, v8
	v_mul_f32_e32 v8, 0x3fb8aa3b, v8
	v_add_f32_e32 v20, 1.0, v20
	v_cmp_gt_f32_e64 s[0:1], s14, v20
	v_exp_f32_e32 v8, v8
	s_nop 0
	v_cndmask_b32_e64 v21, 0, 32, s[0:1]
	v_ldexp_f32 v20, v20, v21
	v_log_f32_e32 v20, v20
	s_nop 0
	v_mul_f32_e32 v21, 0x3f317217, v20
	v_fma_f32 v21, v20, s16, -v21
	v_fmac_f32_e32 v21, 0x3377d1cf, v20
	v_fmac_f32_e32 v21, 0x3f317217, v20
	v_cmp_lt_f32_e64 s[8:9], |v20|, s17
	s_nop 1
	v_cndmask_b32_e64 v20, v20, v21, s[8:9]
	v_cndmask_b32_e64 v21, 0, v213, s[0:1]
; __device__ __forceinline__ float softplusf_(float x) { return x > 20.f ? x : __logf(1.f + __expf(x)); }
;     ...
;   for (int it = 0;; it++) {
;     int tile;
;     if (nb == 512) tile = ((it * 8 + (bid & 7)) << 6) + (bid >> 3); else tile = it * nb + bid;
;     tile += tbeg;
;     if (tile >= MTX * ntn || tile >= tend) break;
;     ...
;             } else if constexpr (EPI == EPI_LW) {
;               const float4 w0v = *(const float4*)(e.v0 + col);
;               uint2 o;
;               o.x = pack2(__expf(-softplusf_(-(w0v.x + a[0])) - 0.5f), __expf(-softplusf_(-(w0v.y + a[1])) - 0.5f));
;               o.y = pack2(__expf(-softplusf_(-(w0v.z + a[2])) - 0.5f), __expf(-softplusf_(-(w0v.w + a[3])) - 0.5f));
;               *(uint2*)(e.b0 + (row * (unsigned)D + col)) = o;
	v_sub_f32_e32 v20, v20, v21
	v_cndmask_b32_e64 v19, v20, -v19, vcc
	v_sub_f32_e32 v19, -0.5, v19
	v_mul_f32_e32 v19, 0x3fb8aa3b, v19
	v_exp_f32_e32 v19, v19
	s_nop 0
	v_cvt_pk_bf16_f32 v19, v8, v19
	v_add_u32_e32 v8, v30, v71
	v_lshl_add_u64 v[20:21], v[8:9], 1, s[12:13]
	v_mov_b32_e32 v188, v18
	v_mov_b32_e32 v189, v19
	s_nop 1
	v_permlane16_swap_b32 v186, v188
	v_permlane16_swap_b32 v187, v189
	s_nop 1
	global_store_dwordx4 v[182:183], v[186:189], off
	v_mov_b32_e32 v18, v174
	v_mov_b32_e32 v19, v175
	v_mov_b32_e32 v20, v176
	v_mov_b32_e32 v21, v177
	v_add_f32_e32 v8, v14, v18
	v_mul_f32_e32 v14, 0xbfb8aa3b, v8
	v_exp_f32_e32 v14, v14
	v_cmp_gt_f32_e32 vcc, s15, v8
	v_add_f32_e32 v14, 1.0, v14
	v_cmp_gt_f32_e64 s[0:1], s14, v14
	s_nop 1
	v_cndmask_b32_e64 v18, 0, 32, s[0:1]
	v_ldexp_f32 v14, v14, v18
	v_log_f32_e32 v14, v14
	s_nop 0
	v_mul_f32_e32 v18, 0x3f317217, v14
	v_fma_f32 v18, v14, s16, -v18
	v_fmac_f32_e32 v18, 0x3377d1cf, v14
	v_fmac_f32_e32 v18, 0x3f317217, v14
	v_cmp_lt_f32_e64 s[8:9], |v14|, s17
	s_nop 1
	v_cndmask_b32_e64 v14, v14, v18, s[8:9]
	v_cndmask_b32_e64 v18, 0, v213, s[0:1]
	v_sub_f32_e32 v14, v14, v18
	v_cndmask_b32_e64 v8, v14, -v8, vcc
	v_add_f32_e32 v14, v15, v19
	v_mul_f32_e32 v15, 0xbfb8aa3b, v14
	v_exp_f32_e32 v15, v15
	v_cmp_gt_f32_e32 vcc, s15, v14
	v_sub_f32_e32 v8, -0.5, v8
	v_mul_f32_e32 v8, 0x3fb8aa3b, v8
	v_add_f32_e32 v15, 1.0, v15
	v_cmp_gt_f32_e64 s[0:1], s14, v15
	v_exp_f32_e32 v8, v8
	s_nop 0
	v_cndmask_b32_e64 v18, 0, 32, s[0:1]
	v_ldexp_f32 v15, v15, v18
	v_log_f32_e32 v15, v15
	s_nop 0
	v_mul_f32_e32 v18, 0x3f317217, v15
	v_fma_f32 v18, v15, s16, -v18
	v_fmac_f32_e32 v18, 0x3377d1cf, v15
	v_fmac_f32_e32 v18, 0x3f317217, v15
	v_cmp_lt_f32_e64 s[8:9], |v15|, s17
	s_nop 1
	v_cndmask_b32_e64 v15, v15, v18, s[8:9]
	v_cndmask_b32_e64 v18, 0, v213, s[0:1]
	v_sub_f32_e32 v15, v15, v18
	v_cndmask_b32_e64 v14, v15, -v14, vcc
	v_sub_f32_e32 v14, -0.5, v14
	v_mul_f32_e32 v14, 0x3fb8aa3b, v14
	v_exp_f32_e32 v14, v14
	s_nop 0
	v_cvt_pk_bf16_f32 v14, v8, v14
	v_add_f32_e32 v8, v16, v20
	v_mul_f32_e32 v15, 0xbfb8aa3b, v8
	v_exp_f32_e32 v15, v15
	v_cmp_gt_f32_e32 vcc, s15, v8
	v_add_f32_e32 v15, 1.0, v15
	v_cmp_gt_f32_e64 s[0:1], s14, v15
	s_nop 1
	v_cndmask_b32_e64 v16, 0, 32, s[0:1]
	v_ldexp_f32 v15, v15, v16
	v_log_f32_e32 v15, v15
	s_nop 0
	v_mul_f32_e32 v16, 0x3f317217, v15
	v_fma_f32 v16, v15, s16, -v16
	v_fmac_f32_e32 v16, 0x3377d1cf, v15
	v_fmac_f32_e32 v16, 0x3f317217, v15
	v_cmp_lt_f32_e64 s[8:9], |v15|, s17
	s_nop 1
	v_cndmask_b32_e64 v15, v15, v16, s[8:9]
	v_cndmask_b32_e64 v16, 0, v213, s[0:1]
	v_sub_f32_e32 v15, v15, v16
	v_cndmask_b32_e64 v8, v15, -v8, vcc
	v_add_f32_e32 v15, v17, v21
	v_mul_f32_e32 v16, 0xbfb8aa3b, v15
	v_exp_f32_e32 v16, v16
	v_cmp_gt_f32_e32 vcc, s15, v15
	v_sub_f32_e32 v8, -0.5, v8
	v_mul_f32_e32 v8, 0x3fb8aa3b, v8
	v_add_f32_e32 v16, 1.0, v16
	v_cmp_gt_f32_e64 s[0:1], s14, v16
	v_exp_f32_e32 v8, v8
	s_nop 0
	v_cndmask_b32_e64 v17, 0, 32, s[0:1]
	v_ldexp_f32 v16, v16, v17
	v_log_f32_e32 v16, v16
	s_nop 0
	v_mul_f32_e32 v17, 0x3f317217, v16
	v_fma_f32 v17, v16, s16, -v17
	v_fmac_f32_e32 v17, 0x3377d1cf, v16
	v_fmac_f32_e32 v17, 0x3f317217, v16
	v_cmp_lt_f32_e64 s[8:9], |v16|, s17
	s_nop 1
	v_cndmask_b32_e64 v16, v16, v17, s[8:9]
	v_cndmask_b32_e64 v17, 0, v213, s[0:1]
	v_sub_f32_e32 v16, v16, v17
	v_cndmask_b32_e64 v15, v16, -v15, vcc
	v_sub_f32_e32 v15, -0.5, v15
	v_mul_f32_e32 v15, 0x3fb8aa3b, v15
	v_exp_f32_e32 v15, v15
	s_nop 0
	v_cvt_pk_bf16_f32 v15, v8, v15
	v_add_u32_e32 v8, v30, v70
	v_lshl_add_u64 v[16:17], v[8:9], 1, s[12:13]
	v_lshl_add_u64 v[184:185], v[194:195], 0, v[16:17]
	v_mov_b32_e32 v190, v14
	v_mov_b32_e32 v191, v15
	v_mov_b32_e32 v14, v178
	v_mov_b32_e32 v15, v179
	v_mov_b32_e32 v16, v180
	v_mov_b32_e32 v17, v181
	v_add_f32_e32 v8, v10, v14
	v_mul_f32_e32 v10, 0xbfb8aa3b, v8
	v_exp_f32_e32 v10, v10
	v_cmp_gt_f32_e32 vcc, s15, v8
	v_add_f32_e32 v10, 1.0, v10
	v_cmp_gt_f32_e64 s[0:1], s14, v10
	s_nop 1
	v_cndmask_b32_e64 v14, 0, 32, s[0:1]
	v_ldexp_f32 v10, v10, v14
	v_log_f32_e32 v10, v10
	s_nop 0
	v_mul_f32_e32 v14, 0x3f317217, v10
	v_fma_f32 v14, v10, s16, -v14
	v_fmac_f32_e32 v14, 0x3377d1cf, v10
	v_fmac_f32_e32 v14, 0x3f317217, v10
	v_cmp_lt_f32_e64 s[8:9], |v10|, s17
	s_nop 1
	v_cndmask_b32_e64 v10, v10, v14, s[8:9]
	v_cndmask_b32_e64 v14, 0, v213, s[0:1]
	v_sub_f32_e32 v10, v10, v14
	v_cndmask_b32_e64 v8, v10, -v8, vcc
	v_add_f32_e32 v10, v11, v15
	v_mul_f32_e32 v11, 0xbfb8aa3b, v10
	v_exp_f32_e32 v11, v11
	v_cmp_gt_f32_e32 vcc, s15, v10
	v_sub_f32_e32 v8, -0.5, v8
	v_mul_f32_e32 v8, 0x3fb8aa3b, v8
	v_add_f32_e32 v11, 1.0, v11
	v_cmp_gt_f32_e64 s[0:1], s14, v11
	v_exp_f32_e32 v8, v8
	s_nop 0
	v_cndmask_b32_e64 v14, 0, 32, s[0:1]
	v_ldexp_f32 v11, v11, v14
	v_log_f32_e32 v11, v11
	s_nop 0
	v_mul_f32_e32 v14, 0x3f317217, v11
	v_fma_f32 v14, v11, s16, -v14
	v_fmac_f32_e32 v14, 0x3377d1cf, v11
	v_fmac_f32_e32 v14, 0x3f317217, v11
	v_cmp_lt_f32_e64 s[8:9], |v11|, s17
	s_nop 1
	v_cndmask_b32_e64 v11, v11, v14, s[8:9]
	v_cndmask_b32_e64 v14, 0, v213, s[0:1]
	v_sub_f32_e32 v11, v11, v14
	v_cndmask_b32_e64 v10, v11, -v10, vcc
	v_sub_f32_e32 v10, -0.5, v10
	v_mul_f32_e32 v10, 0x3fb8aa3b, v10
	v_exp_f32_e32 v10, v10
	s_nop 0
	v_cvt_pk_bf16_f32 v10, v8, v10
	v_add_f32_e32 v8, v12, v16
	v_mul_f32_e32 v11, 0xbfb8aa3b, v8
	v_exp_f32_e32 v11, v11
	v_cmp_gt_f32_e32 vcc, s15, v8
	v_add_f32_e32 v11, 1.0, v11
	v_cmp_gt_f32_e64 s[0:1], s14, v11
	s_nop 1
	v_cndmask_b32_e64 v12, 0, 32, s[0:1]
	v_ldexp_f32 v11, v11, v12
	v_log_f32_e32 v11, v11
	s_nop 0
	v_mul_f32_e32 v12, 0x3f317217, v11
	v_fma_f32 v12, v11, s16, -v12
	v_fmac_f32_e32 v12, 0x3377d1cf, v11
	v_fmac_f32_e32 v12, 0x3f317217, v11
	v_cmp_lt_f32_e64 s[8:9], |v11|, s17
	s_nop 1
	v_cndmask_b32_e64 v11, v11, v12, s[8:9]
	v_cndmask_b32_e64 v12, 0, v213, s[0:1]
	v_sub_f32_e32 v11, v11, v12
	v_cndmask_b32_e64 v8, v11, -v8, vcc
	v_add_f32_e32 v11, v13, v17
	v_mul_f32_e32 v12, 0xbfb8aa3b, v11
	v_exp_f32_e32 v12, v12
	v_cmp_gt_f32_e32 vcc, s15, v11
	v_sub_f32_e32 v8, -0.5, v8
	v_mul_f32_e32 v8, 0x3fb8aa3b, v8
	v_add_f32_e32 v12, 1.0, v12
	v_cmp_gt_f32_e64 s[0:1], s14, v12
	v_exp_f32_e32 v8, v8
	s_nop 0
	v_cndmask_b32_e64 v13, 0, 32, s[0:1]
	v_ldexp_f32 v12, v12, v13
	v_log_f32_e32 v12, v12
	s_nop 0
	v_mul_f32_e32 v13, 0x3f317217, v12
	v_fma_f32 v13, v12, s16, -v13
	v_fmac_f32_e32 v13, 0x3377d1cf, v12
	v_fmac_f32_e32 v13, 0x3f317217, v12
	v_cmp_lt_f32_e64 s[8:9], |v12|, s17
	s_nop 1
	v_cndmask_b32_e64 v12, v12, v13, s[8:9]
	v_cndmask_b32_e64 v13, 0, v213, s[0:1]
	v_sub_f32_e32 v12, v12, v13
	v_cndmask_b32_e64 v11, v12, -v11, vcc
	v_sub_f32_e32 v11, -0.5, v11
	v_mul_f32_e32 v11, 0x3fb8aa3b, v11
	v_exp_f32_e32 v11, v11
	s_nop 0
	v_cvt_pk_bf16_f32 v11, v8, v11
	v_add_u32_e32 v8, v30, v66
	v_lshl_add_u64 v[12:13], v[8:9], 1, s[12:13]
	v_mov_b32_e32 v192, v10
	v_mov_b32_e32 v193, v11
	s_nop 1
	v_permlane16_swap_b32 v190, v192
	v_permlane16_swap_b32 v191, v193
	s_nop 1
	global_store_dwordx4 v[184:185], v[190:193], off
	s_add_i32 s4, s4, 1
	s_addk_i32 s5, 0x200
	s_mov_b64 s[0:1], 0

; __device__ __forceinline__ float sigmoidf_(float x) { return __builtin_amdgcn_rcpf(1.f + __expf(-x)); }
;     ...
;     const bf16_t* ap = A + (size_t)(m0 + lrow) * lda + lsw;
;     const bf16_t* bp = Wt + (size_t)(n0 + lrow) * K + lsw;
;     const size_t a32 = (size_t)32 * lda, b32 = (size_t)32 * K;
;     typedef __attribute__((address_space(3))) unsigned lds_u32;
;     lds_u32* sbase = (lds_u32*)(smem) + wave * 256;
;     ...
;     GLDS(ap, 0, 0, 0)
;     asm volatile("s_waitcnt vmcnt(0)" ::: "memory");
;     __syncthreads();
;     for (int kt = 0; kt < KT; kt++) {
;       const int cur = (kt & 1) * 16384;
;       if (kt + 1 < KT) {
;         const bf16_t* apx = ap;
;         int kc = (kt + 1) * 64;
;         if (SHIFT && kc >= 1024) { apx = ap - lda; kc -= 1024; }
;         const int nxt = ((kt + 1) & 1) * 16384;
;         GLDS(apx, kc, (kt + 1) * 64, nxt)
;       }
; #pragma unroll
;       for (int kk = 0; kk < 2; kk++) {
;         bf16x8 af[4], bfr[4];
;         const int csw = (((kk * 4 + fq) ^ fsw) << 3);
; #pragma unroll
;         for (int mi = 0; mi < 4; mi++) af[mi] = *(const bf16x8*)(smem + cur + (wm * 64 + mi * 16 + fr) * 64 + csw);
; #pragma unroll
;         for (int ni = 0; ni < 4; ni++) bfr[ni] = *(const bf16x8*)(smem + cur + 8192 + (wn * 64 + ni * 16 + fr) * 64 + csw);
; #pragma unroll
;         for (int mi = 0; mi < 4; mi++)
; #pragma unroll
;           for (int ni = 0; ni < 4; ni++)
;             acc[mi][ni] = TR ? __builtin_amdgcn_mfma_f32_16x16x32_bf16(bfr[ni], af[mi], acc[mi][ni], 0, 0, 0)
;                              : __builtin_amdgcn_mfma_f32_16x16x32_bf16(af[mi], bfr[ni], acc[mi][ni], 0, 0, 0);
;       }
;       asm volatile("s_waitcnt vmcnt(0)" ::: "memory");
;       __syncthreads();
;     ...
;             } else if constexpr (EPI == EPI_LA) {
;               const float4 a0v = *(const float4*)(e.v0 + col);
;               uint2 o;
;               o.x = pack2(sigmoidf_(a0v.x + a[0]), sigmoidf_(a0v.y + a[1]));
;               o.y = pack2(sigmoidf_(a0v.z + a[2]), sigmoidf_(a0v.w + a[3]));
;               *(uint2*)(e.b0 + (row * (unsigned)D + col)) = o;
.LBB0_594:
	v_bfe_u32 v194, v2, 4, 1
	v_mov_b32_e32 v195, 0
	v_mul_u32_u24_e32 v194, 24, v194
	s_lshl_b32 s0, s9, 7
	v_add_u32_e32 v8, s0, v72
	s_lshl_b32 s1, s8, 7
	v_mad_i64_i32 v[10:11], s[8:9], v8, s45, v[66:67]
	v_readfirstlane_b32 s5, v73
	v_add_u32_e32 v8, 0x1000, v73
	s_mov_b32 m0, s5
	s_mov_b64 s[8:9], 0x5000
	v_readfirstlane_b32 s5, v8
	v_add_u32_e32 v8, 0x2000, v73
	v_add_u32_e32 v12, s1, v72
	global_load_lds_dwordx4 v[10:11], off
	v_lshl_add_u64 v[14:15], v[10:11], 0, s[8:9]
	s_mov_b32 m0, s5
	s_mov_b64 s[8:9], 0xa000
	v_readfirstlane_b32 s5, v8
	v_add_u32_e32 v8, 0x3000, v73
	v_ashrrev_i32_e32 v13, 31, v12
	global_load_lds_dwordx4 v[14:15], off
	v_lshl_add_u64 v[14:15], v[10:11], 0, s[8:9]
	s_mov_b32 m0, s5
	s_mov_b64 s[8:9], 0xf000
	v_readfirstlane_b32 s5, v8
	v_add_u32_e32 v8, 0x4000, v73
	v_lshlrev_b64 v[12:13], 7, v[12:13]
	global_load_lds_dwordx4 v[14:15], off
	v_lshl_add_u64 v[10:11], v[10:11], 0, s[8:9]
	s_mov_b32 m0, s5
	v_readfirstlane_b32 s5, v8
	v_add_u32_e32 v8, 0x5000, v73
	v_lshl_add_u64 v[12:13], v[68:69], 0, v[12:13]
	global_load_lds_dwordx4 v[10:11], off
	s_mov_b32 m0, s5
	s_mov_b64 s[8:9], 0x1000
	v_readfirstlane_b32 s5, v8
	v_add_u32_e32 v8, 0x6000, v73
	global_load_lds_dwordx4 v[12:13], off
	v_lshl_add_u64 v[10:11], v[12:13], 0, s[8:9]
	s_mov_b32 m0, s5
	s_mov_b64 s[8:9], 0x2000
	v_readfirstlane_b32 s5, v8
	v_add_u32_e32 v8, 0x7000, v73
	global_load_lds_dwordx4 v[10:11], off
	v_lshl_add_u64 v[10:11], v[12:13], 0, s[8:9]
	s_mov_b32 m0, s5
	s_mov_b64 s[8:9], 0x3000
	v_readfirstlane_b32 s5, v8
	global_load_lds_dwordx4 v[10:11], off
	v_lshl_add_u64 v[10:11], v[12:13], 0, s[8:9]
	s_mov_b32 m0, s5
	v_or_b32_e32 v8, s1, v74
	v_lshl_add_u64 v[70:71], v[8:9], 2, s[84:85]
	global_load_dwordx4 v[166:169], v[70:71], off
	global_load_dwordx4 v[170:173], v[70:71], off offset:64
	global_load_dwordx4 v[174:177], v[70:71], off offset:128
	global_load_dwordx4 v[178:181], v[70:71], off offset:192
	global_load_lds_dwordx4 v[10:11], off
	s_waitcnt vmcnt(0)
	s_waitcnt vmcnt(0) lgkmcnt(0)
	s_barrier
	ds_read_b128 v[10:13], v76
	ds_read_b128 v[14:17], v76 offset:2048
	ds_read_b128 v[18:21], v76 offset:4096
	ds_read_b128 v[22:25], v76 offset:6144
	ds_read_b128 v[26:29], v77 offset:16384
	ds_read_b128 v[30:33], v77 offset:18432
	ds_read_b128 v[34:37], v77 offset:20480
	ds_read_b128 v[38:41], v77 offset:22528
	s_waitcnt lgkmcnt(3)
	v_mfma_f32_16x16x32_bf16 v[42:45], v[26:29], v[10:13], 0
	v_lshl_add_u64 v[70:71], v[8:9], 2, s[84:85]
	v_readlane_b32 s8, v247, 1
	v_readlane_b32 s9, v247, 2
	s_waitcnt lgkmcnt(2)
	v_mfma_f32_16x16x32_bf16 v[46:49], v[30:33], v[10:13], 0
	v_readlane_b32 s10, v247, 3
	v_readlane_b32 s11, v247, 4
	s_waitcnt lgkmcnt(1)
	v_mfma_f32_16x16x32_bf16 v[50:53], v[34:37], v[10:13], 0
	v_mfma_f32_16x16x32_bf16 v[54:57], v[26:29], v[14:17], 0
	v_mfma_f32_16x16x32_bf16 v[80:83], v[30:33], v[14:17], 0
	v_mfma_f32_16x16x32_bf16 v[84:87], v[34:37], v[14:17], 0
	v_mfma_f32_16x16x32_bf16 v[88:91], v[26:29], v[18:21], 0
	v_mfma_f32_16x16x32_bf16 v[100:103], v[26:29], v[22:25], 0
	v_mfma_f32_16x16x32_bf16 v[104:107], v[30:33], v[22:25], 0
	v_mfma_f32_16x16x32_bf16 v[108:111], v[34:37], v[22:25], 0
	s_waitcnt lgkmcnt(0)
	v_mfma_f32_16x16x32_bf16 v[112:115], v[38:41], v[22:25], 0
	ds_read_b128 v[22:25], v78
	ds_read_b128 v[26:29], v78 offset:2048
	ds_read_b128 v[116:119], v78 offset:4096
	ds_read_b128 v[120:123], v78 offset:6144
	ds_read_b128 v[124:127], v79 offset:16384
	ds_read_b128 v[128:131], v79 offset:18432
	ds_read_b128 v[132:135], v79 offset:20480
	ds_read_b128 v[136:139], v79 offset:22528
	s_waitcnt vmcnt(0)
	s_waitcnt lgkmcnt(0)
	v_mfma_f32_16x16x32_bf16 v[144:147], v[128:131], v[22:25], v[46:49]
	s_barrier
	v_mfma_f32_16x16x32_bf16 v[62:65], v[132:135], v[22:25], v[50:53]
	v_mfma_f32_16x16x32_bf16 v[50:53], v[128:131], v[26:29], v[80:83]
	v_mfma_f32_16x16x32_bf16 v[46:49], v[132:135], v[26:29], v[84:87]
	s_nop 1
	v_add_lshl_u32 v80, v75, s0, 10
	v_mfma_f32_16x16x32_bf16 v[140:143], v[124:127], v[22:25], v[42:45]
	v_mfma_f32_16x16x32_bf16 v[10:13], v[38:41], v[10:13], 0
	v_mfma_f32_16x16x32_bf16 v[58:61], v[136:139], v[22:25], v[10:13]
	v_mov_b32_e32 v82, v166
	v_mov_b32_e32 v83, v167
	v_mov_b32_e32 v84, v168
	v_mov_b32_e32 v85, v169
	s_nop 4
	v_add_f32_e32 v81, v140, v82
	v_add_f32_e32 v82, v141, v83
	v_mul_f32_e32 v81, 0xbfb8aa3b, v81
	v_mul_f32_e32 v82, 0xbfb8aa3b, v82
	v_exp_f32_e32 v81, v81
	v_exp_f32_e32 v82, v82
	v_add_f32_e32 v83, v143, v85
	v_mul_f32_e32 v83, 0xbfb8aa3b, v83
	v_add_f32_e32 v81, 1.0, v81
	v_add_f32_e32 v82, 1.0, v82
	v_rcp_f32_e32 v81, v81
	v_rcp_f32_e32 v82, v82
	v_exp_f32_e32 v83, v83
	v_mov_b32_e32 v85, v9
	v_mfma_f32_16x16x32_bf16 v[14:17], v[38:41], v[14:17], 0
	v_cvt_pk_bf16_f32 v82, v81, v82
	v_add_f32_e32 v81, v142, v84
	v_mul_f32_e32 v81, 0xbfb8aa3b, v81
	v_exp_f32_e32 v81, v81
	v_add_f32_e32 v83, 1.0, v83
	v_rcp_f32_e32 v83, v83
	v_add_u32_e32 v84, v80, v8
	v_add_f32_e32 v81, 1.0, v81
	v_rcp_f32_e32 v81, v81
	v_lshl_add_u64 v[84:85], v[84:85], 1, s[8:9]
	v_mfma_f32_16x16x32_bf16 v[92:95], v[30:33], v[18:21], 0
	v_cvt_pk_bf16_f32 v83, v81, v83
	v_lshl_add_u64 v[182:183], v[194:195], 0, v[84:85]
	v_mov_b32_e32 v186, v82
	v_mov_b32_e32 v187, v83
	v_or_b32_e32 v81, 16, v8
	v_mfma_f32_16x16x32_bf16 v[96:99], v[34:37], v[18:21], 0
	v_mov_b32_e32 v82, v170
	v_mov_b32_e32 v83, v171
	v_mov_b32_e32 v84, v172
	v_mov_b32_e32 v85, v173
	v_add_f32_e32 v82, v144, v82
	v_add_f32_e32 v83, v145, v83
	v_mul_f32_e32 v82, 0xbfb8aa3b, v82
	v_mul_f32_e32 v83, 0xbfb8aa3b, v83
	v_exp_f32_e32 v82, v82
	v_exp_f32_e32 v83, v83
	v_mfma_f32_16x16x32_bf16 v[18:21], v[38:41], v[18:21], 0
	v_add_f32_e32 v82, 1.0, v82
; __device__ __forceinline__ float sigmoidf_(float x) { return __builtin_amdgcn_rcpf(1.f + __expf(-x)); }
;     ...
;             } else if constexpr (EPI == EPI_LA) {
;               const float4 a0v = *(const float4*)(e.v0 + col);
;               uint2 o;
;               o.x = pack2(sigmoidf_(a0v.x + a[0]), sigmoidf_(a0v.y + a[1]));
;               o.y = pack2(sigmoidf_(a0v.z + a[2]), sigmoidf_(a0v.w + a[3]));
;               *(uint2*)(e.b0 + (row * (unsigned)D + col)) = o;
	v_add_f32_e32 v83, 1.0, v83
	v_rcp_f32_e32 v82, v82
	v_rcp_f32_e32 v83, v83
	v_mfma_f32_16x16x32_bf16 v[54:57], v[124:127], v[26:29], v[54:57]
	v_cvt_pk_bf16_f32 v82, v82, v83
	v_add_f32_e32 v83, v146, v84
	v_add_f32_e32 v84, v147, v85
	v_mul_f32_e32 v83, 0xbfb8aa3b, v83
	v_mul_f32_e32 v84, 0xbfb8aa3b, v84
	v_exp_f32_e32 v83, v83
	v_exp_f32_e32 v84, v84
	v_mov_b32_e32 v85, v9
	v_mfma_f32_16x16x32_bf16 v[42:45], v[136:139], v[26:29], v[14:17]
	v_add_f32_e32 v83, 1.0, v83
	v_add_f32_e32 v84, 1.0, v84
	v_rcp_f32_e32 v83, v83
	v_rcp_f32_e32 v84, v84
	v_mfma_f32_16x16x32_bf16 v[38:41], v[124:127], v[116:119], v[88:91]
	v_cvt_pk_bf16_f32 v83, v83, v84
	v_add_u32_e32 v84, v80, v81
	v_lshl_add_u64 v[84:85], v[84:85], 1, s[8:9]
	v_mov_b32_e32 v188, v82
	v_mov_b32_e32 v189, v83
	s_nop 1
	v_permlane16_swap_b32 v186, v188
	v_permlane16_swap_b32 v187, v189
	s_nop 1
	global_store_dwordx4 v[182:183], v[186:189], off
	v_or_b32_e32 v82, 32, v8
	v_mfma_f32_16x16x32_bf16 v[34:37], v[128:131], v[116:119], v[92:95]
	v_mov_b32_e32 v84, v174
	v_mov_b32_e32 v85, v175
	v_mov_b32_e32 v86, v176
	v_mov_b32_e32 v87, v177
	v_add_f32_e32 v62, v62, v84
	v_add_f32_e32 v63, v63, v85
	v_mul_f32_e32 v62, 0xbfb8aa3b, v62
	v_mul_f32_e32 v63, 0xbfb8aa3b, v63
	v_exp_f32_e32 v62, v62
	v_exp_f32_e32 v63, v63
	v_mfma_f32_16x16x32_bf16 v[30:33], v[132:135], v[116:119], v[96:99]
	v_add_f32_e32 v62, 1.0, v62
	v_add_f32_e32 v63, 1.0, v63
	v_rcp_f32_e32 v62, v62
	v_rcp_f32_e32 v63, v63
	v_mfma_f32_16x16x32_bf16 v[26:29], v[136:139], v[116:119], v[18:21]
	v_cvt_pk_bf16_f32 v62, v62, v63
	v_add_f32_e32 v63, v64, v86
	v_add_f32_e32 v64, v65, v87
	v_mul_f32_e32 v63, 0xbfb8aa3b, v63
	v_mul_f32_e32 v64, 0xbfb8aa3b, v64
	v_exp_f32_e32 v63, v63
	v_exp_f32_e32 v64, v64
	v_mov_b32_e32 v65, v9
	v_mfma_f32_16x16x32_bf16 v[22:25], v[124:127], v[120:123], v[100:103]
	v_add_f32_e32 v63, 1.0, v63
	v_add_f32_e32 v64, 1.0, v64
	v_rcp_f32_e32 v63, v63
	v_rcp_f32_e32 v64, v64
	v_mfma_f32_16x16x32_bf16 v[18:21], v[128:131], v[120:123], v[104:107]
	v_cvt_pk_bf16_f32 v63, v63, v64
	v_add_u32_e32 v64, v80, v82
	v_lshl_add_u64 v[64:65], v[64:65], 1, s[8:9]
	v_lshl_add_u64 v[184:185], v[194:195], 0, v[64:65]
	v_mov_b32_e32 v190, v62
	v_mov_b32_e32 v191, v63
	v_or_b32_e32 v62, 48, v8
	v_mfma_f32_16x16x32_bf16 v[14:17], v[132:135], v[120:123], v[108:111]
	v_mov_b32_e32 v84, v178
	v_mov_b32_e32 v85, v179
	v_mov_b32_e32 v86, v180
	v_mov_b32_e32 v87, v181
	v_add_f32_e32 v58, v58, v84
	v_add_f32_e32 v59, v59, v85
	v_mul_f32_e32 v58, 0xbfb8aa3b, v58
	v_mul_f32_e32 v59, 0xbfb8aa3b, v59
	v_exp_f32_e32 v58, v58
	v_exp_f32_e32 v59, v59
	v_mfma_f32_16x16x32_bf16 v[10:13], v[136:139], v[120:123], v[112:115]
	v_add_f32_e32 v58, 1.0, v58
	v_add_f32_e32 v59, 1.0, v59
	v_rcp_f32_e32 v58, v58
	v_rcp_f32_e32 v59, v59
	s_nop 0
	v_cvt_pk_bf16_f32 v58, v58, v59
	v_add_f32_e32 v59, v60, v86
	v_add_f32_e32 v60, v61, v87
	v_mul_f32_e32 v59, 0xbfb8aa3b, v59
	v_mul_f32_e32 v60, 0xbfb8aa3b, v60
	v_exp_f32_e32 v59, v59
	v_exp_f32_e32 v60, v60
	v_mov_b32_e32 v61, v9
	v_add_f32_e32 v59, 1.0, v59
	v_add_f32_e32 v60, 1.0, v60
	v_rcp_f32_e32 v59, v59
	v_rcp_f32_e32 v60, v60
	s_nop 0
	v_cvt_pk_bf16_f32 v59, v59, v60
	v_add_u32_e32 v60, v80, v62
	v_lshl_add_u64 v[60:61], v[60:61], 1, s[8:9]
	v_mov_b32_e32 v192, v58
	v_mov_b32_e32 v193, v59
	s_nop 1
	v_permlane16_swap_b32 v190, v192
	v_permlane16_swap_b32 v191, v193
	s_nop 1
	global_store_dwordx4 v[184:185], v[190:193], off
	v_or_b32_e32 v58, 0x4000, v80
	v_mov_b32_e32 v84, v166
	v_mov_b32_e32 v85, v167
	v_mov_b32_e32 v86, v168
	v_mov_b32_e32 v87, v169
	v_add_f32_e32 v54, v54, v84
	v_add_f32_e32 v55, v55, v85
	v_mul_f32_e32 v54, 0xbfb8aa3b, v54
	v_mul_f32_e32 v55, 0xbfb8aa3b, v55
	v_exp_f32_e32 v54, v54
	v_exp_f32_e32 v55, v55
	v_add_f32_e32 v54, 1.0, v54
	v_add_f32_e32 v55, 1.0, v55
	v_rcp_f32_e32 v54, v54
	v_rcp_f32_e32 v55, v55
	s_nop 0
	v_cvt_pk_bf16_f32 v54, v54, v55
	v_add_f32_e32 v55, v56, v86
	v_add_f32_e32 v56, v57, v87
	v_mul_f32_e32 v55, 0xbfb8aa3b, v55
	v_mul_f32_e32 v56, 0xbfb8aa3b, v56
	v_exp_f32_e32 v55, v55
	v_exp_f32_e32 v56, v56
	v_mov_b32_e32 v57, v9
	v_add_f32_e32 v55, 1.0, v55
	v_add_f32_e32 v56, 1.0, v56
	v_rcp_f32_e32 v55, v55
	v_rcp_f32_e32 v56, v56
	s_nop 0
	v_cvt_pk_bf16_f32 v55, v55, v56
	v_add_u32_e32 v56, v58, v8
	v_lshl_add_u64 v[56:57], v[56:57], 1, s[8:9]
	v_lshl_add_u64 v[182:183], v[194:195], 0, v[56:57]
	v_mov_b32_e32 v186, v54
	v_mov_b32_e32 v187, v55
	v_mov_b32_e32 v54, v170
	v_mov_b32_e32 v55, v171
	v_mov_b32_e32 v56, v172
	v_mov_b32_e32 v57, v173
	v_add_f32_e32 v50, v50, v54
	v_add_f32_e32 v51, v51, v55
	v_mul_f32_e32 v50, 0xbfb8aa3b, v50
	v_mul_f32_e32 v51, 0xbfb8aa3b, v51
	v_exp_f32_e32 v50, v50
	v_exp_f32_e32 v51, v51
	v_add_f32_e32 v50, 1.0, v50
	v_add_f32_e32 v51, 1.0, v51
	v_rcp_f32_e32 v50, v50
	v_rcp_f32_e32 v51, v51
	s_nop 0
	v_cvt_pk_bf16_f32 v50, v50, v51
	v_add_f32_e32 v51, v52, v56
	v_add_f32_e32 v52, v53, v57
	v_mul_f32_e32 v51, 0xbfb8aa3b, v51
	v_mul_f32_e32 v52, 0xbfb8aa3b, v52
	v_exp_f32_e32 v51, v51
	v_exp_f32_e32 v52, v52
	v_mov_b32_e32 v53, v9
	v_add_f32_e32 v51, 1.0, v51
	v_add_f32_e32 v52, 1.0, v52
	v_rcp_f32_e32 v51, v51
	v_rcp_f32_e32 v52, v52
	s_nop 0
	v_cvt_pk_bf16_f32 v51, v51, v52
	v_add_u32_e32 v52, v58, v81
	v_lshl_add_u64 v[52:53], v[52:53], 1, s[8:9]
	v_mov_b32_e32 v188, v50
	v_mov_b32_e32 v189, v51
	s_nop 1
	v_permlane16_swap_b32 v186, v188
	v_permlane16_swap_b32 v187, v189
	s_nop 1
	global_store_dwordx4 v[182:183], v[186:189], off
	v_mov_b32_e32 v50, v174
	v_mov_b32_e32 v51, v175
	v_mov_b32_e32 v52, v176
	v_mov_b32_e32 v53, v177
	v_add_f32_e32 v46, v46, v50
	v_add_f32_e32 v47, v47, v51
	v_mul_f32_e32 v46, 0xbfb8aa3b, v46
; __device__ __forceinline__ float sigmoidf_(float x) { return __builtin_amdgcn_rcpf(1.f + __expf(-x)); }
;     ...
;             } else if constexpr (EPI == EPI_LA) {
;               const float4 a0v = *(const float4*)(e.v0 + col);
;               uint2 o;
;               o.x = pack2(sigmoidf_(a0v.x + a[0]), sigmoidf_(a0v.y + a[1]));
;               o.y = pack2(sigmoidf_(a0v.z + a[2]), sigmoidf_(a0v.w + a[3]));
;               *(uint2*)(e.b0 + (row * (unsigned)D + col)) = o;
	v_mul_f32_e32 v47, 0xbfb8aa3b, v47
	v_exp_f32_e32 v46, v46
	v_exp_f32_e32 v47, v47
	v_add_f32_e32 v46, 1.0, v46
	v_add_f32_e32 v47, 1.0, v47
	v_rcp_f32_e32 v46, v46
	v_rcp_f32_e32 v47, v47
	s_nop 0
	v_cvt_pk_bf16_f32 v46, v46, v47
	v_add_f32_e32 v47, v48, v52
	v_add_f32_e32 v48, v49, v53
	v_mul_f32_e32 v47, 0xbfb8aa3b, v47
	v_mul_f32_e32 v48, 0xbfb8aa3b, v48
	v_exp_f32_e32 v47, v47
	v_exp_f32_e32 v48, v48
	v_mov_b32_e32 v49, v9
	v_add_f32_e32 v47, 1.0, v47
	v_add_f32_e32 v48, 1.0, v48
	v_rcp_f32_e32 v47, v47
	v_rcp_f32_e32 v48, v48
	s_nop 0
	v_cvt_pk_bf16_f32 v47, v47, v48
	v_add_u32_e32 v48, v58, v82
	v_lshl_add_u64 v[48:49], v[48:49], 1, s[8:9]
	v_lshl_add_u64 v[184:185], v[194:195], 0, v[48:49]
	v_mov_b32_e32 v190, v46
	v_mov_b32_e32 v191, v47
	v_mov_b32_e32 v46, v178
	v_mov_b32_e32 v47, v179
	v_mov_b32_e32 v48, v180
	v_mov_b32_e32 v49, v181
	v_add_f32_e32 v42, v42, v46
	v_add_f32_e32 v43, v43, v47
	v_mul_f32_e32 v42, 0xbfb8aa3b, v42
	v_mul_f32_e32 v43, 0xbfb8aa3b, v43
	v_exp_f32_e32 v42, v42
	v_exp_f32_e32 v43, v43
	v_add_f32_e32 v42, 1.0, v42
	v_add_f32_e32 v43, 1.0, v43
	v_rcp_f32_e32 v42, v42
	v_rcp_f32_e32 v43, v43
	s_nop 0
	v_cvt_pk_bf16_f32 v42, v42, v43
	v_add_f32_e32 v43, v44, v48
	v_add_f32_e32 v44, v45, v49
	v_mul_f32_e32 v43, 0xbfb8aa3b, v43
	v_mul_f32_e32 v44, 0xbfb8aa3b, v44
	v_exp_f32_e32 v43, v43
	v_exp_f32_e32 v44, v44
	v_mov_b32_e32 v45, v9
	v_add_f32_e32 v43, 1.0, v43
	v_add_f32_e32 v44, 1.0, v44
	v_rcp_f32_e32 v43, v43
	v_rcp_f32_e32 v44, v44
	s_nop 0
	v_cvt_pk_bf16_f32 v43, v43, v44
	v_add_u32_e32 v44, v58, v62
	v_lshl_add_u64 v[44:45], v[44:45], 1, s[8:9]
	v_mov_b32_e32 v192, v42
	v_mov_b32_e32 v193, v43
	s_nop 1
	v_permlane16_swap_b32 v190, v192
	v_permlane16_swap_b32 v191, v193
	s_nop 1
	global_store_dwordx4 v[184:185], v[190:193], off
	v_or_b32_e32 v42, 0x8000, v80
	v_mov_b32_e32 v44, v166
	v_mov_b32_e32 v45, v167
	v_mov_b32_e32 v46, v168
	v_mov_b32_e32 v47, v169
	v_add_f32_e32 v38, v38, v44
	v_add_f32_e32 v39, v39, v45
	v_mul_f32_e32 v38, 0xbfb8aa3b, v38
	v_mul_f32_e32 v39, 0xbfb8aa3b, v39
	v_exp_f32_e32 v38, v38
	v_exp_f32_e32 v39, v39
	v_add_f32_e32 v38, 1.0, v38
	v_add_f32_e32 v39, 1.0, v39
	v_rcp_f32_e32 v38, v38
	v_rcp_f32_e32 v39, v39
	s_nop 0
	v_cvt_pk_bf16_f32 v38, v38, v39
	v_add_f32_e32 v39, v40, v46
	v_add_f32_e32 v40, v41, v47
	v_mul_f32_e32 v39, 0xbfb8aa3b, v39
	v_mul_f32_e32 v40, 0xbfb8aa3b, v40
	v_exp_f32_e32 v39, v39
	v_exp_f32_e32 v40, v40
	v_mov_b32_e32 v41, v9
	v_add_f32_e32 v39, 1.0, v39
	v_add_f32_e32 v40, 1.0, v40
	v_rcp_f32_e32 v39, v39
	v_rcp_f32_e32 v40, v40
	s_nop 0
	v_cvt_pk_bf16_f32 v39, v39, v40
	v_add_u32_e32 v40, v42, v8
	v_lshl_add_u64 v[40:41], v[40:41], 1, s[8:9]
	v_lshl_add_u64 v[182:183], v[194:195], 0, v[40:41]
	v_mov_b32_e32 v186, v38
	v_mov_b32_e32 v187, v39
	v_mov_b32_e32 v38, v170
	v_mov_b32_e32 v39, v171
	v_mov_b32_e32 v40, v172
	v_mov_b32_e32 v41, v173
	v_add_f32_e32 v34, v34, v38
	v_add_f32_e32 v35, v35, v39
	v_mul_f32_e32 v34, 0xbfb8aa3b, v34
	v_mul_f32_e32 v35, 0xbfb8aa3b, v35
	v_exp_f32_e32 v34, v34
	v_exp_f32_e32 v35, v35
	v_add_f32_e32 v34, 1.0, v34
	v_add_f32_e32 v35, 1.0, v35
	v_rcp_f32_e32 v34, v34
	v_rcp_f32_e32 v35, v35
	s_nop 0
	v_cvt_pk_bf16_f32 v34, v34, v35
	v_add_f32_e32 v35, v36, v40
	v_add_f32_e32 v36, v37, v41
	v_mul_f32_e32 v35, 0xbfb8aa3b, v35
	v_mul_f32_e32 v36, 0xbfb8aa3b, v36
	v_exp_f32_e32 v35, v35
	v_exp_f32_e32 v36, v36
	v_mov_b32_e32 v37, v9
	v_add_f32_e32 v35, 1.0, v35
	v_add_f32_e32 v36, 1.0, v36
	v_rcp_f32_e32 v35, v35
	v_rcp_f32_e32 v36, v36
	s_nop 0
	v_cvt_pk_bf16_f32 v35, v35, v36
	v_add_u32_e32 v36, v42, v81
	v_lshl_add_u64 v[36:37], v[36:37], 1, s[8:9]
	v_mov_b32_e32 v188, v34
	v_mov_b32_e32 v189, v35
	s_nop 1
	v_permlane16_swap_b32 v186, v188
	v_permlane16_swap_b32 v187, v189
	s_nop 1
	global_store_dwordx4 v[182:183], v[186:189], off
	v_mov_b32_e32 v34, v174
	v_mov_b32_e32 v35, v175
	v_mov_b32_e32 v36, v176
	v_mov_b32_e32 v37, v177
	v_add_f32_e32 v30, v30, v34
	v_add_f32_e32 v31, v31, v35
	v_mul_f32_e32 v30, 0xbfb8aa3b, v30
	v_mul_f32_e32 v31, 0xbfb8aa3b, v31
	v_exp_f32_e32 v30, v30
	v_exp_f32_e32 v31, v31
	v_add_f32_e32 v30, 1.0, v30
	v_add_f32_e32 v31, 1.0, v31
	v_rcp_f32_e32 v30, v30
	v_rcp_f32_e32 v31, v31
	s_nop 0
	v_cvt_pk_bf16_f32 v30, v30, v31
	v_add_f32_e32 v31, v32, v36
	v_add_f32_e32 v32, v33, v37
	v_mul_f32_e32 v31, 0xbfb8aa3b, v31
	v_mul_f32_e32 v32, 0xbfb8aa3b, v32
	v_exp_f32_e32 v31, v31
	v_exp_f32_e32 v32, v32
	v_mov_b32_e32 v33, v9
	v_add_f32_e32 v31, 1.0, v31
	v_add_f32_e32 v32, 1.0, v32
	v_rcp_f32_e32 v31, v31
	v_rcp_f32_e32 v32, v32
	s_nop 0
	v_cvt_pk_bf16_f32 v31, v31, v32
	v_add_u32_e32 v32, v42, v82
	v_lshl_add_u64 v[32:33], v[32:33], 1, s[8:9]
	v_lshl_add_u64 v[184:185], v[194:195], 0, v[32:33]
	v_mov_b32_e32 v190, v30
	v_mov_b32_e32 v191, v31
	v_mov_b32_e32 v30, v178
	v_mov_b32_e32 v31, v179
	v_mov_b32_e32 v32, v180
; __device__ __forceinline__ float sigmoidf_(float x) { return __builtin_amdgcn_rcpf(1.f + __expf(-x)); }
;     ...
;   for (int it = 0;; it++) {
;     int tile;
;     if (nb == 512) tile = ((it * 8 + (bid & 7)) << 6) + (bid >> 3); else tile = it * nb + bid;
;     tile += tbeg;
;     if (tile >= MTX * ntn || tile >= tend) break;
;     ...
;             } else if constexpr (EPI == EPI_LA) {
;               const float4 a0v = *(const float4*)(e.v0 + col);
;               uint2 o;
;               o.x = pack2(sigmoidf_(a0v.x + a[0]), sigmoidf_(a0v.y + a[1]));
;               o.y = pack2(sigmoidf_(a0v.z + a[2]), sigmoidf_(a0v.w + a[3]));
;               *(uint2*)(e.b0 + (row * (unsigned)D + col)) = o;
	v_mov_b32_e32 v33, v181
	v_add_f32_e32 v26, v26, v30
	v_add_f32_e32 v27, v27, v31
	v_mul_f32_e32 v26, 0xbfb8aa3b, v26
	v_mul_f32_e32 v27, 0xbfb8aa3b, v27
	v_exp_f32_e32 v26, v26
	v_exp_f32_e32 v27, v27
	v_add_f32_e32 v26, 1.0, v26
	v_add_f32_e32 v27, 1.0, v27
	v_rcp_f32_e32 v26, v26
	v_rcp_f32_e32 v27, v27
	s_nop 0
	v_cvt_pk_bf16_f32 v26, v26, v27
	v_add_f32_e32 v27, v28, v32
	v_add_f32_e32 v28, v29, v33
	v_mul_f32_e32 v27, 0xbfb8aa3b, v27
	v_mul_f32_e32 v28, 0xbfb8aa3b, v28
	v_exp_f32_e32 v27, v27
	v_exp_f32_e32 v28, v28
	v_mov_b32_e32 v29, v9
	v_add_f32_e32 v27, 1.0, v27
	v_add_f32_e32 v28, 1.0, v28
	v_rcp_f32_e32 v27, v27
	v_rcp_f32_e32 v28, v28
	s_nop 0
	v_cvt_pk_bf16_f32 v27, v27, v28
	v_add_u32_e32 v28, v42, v62
	v_lshl_add_u64 v[28:29], v[28:29], 1, s[8:9]
	v_mov_b32_e32 v192, v26
	v_mov_b32_e32 v193, v27
	s_nop 1
	v_permlane16_swap_b32 v190, v192
	v_permlane16_swap_b32 v191, v193
	s_nop 1
	global_store_dwordx4 v[184:185], v[190:193], off
	v_or_b32_e32 v30, 0xc000, v80
	v_add_u32_e32 v8, v30, v8
	v_mov_b32_e32 v26, v166
	v_mov_b32_e32 v27, v167
	v_mov_b32_e32 v28, v168
	v_mov_b32_e32 v29, v169
	v_add_f32_e32 v22, v22, v26
	v_add_f32_e32 v23, v23, v27
	v_add_f32_e32 v24, v24, v28
	v_add_f32_e32 v25, v25, v29
	v_mul_f32_e32 v22, 0xbfb8aa3b, v22
	v_mul_f32_e32 v23, 0xbfb8aa3b, v23
	v_mul_f32_e32 v24, 0xbfb8aa3b, v24
	v_mul_f32_e32 v25, 0xbfb8aa3b, v25
	v_exp_f32_e32 v22, v22
	v_exp_f32_e32 v23, v23
	v_exp_f32_e32 v24, v24
	v_exp_f32_e32 v25, v25
	v_add_f32_e32 v22, 1.0, v22
	v_add_f32_e32 v23, 1.0, v23
	v_add_f32_e32 v24, 1.0, v24
	v_add_f32_e32 v25, 1.0, v25
	v_rcp_f32_e32 v26, v22
	v_rcp_f32_e32 v27, v23
	v_rcp_f32_e32 v28, v24
	v_rcp_f32_e32 v25, v25
	v_lshl_add_u64 v[22:23], v[8:9], 1, s[8:9]
	v_cvt_pk_bf16_f32 v24, v26, v27
	v_cvt_pk_bf16_f32 v25, v28, v25
	v_lshl_add_u64 v[182:183], v[194:195], 0, v[22:23]
	v_mov_b32_e32 v186, v24
	v_mov_b32_e32 v187, v25
	v_mov_b32_e32 v22, v170
	v_mov_b32_e32 v23, v171
	v_mov_b32_e32 v24, v172
	v_mov_b32_e32 v25, v173
	v_add_f32_e32 v8, v18, v22
	v_add_f32_e32 v18, v19, v23
	v_add_f32_e32 v19, v20, v24
	v_add_f32_e32 v20, v21, v25
	v_mul_f32_e32 v8, 0xbfb8aa3b, v8
	v_mul_f32_e32 v18, 0xbfb8aa3b, v18
	v_mul_f32_e32 v19, 0xbfb8aa3b, v19
	v_mul_f32_e32 v20, 0xbfb8aa3b, v20
	v_exp_f32_e32 v8, v8
	v_exp_f32_e32 v18, v18
	v_exp_f32_e32 v19, v19
	v_exp_f32_e32 v20, v20
	v_add_f32_e32 v8, 1.0, v8
	v_add_f32_e32 v18, 1.0, v18
	v_add_f32_e32 v19, 1.0, v19
	v_add_f32_e32 v20, 1.0, v20
	v_rcp_f32_e32 v21, v8
	v_rcp_f32_e32 v22, v18
	v_rcp_f32_e32 v23, v19
	v_rcp_f32_e32 v24, v20
	v_add_u32_e32 v8, v30, v81
	v_lshl_add_u64 v[18:19], v[8:9], 1, s[8:9]
	v_cvt_pk_bf16_f32 v20, v21, v22
	v_cvt_pk_bf16_f32 v21, v23, v24
	v_mov_b32_e32 v188, v20
	v_mov_b32_e32 v189, v21
	s_nop 1
	v_permlane16_swap_b32 v186, v188
	v_permlane16_swap_b32 v187, v189
	s_nop 1
	global_store_dwordx4 v[182:183], v[186:189], off
	v_mov_b32_e32 v18, v174
	v_mov_b32_e32 v19, v175
	v_mov_b32_e32 v20, v176
	v_mov_b32_e32 v21, v177
	v_add_f32_e32 v8, v14, v18
	v_add_f32_e32 v14, v15, v19
	v_add_f32_e32 v15, v16, v20
	v_add_f32_e32 v16, v17, v21
	v_mul_f32_e32 v8, 0xbfb8aa3b, v8
	v_mul_f32_e32 v14, 0xbfb8aa3b, v14
	v_mul_f32_e32 v15, 0xbfb8aa3b, v15
	v_mul_f32_e32 v16, 0xbfb8aa3b, v16
	v_exp_f32_e32 v8, v8
	v_exp_f32_e32 v14, v14
	v_exp_f32_e32 v15, v15
	v_exp_f32_e32 v16, v16
	v_add_f32_e32 v8, 1.0, v8
	v_add_f32_e32 v14, 1.0, v14
	v_add_f32_e32 v15, 1.0, v15
	v_add_f32_e32 v16, 1.0, v16
	v_rcp_f32_e32 v17, v8
	v_rcp_f32_e32 v18, v14
	v_rcp_f32_e32 v19, v15
	v_rcp_f32_e32 v20, v16
	v_add_u32_e32 v8, v30, v82
	v_lshl_add_u64 v[14:15], v[8:9], 1, s[8:9]
	v_cvt_pk_bf16_f32 v16, v17, v18
	v_cvt_pk_bf16_f32 v17, v19, v20
	v_lshl_add_u64 v[184:185], v[194:195], 0, v[14:15]
	v_mov_b32_e32 v190, v16
	v_mov_b32_e32 v191, v17
	v_mov_b32_e32 v14, v178
	v_mov_b32_e32 v15, v179
	v_mov_b32_e32 v16, v180
	v_mov_b32_e32 v17, v181
	v_add_f32_e32 v8, v10, v14
	v_add_f32_e32 v10, v11, v15
	v_add_f32_e32 v11, v12, v16
	v_add_f32_e32 v12, v13, v17
	v_mul_f32_e32 v8, 0xbfb8aa3b, v8
	v_mul_f32_e32 v10, 0xbfb8aa3b, v10
	v_mul_f32_e32 v11, 0xbfb8aa3b, v11
	v_mul_f32_e32 v12, 0xbfb8aa3b, v12
	v_exp_f32_e32 v8, v8
	v_exp_f32_e32 v10, v10
	v_exp_f32_e32 v11, v11
	v_exp_f32_e32 v12, v12
	v_add_f32_e32 v8, 1.0, v8
	v_add_f32_e32 v10, 1.0, v10
	v_add_f32_e32 v11, 1.0, v11
	v_add_f32_e32 v12, 1.0, v12
	v_rcp_f32_e32 v13, v8
	v_rcp_f32_e32 v10, v10
	v_rcp_f32_e32 v11, v11
	v_rcp_f32_e32 v12, v12
	v_add_u32_e32 v8, v30, v62
	v_cvt_pk_bf16_f32 v10, v13, v10
	v_cvt_pk_bf16_f32 v11, v11, v12
	v_lshl_add_u64 v[12:13], v[8:9], 1, s[8:9]
	v_mov_b32_e32 v192, v10
	v_mov_b32_e32 v193, v11
	s_nop 1
	v_permlane16_swap_b32 v190, v192
	v_permlane16_swap_b32 v191, v193
	s_nop 1
	global_store_dwordx4 v[184:185], v[190:193], off
	s_add_i32 s4, s4, 1
	s_addk_i32 s2, 0x200
	s_mov_b64 s[0:1], 0
